# v054 + unit-boundary de-serialisation: the trailing half (waves 4-7) takes its one-barrier offset at the K-loop entry, after its unit preamble (S.next + zeroing), instead of before it; phase-prologue
# speedup vs baseline: 1.0061x; 1.0061x over previous
.LBB0_309:
	v_ashrrev_i32_e32 v3, 31, v143
	v_lshrrev_b32_e32 v3, 26, v3
	v_add_u32_e32 v3, v143, v3
	s_waitcnt vmcnt(0)
	v_ashrrev_i32_e32 v10, 6, v3
	v_bfe_i32 v3, v143, 27, 1
	v_lshlrev_b32_e32 v2, 4, v143
	v_lshrrev_b32_e32 v3, 22, v3
	v_add_u32_e32 v3, v2, v3
	v_and_b32_e32 v3, 0xfffffc00, v3
	v_sub_u32_e32 v3, v2, v3
	s_add_u32 s64, s56, 0x69000000
	v_lshrrev_b32_e32 v4, 4, v3
	s_addc_u32 s65, s57, 0
	v_readlane_b32 s4, v255, 22
	v_bitop3_b32 v3, v4, v3, 32 bitop3:0x6c
	s_add_u32 s4, s56, s4
	v_ashrrev_i32_e32 v5, 31, v3
	s_addc_u32 s5, s57, s77
	v_lshrrev_b32_e32 v5, 26, v5
	s_add_u32 s66, s4, 0x800000
	v_add_u32_e32 v5, v3, v5
	s_addc_u32 s67, s5, 0
	s_lshl_b64 s[4:5], s[20:21], 19
	v_lshlrev_b32_e32 v4, 3, v10
	v_ashrrev_i32_e32 v11, 6, v5
	v_and_b32_e32 v5, 0xc0, v5
	s_add_u32 s24, s64, s4
	v_and_b32_e32 v4, -16, v4
	v_sub_u32_e32 v3, v3, v5
	s_addc_u32 s25, s65, s5
	s_lshl_b64 s[4:5], s[22:23], 20
	v_add_u32_e32 v4, v11, v4
	v_ashrrev_i16_sdwa v3, v219, sext(v3) dst_sel:DWORD dst_unused:UNUSED_PAD src0_sel:DWORD src1_sel:BYTE_0
	s_add_u32 s26, s66, s4
	v_lshlrev_b32_e32 v6, 5, v10
	v_bfe_i32 v12, v3, 0, 16
	v_lshlrev_b32_e32 v3, 1, v4
	v_lshrrev_b32_e32 v5, 2, v4
	v_and_b32_e32 v7, 3, v11
	s_mov_b32 s4, 0xfffe0
	v_and_b32_e32 v6, 32, v6
	v_and_b32_e32 v3, 24, v3
	v_and_b32_e32 v5, 4, v5
	v_and_or_b32 v7, v4, s4, v7
	v_or3_b32 v3, v7, v5, v3
	v_add_lshl_u32 v5, v6, v12, 1
	v_add_u32_e32 v2, 0x2000, v2
	v_lshl_add_u32 v162, v3, 12, v5
	v_ashrrev_i32_e32 v3, 31, v2
	v_lshrrev_b32_e32 v3, 22, v3
	v_add_u32_e32 v3, v2, v3
	v_ashrrev_i32_e32 v13, 10, v3
	v_mul_i32_i24_e32 v3, 0x400, v13
	v_sub_u32_e32 v2, v2, v3
	v_lshrrev_b32_e32 v3, 4, v2
	v_bitop3_b32 v2, v3, v2, 32 bitop3:0x6c
	v_lshl_add_u32 v130, v4, 11, v5
	v_ashrrev_i32_e32 v4, 31, v2
	v_lshrrev_b32_e32 v4, 26, v4
	v_add_u32_e32 v4, v2, v4
	v_lshlrev_b32_e32 v3, 3, v13
	v_ashrrev_i32_e32 v14, 6, v4
	v_and_b32_e32 v4, 0xc0, v4
	v_and_b32_e32 v3, -16, v3
	v_sub_u32_e32 v2, v2, v4
	s_addc_u32 s27, s67, s5
	v_add_u32_e32 v3, v14, v3
	v_ashrrev_i16_sdwa v2, v219, sext(v2) dst_sel:DWORD dst_unused:UNUSED_PAD src0_sel:DWORD src1_sel:BYTE_0
	s_lshl_b32 s23, s13, 10
	v_lshlrev_b32_e32 v5, 5, v13
	v_bfe_i32 v15, v2, 0, 16
	v_lshlrev_b32_e32 v2, 1, v3
	v_lshrrev_b32_e32 v4, 2, v3
	v_and_b32_e32 v6, 3, v14
	s_add_i32 s68, s23, 0
	v_and_b32_e32 v5, 32, v5
	v_and_b32_e32 v2, 24, v2
	v_and_b32_e32 v4, 4, v4
	v_and_or_b32 v6, v3, s4, v6
	s_add_i32 m0, s68, 0x10000
	v_or3_b32 v2, v6, v4, v2
	v_add_lshl_u32 v4, v5, v15, 1
	s_ashr_i32 s4, s12, 8
	global_load_lds_dwordx4 v162, s[26:27]
	s_add_i32 m0, s68, 0x12000
	v_lshl_add_u32 v134, v2, 12, v4
	s_add_u32 s8, s26, 0x80000
	global_load_lds_dwordx4 v134, s[26:27]
	s_addc_u32 s9, s27, 0
	s_add_i32 m0, s68, 0x14000
	s_add_i32 s69, s68, 0x2000
	global_load_lds_dwordx4 v162, s[8:9]
	s_add_i32 m0, s68, 0x16000
	v_lshl_add_u32 v132, v3, 11, v4
	global_load_lds_dwordx4 v134, s[8:9]
	s_mov_b32 m0, s68
	s_add_u32 s8, s24, 0x40000
	global_load_lds_dwordx4 v130, s[24:25]
	s_mov_b32 m0, s69
	s_addc_u32 s9, s25, 0
	s_add_i32 s70, s68, 0x4000
	global_load_lds_dwordx4 v132, s[24:25]
	s_mov_b32 m0, s70
	s_add_i32 s71, s68, 0x6000
	global_load_lds_dwordx4 v130, s[8:9]
	s_mov_b32 m0, s71
	v_mov_b32_e32 v135, v163
	global_load_lds_dwordx4 v132, s[8:9]
	v_mov_b32_e32 v131, v163
	v_mov_b32_e32 v133, v163
	s_cmp_eq_u32 s4, 1
	v_lshl_add_u64 v[8:9], s[26:27], 0, v[162:163]
	v_lshl_add_u64 v[6:7], s[26:27], 0, v[134:135]
	v_lshl_add_u64 v[2:3], s[24:25], 0, v[130:131]
	s_cselect_b64 s[8:9], -1, 0
	s_cmp_lg_u32 s4, 1
	v_lshl_add_u64 v[4:5], s[24:25], 0, v[132:133]
	s_movk_i32 s31, 0x161
	s_cbranch_scc1 .LBB0_311
.LBB0_311:
	s_and_b32 s14, s13, 3
	s_add_i32 m0, s68, 0x18000
	v_lshl_add_u64 v[8:9], v[8:9], 0, s[44:45]
	s_lshl_b32 s15, s4, 6
	s_lshl_b32 s10, s4, 13
	s_lshl_b32 s11, s14, 12
	s_waitcnt vmcnt(2)
	s_barrier
	global_load_lds_dwordx4 v[8:9], off
	v_lshl_add_u64 v[6:7], v[6:7], 0, s[44:45]
	s_add_i32 m0, s68, 0x1a000
	s_add_i32 s72, s68, 0x8000
	s_add_i32 s73, s68, 0xa000
	global_load_lds_dwordx4 v[6:7], off
	v_lshl_add_u64 v[2:3], v[2:3], 0, s[44:45]
	s_mov_b32 m0, s72
	s_add_u32 s4, s26, 0x80080
	global_load_lds_dwordx4 v[2:3], off
	v_lshl_add_u64 v[2:3], v[4:5], 0, s[44:45]
	s_mov_b32 m0, s73
	s_addc_u32 s5, s27, 0
	global_load_lds_dwordx4 v[2:3], off
	s_add_i32 m0, s68, 0x1c000
	v_lshl_add_u64 v[2:3], s[4:5], 0, v[162:163]
	global_load_lds_dwordx4 v[2:3], off
	v_lshl_add_u64 v[2:3], s[4:5], 0, v[134:135]
	s_add_i32 m0, s68, 0x1e000
	v_lshrrev_b32_e32 v4, 1, v143
	global_load_lds_dwordx4 v[2:3], off
	s_and_b32 s4, s2, 7
	v_and_b32_e32 v159, 24, v4
	s_lshl_b32 s5, s4, 3
	s_ashr_i32 s75, s2, 6
	s_bfe_u32 s77, s2, 0x30003
	s_mul_i32 s4, s4, 44
	v_and_b32_e32 v3, 15, v143
	v_lshlrev_b32_e32 v4, 1, v159
	v_lshlrev_b32_e32 v5, 2, v143
	s_ashr_i32 s74, s2, 31
	s_add_i32 s76, s5, s75
	s_or_b32 s78, s5, s77
	s_lshr_b32 s79, s4, 3
	v_or_b32_e32 v2, s15, v3
	v_lshl_or_b32 v3, v3, 6, v4
	v_and_b32_e32 v5, 32, v5
	s_cmpk_lt_u32 s12, 0x100
	v_bitop3_b32 v6, v3, s10, v5 bitop3:0xde
	v_bitop3_b32 v161, v3, s11, v5 bitop3:0xde
	s_cselect_b64 s[10:11], -1, 0
	s_ashr_i32 s4, s15, 31
	v_mov_b32_e32 v3, s4
	s_lshl_b32 s4, s13, 6
	s_bfe_u32 s80, s13, 0x10001
	s_lshl_b32 s81, s14, 7
	s_and_b32 s4, s4, 64
	s_add_u32 s4, s56, s4
	s_addc_u32 s5, s57, 0
	v_mov_b32_e32 v5, v163
	v_lshlrev_b32_e32 v173, 3, v2
	v_lshl_add_u64 v[4:5], s[4:5], 0, v[4:5]
	v_lshlrev_b64 v[2:3], 7, v[2:3]
	v_lshl_add_u64 v[2:3], v[4:5], 0, v[2:3]
	s_mov_b64 s[4:5], 0x58000000
	v_lshl_add_u64 v[136:137], v[2:3], 0, s[4:5]
	v_lshlrev_b32_e32 v2, 14, v13
	v_and_b32_e32 v2, 0xffff8000, v2
	v_lshl_add_u32 v2, v14, 11, v2
	v_and_b32_e32 v3, 1, v13
	v_lshl_or_b32 v2, v3, 6, v2
	v_lshl_add_u32 v138, v15, 1, v2
	v_lshlrev_b32_e32 v2, 14, v10
	v_and_b32_e32 v2, 0xffff8000, v2
	s_waitcnt vmcnt(6)
	v_lshl_add_u32 v2, v11, 11, v2
	v_and_b32_e32 v3, 1, v10
	v_lshl_or_b32 v2, v3, 6, v2
	v_mov_b32_e32 v139, v163
	v_lshl_add_u32 v140, v12, 1, v2
	v_mov_b32_e32 v141, v163
	s_mov_b32 s83, 0
	v_add_u32_e32 v177, 0, v6
	s_mov_b32 s82, 0
	s_barrier
	s_branch .LBB0_314

.LBB0_322:
	s_add_u32 s13, s26, 0x100
	s_addc_u32 s15, s27, 0
	s_add_u32 s24, s24, 0x40080
	v_mov_b32_e32 v2, 0
	s_addc_u32 s25, s25, 0
	s_mov_b32 s21, -2
	v_mov_b32_e32 v3, v2
	v_mov_b32_e32 v4, v2
	v_mov_b32_e32 v5, v2
	v_mov_b32_e32 v10, v2
	v_mov_b32_e32 v11, v2
	v_mov_b32_e32 v12, v2
	v_mov_b32_e32 v13, v2
	v_mov_b32_e32 v18, v2
	v_mov_b32_e32 v19, v2
	v_mov_b32_e32 v20, v2
	v_mov_b32_e32 v21, v2
	v_mov_b32_e32 v26, v2
	v_mov_b32_e32 v27, v2
	v_mov_b32_e32 v28, v2
	v_mov_b32_e32 v29, v2
	v_mov_b32_e32 v34, v2
	v_mov_b32_e32 v35, v2
	v_mov_b32_e32 v36, v2
	v_mov_b32_e32 v37, v2
	v_mov_b32_e32 v42, v2
	v_mov_b32_e32 v43, v2
	v_mov_b32_e32 v44, v2
	v_mov_b32_e32 v45, v2
	v_mov_b32_e32 v50, v2
	v_mov_b32_e32 v51, v2
	v_mov_b32_e32 v52, v2
	v_mov_b32_e32 v53, v2
	v_mov_b32_e32 v58, v2
	v_mov_b32_e32 v59, v2
	v_mov_b32_e32 v60, v2
	v_mov_b32_e32 v61, v2
	v_mov_b32_e32 v6, v2
	v_mov_b32_e32 v7, v2
	v_mov_b32_e32 v8, v2
	v_mov_b32_e32 v9, v2
	v_mov_b32_e32 v14, v2
	v_mov_b32_e32 v15, v2
	v_mov_b32_e32 v16, v2
	v_mov_b32_e32 v17, v2
	v_mov_b32_e32 v22, v2
	v_mov_b32_e32 v23, v2
	v_mov_b32_e32 v24, v2
	v_mov_b32_e32 v25, v2
	v_mov_b32_e32 v30, v2
	v_mov_b32_e32 v31, v2
	v_mov_b32_e32 v32, v2
	v_mov_b32_e32 v33, v2
	v_mov_b32_e32 v38, v2
	v_mov_b32_e32 v39, v2
	v_mov_b32_e32 v40, v2
	v_mov_b32_e32 v41, v2
	v_mov_b32_e32 v46, v2
	v_mov_b32_e32 v47, v2
	v_mov_b32_e32 v48, v2
	v_mov_b32_e32 v49, v2
	v_mov_b32_e32 v54, v2
	v_mov_b32_e32 v55, v2
	v_mov_b32_e32 v56, v2
	v_mov_b32_e32 v57, v2
	v_mov_b32_e32 v62, v2
	v_mov_b32_e32 v63, v2
	v_mov_b32_e32 v64, v2
	v_mov_b32_e32 v65, v2
	v_mov_b32_e32 v66, v2
	v_mov_b32_e32 v67, v2
	v_mov_b32_e32 v68, v2
	v_mov_b32_e32 v69, v2
	v_mov_b32_e32 v74, v2
	v_mov_b32_e32 v75, v2
	v_mov_b32_e32 v76, v2
	v_mov_b32_e32 v77, v2
	v_mov_b32_e32 v82, v2
	v_mov_b32_e32 v83, v2
	v_mov_b32_e32 v84, v2
	v_mov_b32_e32 v85, v2
	v_mov_b32_e32 v90, v2
	v_mov_b32_e32 v91, v2
	v_mov_b32_e32 v92, v2
	v_mov_b32_e32 v93, v2
	v_mov_b32_e32 v98, v2
	v_mov_b32_e32 v99, v2
	v_mov_b32_e32 v100, v2
	v_mov_b32_e32 v101, v2
	v_mov_b32_e32 v106, v2
	v_mov_b32_e32 v107, v2
	v_mov_b32_e32 v108, v2
	v_mov_b32_e32 v109, v2
	v_mov_b32_e32 v114, v2
	v_mov_b32_e32 v115, v2
	v_mov_b32_e32 v116, v2
	v_mov_b32_e32 v117, v2
	v_mov_b32_e32 v122, v2
	v_mov_b32_e32 v123, v2
	v_mov_b32_e32 v124, v2
	v_mov_b32_e32 v125, v2
	v_mov_b32_e32 v70, v2
	v_mov_b32_e32 v71, v2
	v_mov_b32_e32 v72, v2
	v_mov_b32_e32 v73, v2
	v_mov_b32_e32 v78, v2
	v_mov_b32_e32 v79, v2
	v_mov_b32_e32 v80, v2
	v_mov_b32_e32 v81, v2
	v_mov_b32_e32 v86, v2
	v_mov_b32_e32 v87, v2
	v_mov_b32_e32 v88, v2
	v_mov_b32_e32 v89, v2
	v_mov_b32_e32 v94, v2
	v_mov_b32_e32 v95, v2
	v_mov_b32_e32 v96, v2
	v_mov_b32_e32 v97, v2
	v_mov_b32_e32 v102, v2
	v_mov_b32_e32 v103, v2
	v_mov_b32_e32 v104, v2
	v_mov_b32_e32 v105, v2
	v_mov_b32_e32 v110, v2
	v_mov_b32_e32 v111, v2
	v_mov_b32_e32 v112, v2
	v_mov_b32_e32 v113, v2
	v_mov_b32_e32 v118, v2
	v_mov_b32_e32 v119, v2
	v_mov_b32_e32 v120, v2
	v_mov_b32_e32 v121, v2
	v_mov_b32_e32 v126, v2
	v_mov_b32_e32 v127, v2
	v_mov_b32_e32 v128, v2
	v_mov_b32_e32 v129, v2
	v_readfirstlane_b32 s100, v0
	s_nop 3
	s_bitcmp1_b32 s100, 8
	s_cbranch_scc0 .Lrb_skip0
	s_barrier
.Lrb_skip0:
.LBB0_323:
	s_add_u32 s26, s24, 0xfffc0080
	s_addc_u32 s27, s25, -1
	s_add_i32 s36, 0, 0x10000
	s_cmp_eq_u32 s21, 12
	s_cselect_b32 s57, s17, s27
	s_cselect_b32 s56, s16, s26
	v_add_u32_e32 v142, s36, v161
	s_cselect_b32 s27, s19, s15
	s_cselect_b32 s26, s18, s13
	s_add_i32 s38, 0, 0x14000
	ds_read_b128 v[144:147], v142
	ds_read_b128 v[148:151], v142 offset:1024
	ds_read_b128 v[152:155], v142 offset:2048
	ds_read_b128 v[178:181], v142 offset:3072
	v_add_u32_e32 v142, s38, v161
	ds_read_b128 v[182:185], v142
	ds_read_b128 v[186:189], v142 offset:1024
	ds_read_b128 v[190:193], v142 offset:2048
	ds_read_b128 v[194:197], v142 offset:3072
	v_lshl_add_u64 v[156:157], s[24:25], 0, v[140:141]
	s_add_i32 m0, s68, 0xc000
	ds_read_b128 v[198:201], v177
	ds_read_b128 v[202:205], v177 offset:1024
	ds_read_b128 v[206:209], v177 offset:2048
	ds_read_b128 v[210:213], v177 offset:3072
	ds_read_b128 v[214:217], v177 offset:4096
	ds_read_b128 v[222:225], v177 offset:5120
	ds_read_b128 v[226:229], v177 offset:6144
	ds_read_b128 v[230:233], v177 offset:7168
	global_load_lds_dwordx4 v[156:157], off
	v_lshl_add_u64 v[156:157], s[24:25], 0, v[138:139]
	s_add_i32 m0, s68, 0xe000
	s_nop 0
	global_load_lds_dwordx4 v[156:157], off
	s_waitcnt vmcnt(8)
	s_waitcnt lgkmcnt(0)
	s_barrier
	v_mfma_i32_16x16x64_i8 v[126:129], v[144:147], v[198:201], v[126:129]
	v_mfma_i32_16x16x64_i8 v[118:121], v[152:155], v[198:201], v[118:121]
	v_mfma_i32_16x16x64_i8 v[110:113], v[144:147], v[206:209], v[110:113]
	v_mfma_i32_16x16x64_i8 v[102:105], v[152:155], v[206:209], v[102:105]
	v_mfma_i32_16x16x64_i8 v[94:97], v[144:147], v[214:217], v[94:97]
	v_mfma_i32_16x16x64_i8 v[86:89], v[152:155], v[214:217], v[86:89]
	v_mfma_i32_16x16x64_i8 v[78:81], v[144:147], v[226:229], v[78:81]
	v_mfma_i32_16x16x64_i8 v[70:73], v[152:155], v[226:229], v[70:73]
	v_mfma_i32_16x16x64_i8 v[126:129], v[148:151], v[202:205], v[126:129]
	v_mfma_i32_16x16x64_i8 v[118:121], v[178:181], v[202:205], v[118:121]
	v_mfma_i32_16x16x64_i8 v[110:113], v[148:151], v[210:213], v[110:113]
	v_mfma_i32_16x16x64_i8 v[102:105], v[178:181], v[210:213], v[102:105]
	v_mfma_i32_16x16x64_i8 v[94:97], v[148:151], v[222:225], v[94:97]
	v_mfma_i32_16x16x64_i8 v[86:89], v[178:181], v[222:225], v[86:89]
	v_mfma_i32_16x16x64_i8 v[78:81], v[148:151], v[230:233], v[78:81]
	v_mfma_i32_16x16x64_i8 v[70:73], v[178:181], v[230:233], v[70:73]
	v_mfma_i32_16x16x64_i8 v[122:125], v[182:185], v[198:201], v[122:125]
	v_mfma_i32_16x16x64_i8 v[114:117], v[190:193], v[198:201], v[114:117]
	v_mfma_i32_16x16x64_i8 v[106:109], v[182:185], v[206:209], v[106:109]
	v_mfma_i32_16x16x64_i8 v[98:101], v[190:193], v[206:209], v[98:101]
	v_mfma_i32_16x16x64_i8 v[90:93], v[182:185], v[214:217], v[90:93]
	v_mfma_i32_16x16x64_i8 v[82:85], v[190:193], v[214:217], v[82:85]
	v_mfma_i32_16x16x64_i8 v[74:77], v[182:185], v[226:229], v[74:77]
	v_mfma_i32_16x16x64_i8 v[66:69], v[190:193], v[226:229], v[66:69]
	v_mfma_i32_16x16x64_i8 v[122:125], v[186:189], v[202:205], v[122:125]
	v_mfma_i32_16x16x64_i8 v[114:117], v[194:197], v[202:205], v[114:117]
	v_mfma_i32_16x16x64_i8 v[106:109], v[186:189], v[210:213], v[106:109]
	v_mfma_i32_16x16x64_i8 v[98:101], v[194:197], v[210:213], v[98:101]
	v_mfma_i32_16x16x64_i8 v[90:93], v[186:189], v[222:225], v[90:93]
	v_mfma_i32_16x16x64_i8 v[82:85], v[194:197], v[222:225], v[82:85]
	v_mfma_i32_16x16x64_i8 v[74:77], v[186:189], v[230:233], v[74:77]
	v_mfma_i32_16x16x64_i8 v[66:69], v[194:197], v[230:233], v[66:69]
	s_barrier
	s_add_i32 s36, s36, s23
	v_lshl_add_u64 v[156:157], s[26:27], 0, v[162:163]
	s_mov_b32 m0, s36
	ds_read_b128 v[198:201], v177 offset:16384
	ds_read_b128 v[202:205], v177 offset:17408
	ds_read_b128 v[206:209], v177 offset:18432
	ds_read_b128 v[210:213], v177 offset:19456
	ds_read_b128 v[214:217], v177 offset:20480
	ds_read_b128 v[222:225], v177 offset:21504
	ds_read_b128 v[226:229], v177 offset:22528
	ds_read_b128 v[230:233], v177 offset:23552
	global_load_lds_dwordx4 v[156:157], off
	s_add_i32 m0, s36, 0x2000
	s_add_u32 s36, s26, 0x80000
	v_lshl_add_u64 v[174:175], s[26:27], 0, v[134:135]
	s_addc_u32 s37, s27, 0
	s_add_i32 s38, s38, s23
	global_load_lds_dwordx4 v[174:175], off
	v_lshl_add_u64 v[234:235], s[36:37], 0, v[162:163]
	s_mov_b32 m0, s38
	v_lshl_add_u64 v[236:237], s[56:57], 0, v[132:133]
	global_load_lds_dwordx4 v[234:235], off
	v_lshl_add_u64 v[234:235], s[36:37], 0, v[134:135]
	s_add_i32 m0, s38, 0x2000
	s_nop 0
	global_load_lds_dwordx4 v[234:235], off
	v_lshl_add_u64 v[234:235], s[56:57], 0, v[130:131]
	s_mov_b32 m0, s68
	s_nop 0
	global_load_lds_dwordx4 v[234:235], off
	s_mov_b32 m0, s69
	s_nop 0
	global_load_lds_dwordx4 v[236:237], off
	s_waitcnt vmcnt(8)
	s_waitcnt lgkmcnt(0)
	s_barrier
	v_mfma_i32_16x16x64_i8 v[62:65], v[144:147], v[198:201], v[62:65]
	v_mfma_i32_16x16x64_i8 v[54:57], v[152:155], v[198:201], v[54:57]
	v_mfma_i32_16x16x64_i8 v[46:49], v[144:147], v[206:209], v[46:49]
	v_mfma_i32_16x16x64_i8 v[38:41], v[152:155], v[206:209], v[38:41]
	v_mfma_i32_16x16x64_i8 v[30:33], v[144:147], v[214:217], v[30:33]
	v_mfma_i32_16x16x64_i8 v[22:25], v[152:155], v[214:217], v[22:25]
	v_mfma_i32_16x16x64_i8 v[14:17], v[144:147], v[226:229], v[14:17]
	v_mfma_i32_16x16x64_i8 v[6:9], v[152:155], v[226:229], v[6:9]
	v_mfma_i32_16x16x64_i8 v[62:65], v[148:151], v[202:205], v[62:65]
	v_mfma_i32_16x16x64_i8 v[54:57], v[178:181], v[202:205], v[54:57]
	v_mfma_i32_16x16x64_i8 v[46:49], v[148:151], v[210:213], v[46:49]
	v_mfma_i32_16x16x64_i8 v[38:41], v[178:181], v[210:213], v[38:41]
	v_mfma_i32_16x16x64_i8 v[30:33], v[148:151], v[222:225], v[30:33]
	v_mfma_i32_16x16x64_i8 v[22:25], v[178:181], v[222:225], v[22:25]
	v_mfma_i32_16x16x64_i8 v[14:17], v[148:151], v[230:233], v[14:17]
	v_mfma_i32_16x16x64_i8 v[6:9], v[178:181], v[230:233], v[6:9]
	v_mfma_i32_16x16x64_i8 v[58:61], v[182:185], v[198:201], v[58:61]
	v_mfma_i32_16x16x64_i8 v[50:53], v[190:193], v[198:201], v[50:53]
	v_mfma_i32_16x16x64_i8 v[42:45], v[182:185], v[206:209], v[42:45]
	v_mfma_i32_16x16x64_i8 v[34:37], v[190:193], v[206:209], v[34:37]
	v_mfma_i32_16x16x64_i8 v[26:29], v[182:185], v[214:217], v[26:29]
	v_mfma_i32_16x16x64_i8 v[18:21], v[190:193], v[214:217], v[18:21]
	v_mfma_i32_16x16x64_i8 v[10:13], v[182:185], v[226:229], v[10:13]
	v_mfma_i32_16x16x64_i8 v[2:5], v[190:193], v[226:229], v[2:5]
	v_mfma_i32_16x16x64_i8 v[58:61], v[186:189], v[202:205], v[58:61]
	v_mfma_i32_16x16x64_i8 v[50:53], v[194:197], v[202:205], v[50:53]
	v_mfma_i32_16x16x64_i8 v[42:45], v[186:189], v[210:213], v[42:45]
	v_mfma_i32_16x16x64_i8 v[34:37], v[194:197], v[210:213], v[34:37]
	v_mfma_i32_16x16x64_i8 v[26:29], v[186:189], v[222:225], v[26:29]
	v_mfma_i32_16x16x64_i8 v[18:21], v[194:197], v[222:225], v[18:21]
	v_mfma_i32_16x16x64_i8 v[10:13], v[186:189], v[230:233], v[10:13]
	v_mfma_i32_16x16x64_i8 v[2:5], v[194:197], v[230:233], v[2:5]
	s_barrier
	s_add_i32 s38, 0, 0x18000
	v_add_u32_e32 v142, s38, v161
	s_add_i32 s39, 0, 0x1c000
	ds_read_b128 v[144:147], v142
	ds_read_b128 v[148:151], v142 offset:1024
	ds_read_b128 v[152:155], v142 offset:2048
	ds_read_b128 v[178:181], v142 offset:3072
	v_add_u32_e32 v142, s39, v161
	ds_read_b128 v[182:185], v142
	ds_read_b128 v[186:189], v142 offset:1024
	ds_read_b128 v[190:193], v142 offset:2048
	ds_read_b128 v[194:197], v142 offset:3072
	s_add_u32 s36, s56, 0x40000
	s_addc_u32 s37, s57, 0
	s_mov_b32 m0, s70
	v_lshl_add_u64 v[238:239], s[36:37], 0, v[130:131]
	ds_read_b128 v[198:201], v177 offset:32768
	ds_read_b128 v[202:205], v177 offset:33792
	ds_read_b128 v[206:209], v177 offset:34816
	ds_read_b128 v[210:213], v177 offset:35840
	ds_read_b128 v[214:217], v177 offset:36864
	ds_read_b128 v[222:225], v177 offset:37888
	ds_read_b128 v[226:229], v177 offset:38912
	ds_read_b128 v[230:233], v177 offset:39936
	global_load_lds_dwordx4 v[238:239], off
	v_lshl_add_u64 v[238:239], s[36:37], 0, v[132:133]
	s_mov_b32 m0, s71
	s_nop 0
	global_load_lds_dwordx4 v[238:239], off
	s_waitcnt vmcnt(8)
	s_waitcnt lgkmcnt(0)
	s_barrier
	v_mfma_i32_16x16x64_i8 v[126:129], v[144:147], v[198:201], v[126:129]
	v_mfma_i32_16x16x64_i8 v[118:121], v[152:155], v[198:201], v[118:121]
	v_mfma_i32_16x16x64_i8 v[110:113], v[144:147], v[206:209], v[110:113]
	v_mfma_i32_16x16x64_i8 v[102:105], v[152:155], v[206:209], v[102:105]
	v_mfma_i32_16x16x64_i8 v[94:97], v[144:147], v[214:217], v[94:97]
	v_mfma_i32_16x16x64_i8 v[86:89], v[152:155], v[214:217], v[86:89]
	v_mfma_i32_16x16x64_i8 v[78:81], v[144:147], v[226:229], v[78:81]
	v_mfma_i32_16x16x64_i8 v[70:73], v[152:155], v[226:229], v[70:73]
	v_mfma_i32_16x16x64_i8 v[126:129], v[148:151], v[202:205], v[126:129]
	v_mfma_i32_16x16x64_i8 v[118:121], v[178:181], v[202:205], v[118:121]
	v_mfma_i32_16x16x64_i8 v[110:113], v[148:151], v[210:213], v[110:113]
	v_mfma_i32_16x16x64_i8 v[102:105], v[178:181], v[210:213], v[102:105]
	v_mfma_i32_16x16x64_i8 v[94:97], v[148:151], v[222:225], v[94:97]
	v_mfma_i32_16x16x64_i8 v[86:89], v[178:181], v[222:225], v[86:89]
	v_mfma_i32_16x16x64_i8 v[78:81], v[148:151], v[230:233], v[78:81]
	v_mfma_i32_16x16x64_i8 v[70:73], v[178:181], v[230:233], v[70:73]
	v_mfma_i32_16x16x64_i8 v[122:125], v[182:185], v[198:201], v[122:125]
	v_mfma_i32_16x16x64_i8 v[114:117], v[190:193], v[198:201], v[114:117]
	v_mfma_i32_16x16x64_i8 v[106:109], v[182:185], v[206:209], v[106:109]
	v_mfma_i32_16x16x64_i8 v[98:101], v[190:193], v[206:209], v[98:101]
	v_mfma_i32_16x16x64_i8 v[90:93], v[182:185], v[214:217], v[90:93]
	v_mfma_i32_16x16x64_i8 v[82:85], v[190:193], v[214:217], v[82:85]
	v_mfma_i32_16x16x64_i8 v[74:77], v[182:185], v[226:229], v[74:77]
	v_mfma_i32_16x16x64_i8 v[66:69], v[190:193], v[226:229], v[66:69]
	v_mfma_i32_16x16x64_i8 v[122:125], v[186:189], v[202:205], v[122:125]
	v_mfma_i32_16x16x64_i8 v[114:117], v[194:197], v[202:205], v[114:117]
	v_mfma_i32_16x16x64_i8 v[106:109], v[186:189], v[210:213], v[106:109]
	v_mfma_i32_16x16x64_i8 v[98:101], v[194:197], v[210:213], v[98:101]
	v_mfma_i32_16x16x64_i8 v[90:93], v[186:189], v[222:225], v[90:93]
	v_mfma_i32_16x16x64_i8 v[82:85], v[194:197], v[222:225], v[82:85]
	v_mfma_i32_16x16x64_i8 v[74:77], v[186:189], v[230:233], v[74:77]
	v_mfma_i32_16x16x64_i8 v[66:69], v[194:197], v[230:233], v[66:69]
	s_barrier
	s_add_i32 s36, s38, s23
	v_lshl_add_u64 v[156:157], v[156:157], 0, s[44:45]
	s_mov_b32 m0, s36
	ds_read_b128 v[198:201], v177 offset:49152
	ds_read_b128 v[202:205], v177 offset:50176
	ds_read_b128 v[206:209], v177 offset:51200
	ds_read_b128 v[210:213], v177 offset:52224
	ds_read_b128 v[214:217], v177 offset:53248
	ds_read_b128 v[222:225], v177 offset:54272
	ds_read_b128 v[226:229], v177 offset:55296
	ds_read_b128 v[230:233], v177 offset:56320
	global_load_lds_dwordx4 v[156:157], off
	s_add_i32 m0, s36, 0x2000
	s_add_u32 s26, s26, 0x80080
	v_lshl_add_u64 v[156:157], v[174:175], 0, s[44:45]
	s_addc_u32 s27, s27, 0
	s_add_i32 s36, s39, s23
	global_load_lds_dwordx4 v[156:157], off
	v_lshl_add_u64 v[156:157], s[26:27], 0, v[162:163]
	s_mov_b32 m0, s36
	s_nop 0
	global_load_lds_dwordx4 v[156:157], off
	v_lshl_add_u64 v[156:157], s[26:27], 0, v[134:135]
	s_add_i32 m0, s36, 0x2000
	s_nop 0
	global_load_lds_dwordx4 v[156:157], off
	v_lshl_add_u64 v[156:157], v[234:235], 0, s[44:45]
	s_mov_b32 m0, s72
	s_nop 0
	global_load_lds_dwordx4 v[156:157], off
	v_lshl_add_u64 v[156:157], v[236:237], 0, s[44:45]
	s_mov_b32 m0, s73
	s_nop 0
	global_load_lds_dwordx4 v[156:157], off
	s_waitcnt vmcnt(8)
	s_waitcnt lgkmcnt(0)
	s_barrier
	v_mfma_i32_16x16x64_i8 v[62:65], v[144:147], v[198:201], v[62:65]
	v_mfma_i32_16x16x64_i8 v[54:57], v[152:155], v[198:201], v[54:57]
	v_mfma_i32_16x16x64_i8 v[46:49], v[144:147], v[206:209], v[46:49]
	v_mfma_i32_16x16x64_i8 v[38:41], v[152:155], v[206:209], v[38:41]
	v_mfma_i32_16x16x64_i8 v[30:33], v[144:147], v[214:217], v[30:33]
	v_mfma_i32_16x16x64_i8 v[22:25], v[152:155], v[214:217], v[22:25]
	v_mfma_i32_16x16x64_i8 v[14:17], v[144:147], v[226:229], v[14:17]
	v_mfma_i32_16x16x64_i8 v[6:9], v[152:155], v[226:229], v[6:9]
	v_mfma_i32_16x16x64_i8 v[62:65], v[148:151], v[202:205], v[62:65]
	v_mfma_i32_16x16x64_i8 v[54:57], v[178:181], v[202:205], v[54:57]
	v_mfma_i32_16x16x64_i8 v[46:49], v[148:151], v[210:213], v[46:49]
	v_mfma_i32_16x16x64_i8 v[38:41], v[178:181], v[210:213], v[38:41]
	v_mfma_i32_16x16x64_i8 v[30:33], v[148:151], v[222:225], v[30:33]
	v_mfma_i32_16x16x64_i8 v[22:25], v[178:181], v[222:225], v[22:25]
	v_mfma_i32_16x16x64_i8 v[14:17], v[148:151], v[230:233], v[14:17]
	v_mfma_i32_16x16x64_i8 v[6:9], v[178:181], v[230:233], v[6:9]
	v_mfma_i32_16x16x64_i8 v[58:61], v[182:185], v[198:201], v[58:61]
	v_mfma_i32_16x16x64_i8 v[50:53], v[190:193], v[198:201], v[50:53]
	v_mfma_i32_16x16x64_i8 v[42:45], v[182:185], v[206:209], v[42:45]
	v_mfma_i32_16x16x64_i8 v[34:37], v[190:193], v[206:209], v[34:37]
	v_mfma_i32_16x16x64_i8 v[26:29], v[182:185], v[214:217], v[26:29]
	v_mfma_i32_16x16x64_i8 v[18:21], v[190:193], v[214:217], v[18:21]
	v_mfma_i32_16x16x64_i8 v[10:13], v[182:185], v[226:229], v[10:13]
	v_mfma_i32_16x16x64_i8 v[2:5], v[190:193], v[226:229], v[2:5]
	v_mfma_i32_16x16x64_i8 v[58:61], v[186:189], v[202:205], v[58:61]
	v_mfma_i32_16x16x64_i8 v[50:53], v[194:197], v[202:205], v[50:53]
	v_mfma_i32_16x16x64_i8 v[42:45], v[186:189], v[210:213], v[42:45]
	v_mfma_i32_16x16x64_i8 v[34:37], v[194:197], v[210:213], v[34:37]
	v_mfma_i32_16x16x64_i8 v[26:29], v[186:189], v[222:225], v[26:29]
	v_mfma_i32_16x16x64_i8 v[18:21], v[194:197], v[222:225], v[18:21]
	v_mfma_i32_16x16x64_i8 v[10:13], v[186:189], v[230:233], v[10:13]
	v_mfma_i32_16x16x64_i8 v[2:5], v[194:197], v[230:233], v[2:5]
	s_barrier
	s_add_i32 s21, s21, 2
	s_add_u32 s13, s13, 0x100
	s_addc_u32 s15, s15, 0
	s_add_u32 s24, s24, 0x100
	s_addc_u32 s25, s25, 0
	s_cmp_gt_u32 s21, 13
	s_cbranch_scc0 .LBB0_323
	s_and_b64 vcc, exec, s[10:11]
	s_cbranch_vccz .LBB0_326
	s_barrier

.LBB0_329:
	s_andn2_b64 vcc, exec, s[8:9]
	s_cbranch_vccnz .LBB0_312
	s_branch .LBB0_312

.LBB0_418:
	s_and_b64 vcc, exec, s[4:5]
	v_readlane_b32 s4, v255, 23
	s_or_b32 s54, s4, 0x4000
	v_readlane_b32 s5, v255, 24
	s_cbranch_vccnz .LBB0_460
	v_ashrrev_i32_e32 v3, 31, v6
	v_lshrrev_b32_e32 v3, 26, v3
	v_add_u32_e32 v3, v6, v3
	v_ashrrev_i32_e32 v7, 6, v3
	v_bfe_i32 v3, v6, 27, 1
	v_lshlrev_b32_e32 v2, 4, v6
	v_lshrrev_b32_e32 v3, 22, v3
	v_add_u32_e32 v3, v2, v3
	v_and_b32_e32 v3, 0xfffffc00, v3
	v_sub_u32_e32 v3, v2, v3
	v_lshrrev_b32_e32 v4, 4, v3
	v_bitop3_b32 v3, v4, v3, 32 bitop3:0x6c
	v_ashrrev_i32_e32 v5, 31, v3
	v_lshrrev_b32_e32 v5, 26, v5
	v_add_u32_e32 v5, v3, v5
	v_ashrrev_i32_e32 v8, 6, v5
	v_and_b32_e32 v5, 0xc0, v5
	v_lshlrev_b32_e32 v4, 3, v7
	v_sub_u32_e32 v3, v3, v5
	v_and_b32_e32 v4, -16, v4
	v_lshlrev_b32_e32 v9, 5, v7
	v_ashrrev_i16_sdwa v3, v219, sext(v3) dst_sel:DWORD dst_unused:UNUSED_PAD src0_sel:DWORD src1_sel:BYTE_0
	v_add_u32_e32 v4, v8, v4
	v_and_b32_e32 v10, 32, v9
	v_bfe_i32 v9, v3, 0, 16
	v_add_u32_e32 v3, v10, v9
	v_lshlrev_b32_e32 v5, 1, v4
	v_lshrrev_b32_e32 v10, 2, v4
	v_and_b32_e32 v11, 3, v8
	s_mov_b32 s5, 0x7fffe0
	v_and_b32_e32 v5, 24, v5
	v_and_b32_e32 v10, 4, v10
	v_and_or_b32 v11, v4, s5, v11
	v_or3_b32 v5, v11, v10, v5
	v_lshlrev_b32_e32 v4, 7, v4
	v_lshl_add_u32 v158, v3, 1, v4
	v_mul_u32_u24_e32 v4, 0x1600, v5
	v_add_u32_e32 v2, 0x2000, v2
	v_add_lshl_u32 v162, v4, v3, 1
	v_ashrrev_i32_e32 v3, 31, v2
	v_lshrrev_b32_e32 v3, 22, v3
	v_add_u32_e32 v3, v2, v3
	v_ashrrev_i32_e32 v10, 10, v3
	v_mul_i32_i24_e32 v3, 0x400, v10
	v_sub_u32_e32 v2, v2, v3
	v_lshrrev_b32_e32 v3, 4, v2
	v_bitop3_b32 v2, v3, v2, 32 bitop3:0x6c
	v_ashrrev_i32_e32 v4, 31, v2
	v_lshrrev_b32_e32 v4, 26, v4
	v_add_u32_e32 v4, v2, v4
	v_lshlrev_b32_e32 v3, 3, v10
	v_ashrrev_i32_e32 v11, 6, v4
	v_and_b32_e32 v4, 0xc0, v4
	v_and_b32_e32 v3, -16, v3
	v_sub_u32_e32 v2, v2, v4
	v_add_u32_e32 v3, v11, v3
	v_lshlrev_b32_e32 v5, 5, v10
	v_ashrrev_i16_sdwa v2, v219, sext(v2) dst_sel:DWORD dst_unused:UNUSED_PAD src0_sel:DWORD src1_sel:BYTE_0
	v_and_b32_e32 v13, 3, v11
	v_and_b32_e32 v5, 32, v5
	v_bfe_i32 v12, v2, 0, 16
	v_and_or_b32 v13, v3, s5, v13
	s_ashr_i32 s5, s18, 6
	v_add_u32_e32 v2, v5, v12
	v_lshlrev_b32_e32 v4, 1, v3
	v_lshrrev_b32_e32 v5, 2, v3
	s_lshl_b32 s62, s5, 10
	v_and_b32_e32 v4, 24, v4
	v_and_b32_e32 v5, 4, v5
	s_add_i32 s63, s62, 0
	v_or3_b32 v4, v13, v5, v4
	v_lshlrev_b32_e32 v3, 7, v3
	s_add_i32 m0, s63, 0x10000
	s_ashr_i32 s4, s18, 8
	v_lshl_add_u32 v160, v2, 1, v3
	v_mul_u32_u24_e32 v3, 0x1600, v4
	global_load_lds_dwordx4 v162, s[26:27]
	s_add_i32 m0, s63, 0x12000
	v_add_lshl_u32 v172, v3, v2, 1
	s_add_u32 s8, s26, 0x160000
	global_load_lds_dwordx4 v172, s[26:27]
	s_addc_u32 s9, s27, 0
	s_add_i32 m0, s63, 0x14000
	s_add_i32 s64, s63, 0x2000
	global_load_lds_dwordx4 v162, s[8:9]
	s_add_i32 m0, s63, 0x16000
	v_mov_b32_e32 v173, v163
	global_load_lds_dwordx4 v172, s[8:9]
	s_mov_b32 m0, s63
	s_add_u32 s8, s24, 0x4000
	global_load_lds_dwordx4 v158, s[24:25]
	s_mov_b32 m0, s64
	s_addc_u32 s9, s25, 0
	s_add_i32 s65, s63, 0x4000
	global_load_lds_dwordx4 v160, s[24:25]
	s_mov_b32 m0, s65
	s_add_i32 s66, s63, 0x6000
	global_load_lds_dwordx4 v158, s[8:9]
	s_mov_b32 m0, s66
	s_cmp_eq_u32 s4, 1
	global_load_lds_dwordx4 v160, s[8:9]
	v_lshl_add_u64 v[2:3], s[26:27], 0, v[162:163]
	s_cselect_b64 s[8:9], -1, 0
	s_cmp_lg_u32 s4, 1
	v_lshl_add_u64 v[4:5], s[26:27], 0, v[172:173]
	s_cbranch_scc1 .LBB0_421
.LBB0_421:
	s_add_u32 s10, s6, 0x63000000
	s_addc_u32 s11, s7, 0
	s_add_u32 s12, s6, 0x44000000
	s_addc_u32 s13, s7, 0
	s_lshl_b64 s[14:15], s[54:55], 3
	s_add_u32 s14, s6, s14
	s_addc_u32 s15, s7, s15
	s_add_u32 s14, s14, 0x100000
	s_addc_u32 s15, s15, 0
	v_bfe_u32 v14, v6, 4, 2
	s_add_u32 s16, s6, 2.0
	v_and_b32_e32 v13, 15, v6
	v_lshlrev_b32_e32 v15, 4, v14
	v_lshlrev_b32_e32 v6, 2, v6
	s_addc_u32 s17, s7, 0
	v_lshl_or_b32 v196, s4, 6, v13
	v_lshl_or_b32 v13, v13, 6, v15
	s_lshl_b32 s4, s4, 13
	v_and_b32_e32 v6, 32, v6
	v_bitop3_b32 v15, v13, s4, v6 bitop3:0xde
	s_lshl_b32 s4, s5, 5
	s_and_b32 s6, s4, 0x60
	s_add_i32 m0, s63, 0x18000
	v_lshl_add_u64 v[2:3], v[2:3], 0, s[44:45]
	s_lshl_b32 s4, s6, 7
	s_waitcnt vmcnt(2)
	s_barrier
	global_load_lds_dwordx4 v[2:3], off
	s_add_i32 m0, s63, 0x1a000
	v_bitop3_b32 v197, v13, s4, v6 bitop3:0xde
	s_add_u32 s4, s24, 0x8000
	v_mov_b32_e32 v159, v163
	v_lshl_add_u64 v[2:3], v[4:5], 0, s[44:45]
	s_addc_u32 s5, s25, 0
	s_add_i32 s67, s63, 0x8000
	v_mov_b32_e32 v161, v163
	global_load_lds_dwordx4 v[2:3], off
	v_lshl_add_u64 v[2:3], s[4:5], 0, v[158:159]
	s_mov_b32 m0, s67
	s_add_i32 s68, s63, 0xa000
	global_load_lds_dwordx4 v[2:3], off
	v_lshl_add_u64 v[2:3], s[4:5], 0, v[160:161]
	s_add_u32 s4, s26, 0x160080
	s_mov_b32 m0, s68
	s_addc_u32 s5, s27, 0
	global_load_lds_dwordx4 v[2:3], off
	s_add_i32 m0, s63, 0x1c000
	v_lshl_add_u64 v[2:3], s[4:5], 0, v[162:163]
	global_load_lds_dwordx4 v[2:3], off
	v_lshl_add_u64 v[2:3], s[4:5], 0, v[172:173]
	s_add_i32 m0, s63, 0x1e000
	s_and_b32 s70, s2, 7
	global_load_lds_dwordx4 v[2:3], off
	v_lshlrev_b32_e32 v2, 10, v10
	v_and_b32_e32 v2, 0xfffff800, v2
	v_lshl_add_u32 v2, v11, 7, v2
	v_and_b32_e32 v3, 1, v10
	v_lshl_or_b32 v2, v3, 6, v2
	v_lshl_add_u32 v174, v12, 1, v2
	v_lshlrev_b32_e32 v2, 10, v7
	s_lshl_b32 s4, s70, 3
	s_ashr_i32 s71, s2, 6
	s_bfe_u32 s73, s2, 0x30003
	v_and_b32_e32 v2, 0xfffff800, v2
	s_waitcnt vmcnt(6)
	s_ashr_i32 s69, s2, 31
	s_add_i32 s72, s4, s71
	s_or_b32 s74, s4, s73
	v_lshl_add_u32 v2, v8, 7, v2
	v_and_b32_e32 v3, 1, v7
	s_cmpk_lt_u32 s18, 0x100
	v_lshl_or_b32 v2, v3, 6, v2
	s_cselect_b64 s[18:19], -1, 0
	s_mov_b32 s75, 0
	v_cmp_eq_u32_e64 s[4:5], 0, v14
	v_lshl_or_b32 v198, v14, 3, s6
	v_mov_b32_e32 v175, v163
	v_lshl_add_u32 v176, v9, 1, v2
	v_mov_b32_e32 v177, v163
	v_add_u32_e32 v199, 0, v15
	s_barrier
	s_branch .LBB0_424

.LBB0_436:
	s_add_u32 s24, s24, 0xc000
	s_addc_u32 s25, s25, 0
	s_add_u32 s80, s26, 0x100
	v_mov_b32_e32 v2, 0
	s_addc_u32 s81, s27, 0
	s_mov_b32 s82, -2
	s_waitcnt lgkmcnt(0)
	v_mov_b32_e32 v3, v2
	v_mov_b32_e32 v4, v2
	v_mov_b32_e32 v5, v2
	v_mov_b32_e32 v6, v2
	v_mov_b32_e32 v7, v2
	v_mov_b32_e32 v8, v2
	v_mov_b32_e32 v9, v2
	v_mov_b32_e32 v18, v2
	v_mov_b32_e32 v19, v2
	v_mov_b32_e32 v20, v2
	v_mov_b32_e32 v21, v2
	v_mov_b32_e32 v22, v2
	v_mov_b32_e32 v23, v2
	v_mov_b32_e32 v24, v2
	v_mov_b32_e32 v25, v2
	v_mov_b32_e32 v34, v2
	v_mov_b32_e32 v35, v2
	v_mov_b32_e32 v36, v2
	v_mov_b32_e32 v37, v2
	v_mov_b32_e32 v38, v2
	v_mov_b32_e32 v39, v2
	v_mov_b32_e32 v40, v2
	v_mov_b32_e32 v41, v2
	v_mov_b32_e32 v50, v2
	v_mov_b32_e32 v51, v2
	v_mov_b32_e32 v52, v2
	v_mov_b32_e32 v53, v2
	v_mov_b32_e32 v54, v2
	v_mov_b32_e32 v55, v2
	v_mov_b32_e32 v56, v2
	v_mov_b32_e32 v57, v2
	v_mov_b32_e32 v10, v2
	v_mov_b32_e32 v11, v2
	v_mov_b32_e32 v12, v2
	v_mov_b32_e32 v13, v2
	v_mov_b32_e32 v14, v2
	v_mov_b32_e32 v15, v2
	v_mov_b32_e32 v16, v2
	v_mov_b32_e32 v17, v2
	v_mov_b32_e32 v26, v2
	v_mov_b32_e32 v27, v2
	v_mov_b32_e32 v28, v2
	v_mov_b32_e32 v29, v2
	v_mov_b32_e32 v30, v2
	v_mov_b32_e32 v31, v2
	v_mov_b32_e32 v32, v2
	v_mov_b32_e32 v33, v2
	v_mov_b32_e32 v42, v2
	v_mov_b32_e32 v43, v2
	v_mov_b32_e32 v44, v2
	v_mov_b32_e32 v45, v2
	v_mov_b32_e32 v46, v2
	v_mov_b32_e32 v47, v2
	v_mov_b32_e32 v48, v2
	v_mov_b32_e32 v49, v2
	v_mov_b32_e32 v58, v2
	v_mov_b32_e32 v59, v2
	v_mov_b32_e32 v60, v2
	v_mov_b32_e32 v61, v2
	v_mov_b32_e32 v62, v2
	v_mov_b32_e32 v63, v2
	v_mov_b32_e32 v64, v2
	v_mov_b32_e32 v65, v2
	v_mov_b32_e32 v66, v2
	v_mov_b32_e32 v67, v2
	v_mov_b32_e32 v68, v2
	v_mov_b32_e32 v69, v2
	v_mov_b32_e32 v70, v2
	v_mov_b32_e32 v71, v2
	v_mov_b32_e32 v72, v2
	v_mov_b32_e32 v73, v2
	v_mov_b32_e32 v82, v2
	v_mov_b32_e32 v83, v2
	v_mov_b32_e32 v84, v2
	v_mov_b32_e32 v85, v2
	v_mov_b32_e32 v86, v2
	v_mov_b32_e32 v87, v2
	v_mov_b32_e32 v88, v2
	v_mov_b32_e32 v89, v2
	v_mov_b32_e32 v98, v2
	v_mov_b32_e32 v99, v2
	v_mov_b32_e32 v100, v2
	v_mov_b32_e32 v101, v2
	v_mov_b32_e32 v102, v2
	v_mov_b32_e32 v103, v2
	v_mov_b32_e32 v104, v2
	v_mov_b32_e32 v105, v2
	v_mov_b32_e32 v130, v2
	v_mov_b32_e32 v131, v2
	v_mov_b32_e32 v132, v2
	v_mov_b32_e32 v133, v2
	v_mov_b32_e32 v134, v2
	v_mov_b32_e32 v135, v2
	v_mov_b32_e32 v136, v2
	v_mov_b32_e32 v137, v2
	v_mov_b32_e32 v74, v2
	v_mov_b32_e32 v75, v2
	v_mov_b32_e32 v76, v2
	v_mov_b32_e32 v77, v2
	v_mov_b32_e32 v78, v2
	v_mov_b32_e32 v79, v2
	v_mov_b32_e32 v80, v2
	v_mov_b32_e32 v81, v2
	v_mov_b32_e32 v90, v2
	v_mov_b32_e32 v91, v2
	v_mov_b32_e32 v92, v2
	v_mov_b32_e32 v93, v2
	v_mov_b32_e32 v94, v2
	v_mov_b32_e32 v95, v2
	v_mov_b32_e32 v96, v2
	v_mov_b32_e32 v97, v2
	v_mov_b32_e32 v106, v2
	v_mov_b32_e32 v107, v2
	v_mov_b32_e32 v108, v2
	v_mov_b32_e32 v109, v2
	v_mov_b32_e32 v110, v2
	v_mov_b32_e32 v111, v2
	v_mov_b32_e32 v112, v2
	v_mov_b32_e32 v113, v2
	v_mov_b32_e32 v146, v2
	v_mov_b32_e32 v147, v2
	v_mov_b32_e32 v148, v2
	v_mov_b32_e32 v149, v2
	v_mov_b32_e32 v150, v2
	v_mov_b32_e32 v151, v2
	v_mov_b32_e32 v152, v2
	v_mov_b32_e32 v153, v2
	v_readfirstlane_b32 s100, v0
	s_nop 3
	s_bitcmp1_b32 s100, 8
	s_cbranch_scc0 .Lrb_skip1
	s_barrier
.Lrb_skip1:
.LBB0_437:
	s_add_u32 s26, s24, 0x4000
	s_addc_u32 s27, s25, 0
	s_cmpk_eq_i32 s82, 0x54
	s_cselect_b32 s58, s20, s26
	s_cselect_b32 s59, s21, s27
	s_cselect_b32 s56, s22, s80
	s_cselect_b32 s57, s23, s81
	s_add_u32 s26, s58, 0x8000
	s_addc_u32 s27, s59, 0
	s_add_i32 s36, 0, 0x10000
	s_add_i32 s38, 0, 0x14000
	v_add_u32_e32 v126, s36, v197
	v_add_u32_e32 v168, s38, v197
	ds_read_b128 v[114:117], v126
	ds_read_b128 v[118:121], v126 offset:1024
	ds_read_b128 v[122:125], v126 offset:2048
	ds_read_b128 v[126:129], v126 offset:3072
	ds_read_b128 v[138:141], v168
	ds_read_b128 v[142:145], v168 offset:1024
	ds_read_b128 v[154:157], v168 offset:2048
	ds_read_b128 v[178:181], v168 offset:3072
	v_lshl_add_u64 v[194:195], s[24:25], 0, v[176:177]
	s_add_i32 m0, s63, 0xc000
	ds_read_b128 v[182:185], v199
	ds_read_b128 v[186:189], v199 offset:1024
	ds_read_b128 v[190:193], v199 offset:2048
	ds_read_b128 v[200:203], v199 offset:3072
	ds_read_b128 v[204:207], v199 offset:4096
	ds_read_b128 v[208:211], v199 offset:5120
	ds_read_b128 v[212:215], v199 offset:6144
	ds_read_b128 v[222:225], v199 offset:7168
	global_load_lds_dwordx4 v[194:195], off
	v_lshl_add_u64 v[194:195], s[24:25], 0, v[174:175]
	s_add_i32 m0, s63, 0xe000
	s_nop 0
	global_load_lds_dwordx4 v[194:195], off
	s_waitcnt vmcnt(8)
	s_waitcnt lgkmcnt(0)
	s_barrier
	v_mfma_f32_16x16x32_bf16 v[150:153], v[114:117], v[182:185], v[150:153]
	v_mfma_f32_16x16x32_bf16 v[146:149], v[122:125], v[182:185], v[146:149]
	v_mfma_f32_16x16x32_bf16 v[110:113], v[114:117], v[190:193], v[110:113]
	v_mfma_f32_16x16x32_bf16 v[106:109], v[122:125], v[190:193], v[106:109]
	v_mfma_f32_16x16x32_bf16 v[94:97], v[114:117], v[204:207], v[94:97]
	v_mfma_f32_16x16x32_bf16 v[90:93], v[122:125], v[204:207], v[90:93]
	v_mfma_f32_16x16x32_bf16 v[78:81], v[114:117], v[212:215], v[78:81]
	v_mfma_f32_16x16x32_bf16 v[74:77], v[122:125], v[212:215], v[74:77]
	v_mfma_f32_16x16x32_bf16 v[150:153], v[118:121], v[186:189], v[150:153]
	v_mfma_f32_16x16x32_bf16 v[146:149], v[126:129], v[186:189], v[146:149]
	v_mfma_f32_16x16x32_bf16 v[110:113], v[118:121], v[200:203], v[110:113]
	v_mfma_f32_16x16x32_bf16 v[106:109], v[126:129], v[200:203], v[106:109]
	v_mfma_f32_16x16x32_bf16 v[94:97], v[118:121], v[208:211], v[94:97]
	v_mfma_f32_16x16x32_bf16 v[90:93], v[126:129], v[208:211], v[90:93]
	v_mfma_f32_16x16x32_bf16 v[78:81], v[118:121], v[222:225], v[78:81]
	v_mfma_f32_16x16x32_bf16 v[74:77], v[126:129], v[222:225], v[74:77]
	v_mfma_f32_16x16x32_bf16 v[134:137], v[138:141], v[182:185], v[134:137]
	v_mfma_f32_16x16x32_bf16 v[130:133], v[154:157], v[182:185], v[130:133]
	v_mfma_f32_16x16x32_bf16 v[102:105], v[138:141], v[190:193], v[102:105]
	v_mfma_f32_16x16x32_bf16 v[98:101], v[154:157], v[190:193], v[98:101]
	v_mfma_f32_16x16x32_bf16 v[86:89], v[138:141], v[204:207], v[86:89]
	v_mfma_f32_16x16x32_bf16 v[82:85], v[154:157], v[204:207], v[82:85]
	v_mfma_f32_16x16x32_bf16 v[70:73], v[138:141], v[212:215], v[70:73]
	v_mfma_f32_16x16x32_bf16 v[66:69], v[154:157], v[212:215], v[66:69]
	v_mfma_f32_16x16x32_bf16 v[134:137], v[142:145], v[186:189], v[134:137]
	v_mfma_f32_16x16x32_bf16 v[130:133], v[178:181], v[186:189], v[130:133]
	v_mfma_f32_16x16x32_bf16 v[102:105], v[142:145], v[200:203], v[102:105]
	v_mfma_f32_16x16x32_bf16 v[98:101], v[178:181], v[200:203], v[98:101]
	v_mfma_f32_16x16x32_bf16 v[86:89], v[142:145], v[208:211], v[86:89]
	v_mfma_f32_16x16x32_bf16 v[82:85], v[178:181], v[208:211], v[82:85]
	v_mfma_f32_16x16x32_bf16 v[70:73], v[142:145], v[222:225], v[70:73]
	v_mfma_f32_16x16x32_bf16 v[66:69], v[178:181], v[222:225], v[66:69]
	s_barrier
	s_add_i32 s36, s36, s62
	v_lshl_add_u64 v[194:195], s[56:57], 0, v[162:163]
	s_mov_b32 m0, s36
	ds_read_b128 v[182:185], v199 offset:16384
	ds_read_b128 v[186:189], v199 offset:17408
	ds_read_b128 v[190:193], v199 offset:18432
	ds_read_b128 v[200:203], v199 offset:19456
	ds_read_b128 v[204:207], v199 offset:20480
	ds_read_b128 v[208:211], v199 offset:21504
	ds_read_b128 v[212:215], v199 offset:22528
	ds_read_b128 v[222:225], v199 offset:23552
	global_load_lds_dwordx4 v[194:195], off
	s_add_i32 m0, s36, 0x2000
	s_add_u32 s36, s56, 0x160000
	v_lshl_add_u64 v[216:217], s[56:57], 0, v[172:173]
	s_addc_u32 s37, s57, 0
	s_add_i32 s38, s38, s62
	global_load_lds_dwordx4 v[216:217], off
	v_lshl_add_u64 v[226:227], s[36:37], 0, v[162:163]
	s_mov_b32 m0, s38
	s_nop 0
	global_load_lds_dwordx4 v[226:227], off
	v_lshl_add_u64 v[226:227], s[36:37], 0, v[172:173]
	s_add_i32 m0, s38, 0x2000
	s_nop 0
	global_load_lds_dwordx4 v[226:227], off
	v_lshl_add_u64 v[226:227], s[58:59], 0, v[158:159]
	s_mov_b32 m0, s63
	s_nop 0
	global_load_lds_dwordx4 v[226:227], off
	v_lshl_add_u64 v[226:227], s[58:59], 0, v[160:161]
	s_mov_b32 m0, s64
	s_nop 0
	global_load_lds_dwordx4 v[226:227], off
	s_waitcnt vmcnt(8)
	s_waitcnt lgkmcnt(0)
	s_barrier
	v_mfma_f32_16x16x32_bf16 v[62:65], v[114:117], v[182:185], v[62:65]
	v_mfma_f32_16x16x32_bf16 v[58:61], v[122:125], v[182:185], v[58:61]
	v_mfma_f32_16x16x32_bf16 v[46:49], v[114:117], v[190:193], v[46:49]
	v_mfma_f32_16x16x32_bf16 v[42:45], v[122:125], v[190:193], v[42:45]
	v_mfma_f32_16x16x32_bf16 v[30:33], v[114:117], v[204:207], v[30:33]
	v_mfma_f32_16x16x32_bf16 v[26:29], v[122:125], v[204:207], v[26:29]
	v_mfma_f32_16x16x32_bf16 v[14:17], v[114:117], v[212:215], v[14:17]
	v_mfma_f32_16x16x32_bf16 v[10:13], v[122:125], v[212:215], v[10:13]
	v_mfma_f32_16x16x32_bf16 v[62:65], v[118:121], v[186:189], v[62:65]
	v_mfma_f32_16x16x32_bf16 v[58:61], v[126:129], v[186:189], v[58:61]
	v_mfma_f32_16x16x32_bf16 v[46:49], v[118:121], v[200:203], v[46:49]
	v_mfma_f32_16x16x32_bf16 v[42:45], v[126:129], v[200:203], v[42:45]
	v_mfma_f32_16x16x32_bf16 v[30:33], v[118:121], v[208:211], v[30:33]
	v_mfma_f32_16x16x32_bf16 v[26:29], v[126:129], v[208:211], v[26:29]
	v_mfma_f32_16x16x32_bf16 v[14:17], v[118:121], v[222:225], v[14:17]
	v_mfma_f32_16x16x32_bf16 v[10:13], v[126:129], v[222:225], v[10:13]
	v_mfma_f32_16x16x32_bf16 v[54:57], v[138:141], v[182:185], v[54:57]
	v_mfma_f32_16x16x32_bf16 v[50:53], v[154:157], v[182:185], v[50:53]
	v_mfma_f32_16x16x32_bf16 v[38:41], v[138:141], v[190:193], v[38:41]
	v_mfma_f32_16x16x32_bf16 v[34:37], v[154:157], v[190:193], v[34:37]
	v_mfma_f32_16x16x32_bf16 v[22:25], v[138:141], v[204:207], v[22:25]
	v_mfma_f32_16x16x32_bf16 v[18:21], v[154:157], v[204:207], v[18:21]
	v_mfma_f32_16x16x32_bf16 v[6:9], v[138:141], v[212:215], v[6:9]
	v_mfma_f32_16x16x32_bf16 v[2:5], v[154:157], v[212:215], v[2:5]
	v_mfma_f32_16x16x32_bf16 v[54:57], v[142:145], v[186:189], v[54:57]
	v_mfma_f32_16x16x32_bf16 v[50:53], v[178:181], v[186:189], v[50:53]
	v_mfma_f32_16x16x32_bf16 v[38:41], v[142:145], v[200:203], v[38:41]
	v_mfma_f32_16x16x32_bf16 v[34:37], v[178:181], v[200:203], v[34:37]
	v_mfma_f32_16x16x32_bf16 v[22:25], v[142:145], v[208:211], v[22:25]
	v_mfma_f32_16x16x32_bf16 v[18:21], v[178:181], v[208:211], v[18:21]
	v_mfma_f32_16x16x32_bf16 v[6:9], v[142:145], v[222:225], v[6:9]
	v_mfma_f32_16x16x32_bf16 v[2:5], v[178:181], v[222:225], v[2:5]
	s_barrier
	s_add_i32 s38, 0, 0x18000
	s_add_i32 s39, 0, 0x1c000
	v_add_u32_e32 v126, s38, v197
	v_add_u32_e32 v168, s39, v197
	ds_read_b128 v[114:117], v126
	ds_read_b128 v[118:121], v126 offset:1024
	ds_read_b128 v[122:125], v126 offset:2048
	ds_read_b128 v[126:129], v126 offset:3072
	ds_read_b128 v[138:141], v168
	ds_read_b128 v[142:145], v168 offset:1024
	ds_read_b128 v[154:157], v168 offset:2048
	ds_read_b128 v[178:181], v168 offset:3072
	s_add_u32 s36, s58, 0x4000
	s_addc_u32 s37, s59, 0
	s_mov_b32 m0, s65
	v_lshl_add_u64 v[226:227], s[36:37], 0, v[158:159]
	ds_read_b128 v[182:185], v199 offset:32768
	ds_read_b128 v[186:189], v199 offset:33792
	ds_read_b128 v[190:193], v199 offset:34816
	ds_read_b128 v[200:203], v199 offset:35840
	ds_read_b128 v[204:207], v199 offset:36864
	ds_read_b128 v[208:211], v199 offset:37888
	ds_read_b128 v[212:215], v199 offset:38912
	ds_read_b128 v[222:225], v199 offset:39936
	global_load_lds_dwordx4 v[226:227], off
	v_lshl_add_u64 v[226:227], s[36:37], 0, v[160:161]
	s_mov_b32 m0, s66
	s_nop 0
	global_load_lds_dwordx4 v[226:227], off
	s_waitcnt vmcnt(8)
	s_waitcnt lgkmcnt(0)
	s_barrier
	v_mfma_f32_16x16x32_bf16 v[150:153], v[114:117], v[182:185], v[150:153]
	v_mfma_f32_16x16x32_bf16 v[146:149], v[122:125], v[182:185], v[146:149]
	v_mfma_f32_16x16x32_bf16 v[110:113], v[114:117], v[190:193], v[110:113]
	v_mfma_f32_16x16x32_bf16 v[106:109], v[122:125], v[190:193], v[106:109]
	v_mfma_f32_16x16x32_bf16 v[94:97], v[114:117], v[204:207], v[94:97]
	v_mfma_f32_16x16x32_bf16 v[90:93], v[122:125], v[204:207], v[90:93]
	v_mfma_f32_16x16x32_bf16 v[78:81], v[114:117], v[212:215], v[78:81]
	v_mfma_f32_16x16x32_bf16 v[74:77], v[122:125], v[212:215], v[74:77]
	v_mfma_f32_16x16x32_bf16 v[150:153], v[118:121], v[186:189], v[150:153]
	v_mfma_f32_16x16x32_bf16 v[146:149], v[126:129], v[186:189], v[146:149]
	v_mfma_f32_16x16x32_bf16 v[110:113], v[118:121], v[200:203], v[110:113]
	v_mfma_f32_16x16x32_bf16 v[106:109], v[126:129], v[200:203], v[106:109]
	v_mfma_f32_16x16x32_bf16 v[94:97], v[118:121], v[208:211], v[94:97]
	v_mfma_f32_16x16x32_bf16 v[90:93], v[126:129], v[208:211], v[90:93]
	v_mfma_f32_16x16x32_bf16 v[78:81], v[118:121], v[222:225], v[78:81]
	v_mfma_f32_16x16x32_bf16 v[74:77], v[126:129], v[222:225], v[74:77]
	v_mfma_f32_16x16x32_bf16 v[134:137], v[138:141], v[182:185], v[134:137]
	v_mfma_f32_16x16x32_bf16 v[130:133], v[154:157], v[182:185], v[130:133]
	v_mfma_f32_16x16x32_bf16 v[102:105], v[138:141], v[190:193], v[102:105]
	v_mfma_f32_16x16x32_bf16 v[98:101], v[154:157], v[190:193], v[98:101]
	v_mfma_f32_16x16x32_bf16 v[86:89], v[138:141], v[204:207], v[86:89]
	v_mfma_f32_16x16x32_bf16 v[82:85], v[154:157], v[204:207], v[82:85]
	v_mfma_f32_16x16x32_bf16 v[70:73], v[138:141], v[212:215], v[70:73]
	v_mfma_f32_16x16x32_bf16 v[66:69], v[154:157], v[212:215], v[66:69]
	v_mfma_f32_16x16x32_bf16 v[134:137], v[142:145], v[186:189], v[134:137]
	v_mfma_f32_16x16x32_bf16 v[130:133], v[178:181], v[186:189], v[130:133]
	v_mfma_f32_16x16x32_bf16 v[102:105], v[142:145], v[200:203], v[102:105]
	v_mfma_f32_16x16x32_bf16 v[98:101], v[178:181], v[200:203], v[98:101]
	v_mfma_f32_16x16x32_bf16 v[86:89], v[142:145], v[208:211], v[86:89]
	v_mfma_f32_16x16x32_bf16 v[82:85], v[178:181], v[208:211], v[82:85]
	v_mfma_f32_16x16x32_bf16 v[70:73], v[142:145], v[222:225], v[70:73]
	v_mfma_f32_16x16x32_bf16 v[66:69], v[178:181], v[222:225], v[66:69]
	s_barrier
	s_add_i32 s36, s38, s62
	v_lshl_add_u64 v[194:195], v[194:195], 0, s[44:45]
	s_mov_b32 m0, s36
	ds_read_b128 v[182:185], v199 offset:49152
	ds_read_b128 v[186:189], v199 offset:50176
	ds_read_b128 v[190:193], v199 offset:51200
	ds_read_b128 v[200:203], v199 offset:52224
	ds_read_b128 v[204:207], v199 offset:53248
	ds_read_b128 v[208:211], v199 offset:54272
	ds_read_b128 v[212:215], v199 offset:55296
	ds_read_b128 v[222:225], v199 offset:56320
	global_load_lds_dwordx4 v[194:195], off
	s_add_i32 m0, s36, 0x2000
	s_add_u32 s36, s56, 0x160080
	v_lshl_add_u64 v[194:195], v[216:217], 0, s[44:45]
	s_addc_u32 s37, s57, 0
	s_add_i32 s38, s39, s62
	global_load_lds_dwordx4 v[194:195], off
	v_lshl_add_u64 v[194:195], s[36:37], 0, v[162:163]
	s_mov_b32 m0, s38
	s_nop 0
	global_load_lds_dwordx4 v[194:195], off
	v_lshl_add_u64 v[194:195], s[36:37], 0, v[172:173]
	s_add_i32 m0, s38, 0x2000
	s_nop 0
	global_load_lds_dwordx4 v[194:195], off
	v_lshl_add_u64 v[194:195], s[26:27], 0, v[158:159]
	s_mov_b32 m0, s67
	s_nop 0
	global_load_lds_dwordx4 v[194:195], off
	v_lshl_add_u64 v[194:195], s[26:27], 0, v[160:161]
	s_mov_b32 m0, s68
	s_nop 0
	global_load_lds_dwordx4 v[194:195], off
	s_waitcnt vmcnt(8)
	s_waitcnt lgkmcnt(0)
	s_barrier
	v_mfma_f32_16x16x32_bf16 v[62:65], v[114:117], v[182:185], v[62:65]
	v_mfma_f32_16x16x32_bf16 v[58:61], v[122:125], v[182:185], v[58:61]
	v_mfma_f32_16x16x32_bf16 v[46:49], v[114:117], v[190:193], v[46:49]
	v_mfma_f32_16x16x32_bf16 v[42:45], v[122:125], v[190:193], v[42:45]
	v_mfma_f32_16x16x32_bf16 v[30:33], v[114:117], v[204:207], v[30:33]
	v_mfma_f32_16x16x32_bf16 v[26:29], v[122:125], v[204:207], v[26:29]
	v_mfma_f32_16x16x32_bf16 v[14:17], v[114:117], v[212:215], v[14:17]
	v_mfma_f32_16x16x32_bf16 v[10:13], v[122:125], v[212:215], v[10:13]
	v_mfma_f32_16x16x32_bf16 v[62:65], v[118:121], v[186:189], v[62:65]
	v_mfma_f32_16x16x32_bf16 v[58:61], v[126:129], v[186:189], v[58:61]
	v_mfma_f32_16x16x32_bf16 v[46:49], v[118:121], v[200:203], v[46:49]
	v_mfma_f32_16x16x32_bf16 v[42:45], v[126:129], v[200:203], v[42:45]
	v_mfma_f32_16x16x32_bf16 v[30:33], v[118:121], v[208:211], v[30:33]
	v_mfma_f32_16x16x32_bf16 v[26:29], v[126:129], v[208:211], v[26:29]
	v_mfma_f32_16x16x32_bf16 v[14:17], v[118:121], v[222:225], v[14:17]
	v_mfma_f32_16x16x32_bf16 v[10:13], v[126:129], v[222:225], v[10:13]
	v_mfma_f32_16x16x32_bf16 v[54:57], v[138:141], v[182:185], v[54:57]
	v_mfma_f32_16x16x32_bf16 v[50:53], v[154:157], v[182:185], v[50:53]
	v_mfma_f32_16x16x32_bf16 v[38:41], v[138:141], v[190:193], v[38:41]
	v_mfma_f32_16x16x32_bf16 v[34:37], v[154:157], v[190:193], v[34:37]
	v_mfma_f32_16x16x32_bf16 v[22:25], v[138:141], v[204:207], v[22:25]
	v_mfma_f32_16x16x32_bf16 v[18:21], v[154:157], v[204:207], v[18:21]
	v_mfma_f32_16x16x32_bf16 v[6:9], v[138:141], v[212:215], v[6:9]
	v_mfma_f32_16x16x32_bf16 v[2:5], v[154:157], v[212:215], v[2:5]
	v_mfma_f32_16x16x32_bf16 v[54:57], v[142:145], v[186:189], v[54:57]
	v_mfma_f32_16x16x32_bf16 v[50:53], v[178:181], v[186:189], v[50:53]
	v_mfma_f32_16x16x32_bf16 v[38:41], v[142:145], v[200:203], v[38:41]
	v_mfma_f32_16x16x32_bf16 v[34:37], v[178:181], v[200:203], v[34:37]
	v_mfma_f32_16x16x32_bf16 v[22:25], v[142:145], v[208:211], v[22:25]
	v_mfma_f32_16x16x32_bf16 v[18:21], v[178:181], v[208:211], v[18:21]
	v_mfma_f32_16x16x32_bf16 v[6:9], v[142:145], v[222:225], v[6:9]
	v_mfma_f32_16x16x32_bf16 v[2:5], v[178:181], v[222:225], v[2:5]
	s_barrier
	s_add_i32 s82, s82, 2
	s_add_u32 s24, s24, 0x10000
	s_addc_u32 s25, s25, 0
	s_add_u32 s80, s80, 0x100
	s_addc_u32 s81, s81, 0
	s_cmpk_gt_u32 s82, 0x55
	s_cbranch_scc0 .LBB0_437
	s_and_b64 vcc, exec, s[18:19]
	s_cbranch_vccz .LBB0_440
	s_barrier

.LBB0_456:
	s_or_b64 exec, exec, s[24:25]
	s_and_b64 vcc, exec, s[6:7]
	s_mov_b64 s[6:7], -1
	s_cbranch_vccnz .LBB0_423
	s_andn2_b64 vcc, exec, s[8:9]
	s_cbranch_vccnz .LBB0_422
	s_branch .LBB0_422

.LBB0_623:
	s_add_u32 s6, s8, 0x100000
	s_addc_u32 s7, s9, 0
	s_lshl_b64 s[10:11], s[54:55], 3
	s_add_u32 s29, s6, s10
	v_writelane_b32 v255, s10, 28
	s_addc_u32 s71, s7, s11
	s_and_b64 vcc, exec, s[4:5]
	v_writelane_b32 v255, s11, 29
	v_readlane_b32 s10, v254, 56
	s_lshl_b32 s10, s10, 15
	s_add_i32 s54, s10, 0x48000
	v_readlane_b32 s11, v254, 57
	s_cbranch_vccnz .LBB0_671
	v_ashrrev_i32_e32 v3, 31, v157
	v_lshrrev_b32_e32 v3, 26, v3
	v_add_u32_e32 v3, v157, v3
	v_ashrrev_i32_e32 v10, 6, v3
	v_bfe_i32 v3, v157, 27, 1
	v_lshlrev_b32_e32 v2, 4, v157
	v_lshrrev_b32_e32 v3, 22, v3
	v_add_u32_e32 v3, v2, v3
	v_and_b32_e32 v3, 0xfffffc00, v3
	v_sub_u32_e32 v3, v2, v3
	v_lshrrev_b32_e32 v4, 4, v3
	v_bitop3_b32 v3, v4, v3, 32 bitop3:0x6c
	v_ashrrev_i32_e32 v5, 31, v3
	v_lshrrev_b32_e32 v5, 26, v5
	v_add_u32_e32 v5, v3, v5
	v_lshlrev_b32_e32 v4, 3, v10
	v_ashrrev_i32_e32 v11, 6, v5
	v_and_b32_e32 v5, 0xc0, v5
	v_and_b32_e32 v4, -16, v4
	v_sub_u32_e32 v3, v3, v5
	v_add_u32_e32 v4, v11, v4
	v_ashrrev_i16_sdwa v3, v219, sext(v3) dst_sel:DWORD dst_unused:UNUSED_PAD src0_sel:DWORD src1_sel:BYTE_0
	v_lshlrev_b32_e32 v6, 5, v10
	v_bfe_i32 v12, v3, 0, 16
	v_lshlrev_b32_e32 v3, 1, v4
	v_lshrrev_b32_e32 v5, 2, v4
	v_and_b32_e32 v7, 3, v11
	s_mov_b32 s5, 0xfffe0
	v_and_b32_e32 v6, 32, v6
	v_and_b32_e32 v3, 24, v3
	v_and_b32_e32 v5, 4, v5
	v_and_or_b32 v7, v4, s5, v7
	v_or3_b32 v3, v7, v5, v3
	v_add_lshl_u32 v5, v6, v12, 1
	v_add_u32_e32 v2, 0x2000, v2
	v_lshl_add_u32 v162, v3, 12, v5
	v_ashrrev_i32_e32 v3, 31, v2
	v_lshrrev_b32_e32 v3, 22, v3
	v_add_u32_e32 v3, v2, v3
	v_ashrrev_i32_e32 v13, 10, v3
	v_mul_i32_i24_e32 v3, 0x400, v13
	v_sub_u32_e32 v2, v2, v3
	v_lshrrev_b32_e32 v3, 4, v2
	v_bitop3_b32 v2, v3, v2, 32 bitop3:0x6c
	v_lshl_add_u32 v130, v4, 12, v5
	v_ashrrev_i32_e32 v4, 31, v2
	v_lshrrev_b32_e32 v4, 26, v4
	v_add_u32_e32 v4, v2, v4
	v_lshlrev_b32_e32 v3, 3, v13
	v_ashrrev_i32_e32 v14, 6, v4
	v_and_b32_e32 v4, 0xc0, v4
	v_and_b32_e32 v3, -16, v3
	v_sub_u32_e32 v2, v2, v4
	v_add_u32_e32 v3, v14, v3
	v_ashrrev_i16_sdwa v2, v219, sext(v2) dst_sel:DWORD dst_unused:UNUSED_PAD src0_sel:DWORD src1_sel:BYTE_0
	v_lshlrev_b32_e32 v5, 5, v13
	v_bfe_i32 v15, v2, 0, 16
	v_lshlrev_b32_e32 v2, 1, v3
	v_lshrrev_b32_e32 v4, 2, v3
	v_and_b32_e32 v6, 3, v14
	v_and_b32_e32 v5, 32, v5
	v_and_b32_e32 v2, 24, v2
	v_and_b32_e32 v4, 4, v4
	v_and_or_b32 v6, v3, s5, v6
	s_ashr_i32 s5, s16, 6
	s_ashr_i32 s57, s56, 31
	s_ashr_i32 s4, s16, 8
	v_or3_b32 v2, v6, v4, v2
	v_add_lshl_u32 v4, v5, v15, 1
	s_lshl_b32 s72, s5, 10
	s_lshl_b64 s[10:11], s[56:57], 11
	v_lshl_add_u32 v134, v2, 12, v4
	v_mov_b32_e32 v2, v157
	s_add_u32 s10, s29, s10
	v_lshl_add_u32 v132, v3, 12, v4
	s_addc_u32 s11, s71, s11
	v_ashrrev_i32_e32 v3, 31, v2
	v_lshl_add_u64 v[2:3], v[2:3], 2, s[10:11]
	s_lshl_b32 s10, s5, 8
	s_add_i32 s73, s10, 0
	s_add_i32 s73, s73, 0x20940
	s_mov_b32 m0, s73
	s_add_i32 s41, s72, 0
	global_load_lds_dword v[2:3], off
	s_add_i32 m0, s41, 0x10000
	v_mov_b32_e32 v135, v163
	global_load_lds_dwordx4 v162, s[60:61]
	s_add_i32 m0, s41, 0x12000
	s_add_u32 s10, s60, 0x80000
	global_load_lds_dwordx4 v134, s[60:61]
	s_addc_u32 s11, s61, 0
	s_add_i32 m0, s41, 0x14000
	s_add_i32 s66, s41, 0x2000
	global_load_lds_dwordx4 v162, s[10:11]
	s_add_i32 m0, s41, 0x16000
	v_mov_b32_e32 v131, v163
	global_load_lds_dwordx4 v134, s[10:11]
	s_mov_b32 m0, s41
	s_add_u32 s10, s58, 0x80000
	global_load_lds_dwordx4 v130, s[58:59]
	s_mov_b32 m0, s66
	s_addc_u32 s11, s59, 0
	s_add_i32 s74, s41, 0x4000
	global_load_lds_dwordx4 v132, s[58:59]
	s_mov_b32 m0, s74
	s_add_i32 s75, s41, 0x6000
	global_load_lds_dwordx4 v130, s[10:11]
	s_mov_b32 m0, s75
	v_mov_b32_e32 v133, v163
	global_load_lds_dwordx4 v132, s[10:11]
	s_cmp_eq_u32 s4, 1
	v_lshl_add_u64 v[8:9], s[60:61], 0, v[162:163]
	v_lshl_add_u64 v[6:7], s[60:61], 0, v[134:135]
	v_lshl_add_u64 v[2:3], s[58:59], 0, v[130:131]
	s_cselect_b64 s[10:11], -1, 0
	s_cmp_lg_u32 s4, 1
	v_lshl_add_u64 v[4:5], s[58:59], 0, v[132:133]
	s_cbranch_scc1 .LBB0_626
.LBB0_626:
	s_add_u32 s12, s8, 0x32000000
	v_bfe_u32 v17, v157, 4, 2
	s_addc_u32 s13, s9, 0
	s_lshl_b64 s[14:15], s[54:55], 3
	v_and_b32_e32 v16, 15, v157
	v_lshlrev_b32_e32 v18, 4, v17
	s_add_u32 s14, s6, s14
	v_lshl_or_b32 v159, s4, 6, v16
	v_lshl_or_b32 v16, v16, 6, v18
	v_lshlrev_b32_e32 v18, 2, v157
	s_addc_u32 s15, s7, s15
	s_lshl_b32 s4, s4, 13
	v_and_b32_e32 v18, 32, v18
	v_bitop3_b32 v19, v16, s4, v18 bitop3:0xde
	s_lshl_b32 s4, s5, 5
	s_and_b32 s6, s4, 0x60
	s_add_i32 m0, s41, 0x18000
	v_lshl_add_u64 v[8:9], v[8:9], 0, s[44:45]
	s_lshl_b32 s4, s6, 7
	s_waitcnt vmcnt(2)
	s_barrier
	global_load_lds_dwordx4 v[8:9], off
	v_lshl_add_u64 v[6:7], v[6:7], 0, s[44:45]
	s_add_i32 m0, s41, 0x1a000
	s_add_i32 s76, s41, 0x8000
	s_add_i32 s77, s41, 0xa000
	v_bitop3_b32 v161, v16, s4, v18 bitop3:0xde
	global_load_lds_dwordx4 v[6:7], off
	v_lshl_add_u64 v[2:3], v[2:3], 0, s[44:45]
	s_mov_b32 m0, s76
	s_add_u32 s4, s60, 0x80080
	global_load_lds_dwordx4 v[2:3], off
	v_lshl_add_u64 v[2:3], v[4:5], 0, s[44:45]
	s_mov_b32 m0, s77
	s_addc_u32 s5, s61, 0
	global_load_lds_dwordx4 v[2:3], off
	s_add_i32 m0, s41, 0x1c000
	v_lshl_add_u64 v[2:3], s[4:5], 0, v[162:163]
	global_load_lds_dwordx4 v[2:3], off
	v_lshl_add_u64 v[2:3], s[4:5], 0, v[134:135]
	s_add_i32 m0, s41, 0x1e000
	s_and_b32 s4, s2, 7
	global_load_lds_dwordx4 v[2:3], off
	v_lshlrev_b32_e32 v2, 15, v13
	v_and_b32_e32 v2, 0xffff0000, v2
	s_ashr_i32 s79, s2, 3
	v_lshl_add_u32 v2, v14, 12, v2
	v_and_b32_e32 v3, 1, v13
	s_lshl_b32 s5, s4, 3
	s_and_b32 s7, s79, 7
	v_lshl_or_b32 v2, v3, 6, v2
	s_ashr_i32 s78, s2, 31
	s_or_b32 s80, s5, s7
	s_lshl_b32 s81, s4, 1
	v_lshl_add_u32 v136, v15, 1, v2
	v_lshlrev_b32_e32 v2, 15, v10
	s_cmpk_lt_u32 s16, 0x100
	v_and_b32_e32 v2, 0xffff0000, v2
	s_waitcnt vmcnt(6)
	s_cselect_b64 s[16:17], -1, 0
	s_add_i32 s4, 0, 0x20940
	v_lshl_add_u32 v2, v11, 12, v2
	v_and_b32_e32 v3, 1, v10
	s_add_u32 s18, s14, 0x20000
	v_lshl_or_b32 v2, v3, 6, v2
	v_lshl_add_u32 v175, v159, 3, s4
	s_mov_b32 s27, 0
	v_cmp_eq_u32_e64 s[4:5], 0, v17
	s_addc_u32 s19, s15, 0
	v_lshl_or_b32 v177, v17, 3, s6
	v_mov_b32_e32 v137, v163
	v_lshl_add_u32 v138, v12, 1, v2
	v_mov_b32_e32 v139, v163
	v_add_u32_e32 v179, 0, v19
	s_mov_b32 s82, 0
	s_mov_b32 s31, 0x2f800000
	s_barrier
	s_branch .LBB0_629

.LBB0_642:
	s_add_u32 s21, s60, 0x100
	s_addc_u32 s57, s61, 0
	s_add_u32 s58, s58, 0x80080
	v_mov_b32_e32 v2, 0
	s_addc_u32 s59, s59, 0
	s_mov_b32 s64, -2
	s_waitcnt lgkmcnt(0)
	v_mov_b32_e32 v3, v2
	v_mov_b32_e32 v4, v2
	v_mov_b32_e32 v5, v2
	v_mov_b32_e32 v6, v2
	v_mov_b32_e32 v7, v2
	v_mov_b32_e32 v8, v2
	v_mov_b32_e32 v9, v2
	v_mov_b32_e32 v18, v2
	v_mov_b32_e32 v19, v2
	v_mov_b32_e32 v20, v2
	v_mov_b32_e32 v21, v2
	v_mov_b32_e32 v22, v2
	v_mov_b32_e32 v23, v2
	v_mov_b32_e32 v24, v2
	v_mov_b32_e32 v25, v2
	v_mov_b32_e32 v34, v2
	v_mov_b32_e32 v35, v2
	v_mov_b32_e32 v36, v2
	v_mov_b32_e32 v37, v2
	v_mov_b32_e32 v38, v2
	v_mov_b32_e32 v39, v2
	v_mov_b32_e32 v40, v2
	v_mov_b32_e32 v41, v2
	v_mov_b32_e32 v50, v2
	v_mov_b32_e32 v51, v2
	v_mov_b32_e32 v52, v2
	v_mov_b32_e32 v53, v2
	v_mov_b32_e32 v54, v2
	v_mov_b32_e32 v55, v2
	v_mov_b32_e32 v56, v2
	v_mov_b32_e32 v57, v2
	v_mov_b32_e32 v10, v2
	v_mov_b32_e32 v11, v2
	v_mov_b32_e32 v12, v2
	v_mov_b32_e32 v13, v2
	v_mov_b32_e32 v14, v2
	v_mov_b32_e32 v15, v2
	v_mov_b32_e32 v16, v2
	v_mov_b32_e32 v17, v2
	v_mov_b32_e32 v26, v2
	v_mov_b32_e32 v27, v2
	v_mov_b32_e32 v28, v2
	v_mov_b32_e32 v29, v2
	v_mov_b32_e32 v30, v2
	v_mov_b32_e32 v31, v2
	v_mov_b32_e32 v32, v2
	v_mov_b32_e32 v33, v2
	v_mov_b32_e32 v42, v2
	v_mov_b32_e32 v43, v2
	v_mov_b32_e32 v44, v2
	v_mov_b32_e32 v45, v2
	v_mov_b32_e32 v46, v2
	v_mov_b32_e32 v47, v2
	v_mov_b32_e32 v48, v2
	v_mov_b32_e32 v49, v2
	v_mov_b32_e32 v58, v2
	v_mov_b32_e32 v59, v2
	v_mov_b32_e32 v60, v2
	v_mov_b32_e32 v61, v2
	v_mov_b32_e32 v62, v2
	v_mov_b32_e32 v63, v2
	v_mov_b32_e32 v64, v2
	v_mov_b32_e32 v65, v2
	v_mov_b32_e32 v66, v2
	v_mov_b32_e32 v67, v2
	v_mov_b32_e32 v68, v2
	v_mov_b32_e32 v69, v2
	v_mov_b32_e32 v70, v2
	v_mov_b32_e32 v71, v2
	v_mov_b32_e32 v72, v2
	v_mov_b32_e32 v73, v2
	v_mov_b32_e32 v82, v2
	v_mov_b32_e32 v83, v2
	v_mov_b32_e32 v84, v2
	v_mov_b32_e32 v85, v2
	v_mov_b32_e32 v90, v2
	v_mov_b32_e32 v91, v2
	v_mov_b32_e32 v92, v2
	v_mov_b32_e32 v93, v2
	v_mov_b32_e32 v110, v2
	v_mov_b32_e32 v111, v2
	v_mov_b32_e32 v112, v2
	v_mov_b32_e32 v113, v2
	v_mov_b32_e32 v114, v2
	v_mov_b32_e32 v115, v2
	v_mov_b32_e32 v116, v2
	v_mov_b32_e32 v117, v2
	v_mov_b32_e32 v98, v2
	v_mov_b32_e32 v99, v2
	v_mov_b32_e32 v100, v2
	v_mov_b32_e32 v101, v2
	v_mov_b32_e32 v122, v2
	v_mov_b32_e32 v123, v2
	v_mov_b32_e32 v124, v2
	v_mov_b32_e32 v125, v2
	v_mov_b32_e32 v74, v2
	v_mov_b32_e32 v75, v2
	v_mov_b32_e32 v76, v2
	v_mov_b32_e32 v77, v2
	v_mov_b32_e32 v78, v2
	v_mov_b32_e32 v79, v2
	v_mov_b32_e32 v80, v2
	v_mov_b32_e32 v81, v2
	v_mov_b32_e32 v102, v2
	v_mov_b32_e32 v103, v2
	v_mov_b32_e32 v104, v2
	v_mov_b32_e32 v105, v2
	v_mov_b32_e32 v106, v2
	v_mov_b32_e32 v107, v2
	v_mov_b32_e32 v108, v2
	v_mov_b32_e32 v109, v2
	v_mov_b32_e32 v94, v2
	v_mov_b32_e32 v95, v2
	v_mov_b32_e32 v96, v2
	v_mov_b32_e32 v97, v2
	v_mov_b32_e32 v118, v2
	v_mov_b32_e32 v119, v2
	v_mov_b32_e32 v120, v2
	v_mov_b32_e32 v121, v2
	v_mov_b32_e32 v86, v2
	v_mov_b32_e32 v87, v2
	v_mov_b32_e32 v88, v2
	v_mov_b32_e32 v89, v2
	v_mov_b32_e32 v126, v2
	v_mov_b32_e32 v127, v2
	v_mov_b32_e32 v128, v2
	v_mov_b32_e32 v129, v2
	v_readfirstlane_b32 s100, v0
	s_nop 3
	s_bitcmp1_b32 s100, 8
	s_cbranch_scc0 .Lrb_skip2
	s_barrier
.Lrb_skip2:
.LBB0_643:
	s_add_u32 s36, s58, 0xfff80080
	s_addc_u32 s37, s59, -1
	s_add_i32 s38, 0, 0x10000
	s_cmp_eq_u32 s64, 28
	s_cselect_b32 s63, s23, s37
	s_cselect_b32 s62, s22, s36
	s_cselect_b32 s61, s25, s57
	s_cselect_b32 s60, s24, s21
	s_add_i32 s39, 0, 0x14000
	v_add_u32_e32 v152, s38, v161
	v_add_u32_e32 v156, s39, v161
	ds_read_b128 v[140:143], v152
	ds_read_b128 v[144:147], v152 offset:1024
	ds_read_b128 v[148:151], v152 offset:2048
	ds_read_b128 v[152:155], v152 offset:3072
	ds_read_b128 v[180:183], v156
	ds_read_b128 v[184:187], v156 offset:1024
	ds_read_b128 v[188:191], v156 offset:2048
	ds_read_b128 v[192:195], v156 offset:3072
	v_lshl_add_u64 v[172:173], s[58:59], 0, v[138:139]
	s_add_i32 m0, s41, 0xc000
	ds_read_b128 v[196:199], v179
	ds_read_b128 v[200:203], v179 offset:1024
	ds_read_b128 v[204:207], v179 offset:2048
	ds_read_b128 v[208:211], v179 offset:3072
	ds_read_b128 v[212:215], v179 offset:4096
	ds_read_b128 v[222:225], v179 offset:5120
	ds_read_b128 v[226:229], v179 offset:6144
	ds_read_b128 v[230:233], v179 offset:7168
	global_load_lds_dwordx4 v[172:173], off
	v_lshl_add_u64 v[172:173], s[58:59], 0, v[136:137]
	s_add_i32 m0, s41, 0xe000
	s_nop 0
	global_load_lds_dwordx4 v[172:173], off
	s_waitcnt vmcnt(8)
	s_waitcnt lgkmcnt(0)
	s_barrier
	v_mfma_f32_16x16x32_bf16 v[126:129], v[140:143], v[196:199], v[126:129]
	v_mfma_f32_16x16x32_bf16 v[86:89], v[148:151], v[196:199], v[86:89]
	v_mfma_f32_16x16x32_bf16 v[118:121], v[140:143], v[204:207], v[118:121]
	v_mfma_f32_16x16x32_bf16 v[94:97], v[148:151], v[204:207], v[94:97]
	v_mfma_f32_16x16x32_bf16 v[106:109], v[140:143], v[212:215], v[106:109]
	v_mfma_f32_16x16x32_bf16 v[102:105], v[148:151], v[212:215], v[102:105]
	v_mfma_f32_16x16x32_bf16 v[78:81], v[140:143], v[226:229], v[78:81]
	v_mfma_f32_16x16x32_bf16 v[74:77], v[148:151], v[226:229], v[74:77]
	v_mfma_f32_16x16x32_bf16 v[126:129], v[144:147], v[200:203], v[126:129]
	v_mfma_f32_16x16x32_bf16 v[86:89], v[152:155], v[200:203], v[86:89]
	v_mfma_f32_16x16x32_bf16 v[118:121], v[144:147], v[208:211], v[118:121]
	v_mfma_f32_16x16x32_bf16 v[94:97], v[152:155], v[208:211], v[94:97]
	v_mfma_f32_16x16x32_bf16 v[106:109], v[144:147], v[222:225], v[106:109]
	v_mfma_f32_16x16x32_bf16 v[102:105], v[152:155], v[222:225], v[102:105]
	v_mfma_f32_16x16x32_bf16 v[78:81], v[144:147], v[230:233], v[78:81]
	v_mfma_f32_16x16x32_bf16 v[74:77], v[152:155], v[230:233], v[74:77]
	v_mfma_f32_16x16x32_bf16 v[122:125], v[180:183], v[196:199], v[122:125]
	v_mfma_f32_16x16x32_bf16 v[98:101], v[188:191], v[196:199], v[98:101]
	v_mfma_f32_16x16x32_bf16 v[114:117], v[180:183], v[204:207], v[114:117]
	v_mfma_f32_16x16x32_bf16 v[110:113], v[188:191], v[204:207], v[110:113]
	v_mfma_f32_16x16x32_bf16 v[90:93], v[180:183], v[212:215], v[90:93]
	v_mfma_f32_16x16x32_bf16 v[82:85], v[188:191], v[212:215], v[82:85]
	v_mfma_f32_16x16x32_bf16 v[70:73], v[180:183], v[226:229], v[70:73]
	v_mfma_f32_16x16x32_bf16 v[66:69], v[188:191], v[226:229], v[66:69]
	v_mfma_f32_16x16x32_bf16 v[122:125], v[184:187], v[200:203], v[122:125]
	v_mfma_f32_16x16x32_bf16 v[98:101], v[192:195], v[200:203], v[98:101]
	v_mfma_f32_16x16x32_bf16 v[114:117], v[184:187], v[208:211], v[114:117]
	v_mfma_f32_16x16x32_bf16 v[110:113], v[192:195], v[208:211], v[110:113]
	v_mfma_f32_16x16x32_bf16 v[90:93], v[184:187], v[222:225], v[90:93]
	v_mfma_f32_16x16x32_bf16 v[82:85], v[192:195], v[222:225], v[82:85]
	v_mfma_f32_16x16x32_bf16 v[70:73], v[184:187], v[230:233], v[70:73]
	v_mfma_f32_16x16x32_bf16 v[66:69], v[192:195], v[230:233], v[66:69]
	s_barrier
	s_add_i32 s36, s38, s72
	v_lshl_add_u64 v[172:173], s[60:61], 0, v[162:163]
	s_mov_b32 m0, s36
	ds_read_b128 v[196:199], v179 offset:16384
	ds_read_b128 v[200:203], v179 offset:17408
	ds_read_b128 v[204:207], v179 offset:18432
	ds_read_b128 v[208:211], v179 offset:19456
	ds_read_b128 v[212:215], v179 offset:20480
	ds_read_b128 v[222:225], v179 offset:21504
	ds_read_b128 v[226:229], v179 offset:22528
	ds_read_b128 v[230:233], v179 offset:23552
	global_load_lds_dwordx4 v[172:173], off
	s_add_i32 m0, s36, 0x2000
	s_add_u32 s36, s60, 0x80000
	v_lshl_add_u64 v[216:217], s[60:61], 0, v[134:135]
	s_addc_u32 s37, s61, 0
	s_add_i32 s38, s39, s72
	global_load_lds_dwordx4 v[216:217], off
	v_lshl_add_u64 v[234:235], s[36:37], 0, v[162:163]
	s_mov_b32 m0, s38
	v_lshl_add_u64 v[236:237], s[62:63], 0, v[132:133]
	global_load_lds_dwordx4 v[234:235], off
	v_lshl_add_u64 v[234:235], s[36:37], 0, v[134:135]
	s_add_i32 m0, s38, 0x2000
	s_nop 0
	global_load_lds_dwordx4 v[234:235], off
	v_lshl_add_u64 v[234:235], s[62:63], 0, v[130:131]
	s_mov_b32 m0, s41
	s_nop 0
	global_load_lds_dwordx4 v[234:235], off
	s_mov_b32 m0, s66
	s_nop 0
	global_load_lds_dwordx4 v[236:237], off
	s_waitcnt vmcnt(8)
	s_waitcnt lgkmcnt(0)
	s_barrier
	v_mfma_f32_16x16x32_bf16 v[62:65], v[140:143], v[196:199], v[62:65]
	v_mfma_f32_16x16x32_bf16 v[58:61], v[148:151], v[196:199], v[58:61]
	v_mfma_f32_16x16x32_bf16 v[46:49], v[140:143], v[204:207], v[46:49]
	v_mfma_f32_16x16x32_bf16 v[42:45], v[148:151], v[204:207], v[42:45]
	v_mfma_f32_16x16x32_bf16 v[30:33], v[140:143], v[212:215], v[30:33]
	v_mfma_f32_16x16x32_bf16 v[26:29], v[148:151], v[212:215], v[26:29]
	v_mfma_f32_16x16x32_bf16 v[14:17], v[140:143], v[226:229], v[14:17]
	v_mfma_f32_16x16x32_bf16 v[10:13], v[148:151], v[226:229], v[10:13]
	v_mfma_f32_16x16x32_bf16 v[62:65], v[144:147], v[200:203], v[62:65]
	v_mfma_f32_16x16x32_bf16 v[58:61], v[152:155], v[200:203], v[58:61]
	v_mfma_f32_16x16x32_bf16 v[46:49], v[144:147], v[208:211], v[46:49]
	v_mfma_f32_16x16x32_bf16 v[42:45], v[152:155], v[208:211], v[42:45]
	v_mfma_f32_16x16x32_bf16 v[30:33], v[144:147], v[222:225], v[30:33]
	v_mfma_f32_16x16x32_bf16 v[26:29], v[152:155], v[222:225], v[26:29]
	v_mfma_f32_16x16x32_bf16 v[14:17], v[144:147], v[230:233], v[14:17]
	v_mfma_f32_16x16x32_bf16 v[10:13], v[152:155], v[230:233], v[10:13]
	v_mfma_f32_16x16x32_bf16 v[54:57], v[180:183], v[196:199], v[54:57]
	v_mfma_f32_16x16x32_bf16 v[50:53], v[188:191], v[196:199], v[50:53]
	v_mfma_f32_16x16x32_bf16 v[38:41], v[180:183], v[204:207], v[38:41]
	v_mfma_f32_16x16x32_bf16 v[34:37], v[188:191], v[204:207], v[34:37]
	v_mfma_f32_16x16x32_bf16 v[22:25], v[180:183], v[212:215], v[22:25]
	v_mfma_f32_16x16x32_bf16 v[18:21], v[188:191], v[212:215], v[18:21]
	v_mfma_f32_16x16x32_bf16 v[6:9], v[180:183], v[226:229], v[6:9]
	v_mfma_f32_16x16x32_bf16 v[2:5], v[188:191], v[226:229], v[2:5]
	v_mfma_f32_16x16x32_bf16 v[54:57], v[184:187], v[200:203], v[54:57]
	v_mfma_f32_16x16x32_bf16 v[50:53], v[192:195], v[200:203], v[50:53]
	v_mfma_f32_16x16x32_bf16 v[38:41], v[184:187], v[208:211], v[38:41]
	v_mfma_f32_16x16x32_bf16 v[34:37], v[192:195], v[208:211], v[34:37]
	v_mfma_f32_16x16x32_bf16 v[22:25], v[184:187], v[222:225], v[22:25]
	v_mfma_f32_16x16x32_bf16 v[18:21], v[192:195], v[222:225], v[18:21]
	v_mfma_f32_16x16x32_bf16 v[6:9], v[184:187], v[230:233], v[6:9]
	v_mfma_f32_16x16x32_bf16 v[2:5], v[192:195], v[230:233], v[2:5]
	s_barrier
	s_add_i32 s38, 0, 0x18000
	s_add_i32 s39, 0, 0x1c000
	v_add_u32_e32 v152, s38, v161
	v_add_u32_e32 v156, s39, v161
	ds_read_b128 v[140:143], v152
	ds_read_b128 v[144:147], v152 offset:1024
	ds_read_b128 v[148:151], v152 offset:2048
	ds_read_b128 v[152:155], v152 offset:3072
	ds_read_b128 v[180:183], v156
	ds_read_b128 v[184:187], v156 offset:1024
	ds_read_b128 v[188:191], v156 offset:2048
	ds_read_b128 v[192:195], v156 offset:3072
	s_add_u32 s36, s62, 0x80000
	s_addc_u32 s37, s63, 0
	s_mov_b32 m0, s74
	v_lshl_add_u64 v[238:239], s[36:37], 0, v[130:131]
	ds_read_b128 v[196:199], v179 offset:32768
	ds_read_b128 v[200:203], v179 offset:33792
	ds_read_b128 v[204:207], v179 offset:34816
	ds_read_b128 v[208:211], v179 offset:35840
	ds_read_b128 v[212:215], v179 offset:36864
	ds_read_b128 v[222:225], v179 offset:37888
	ds_read_b128 v[226:229], v179 offset:38912
	ds_read_b128 v[230:233], v179 offset:39936
	global_load_lds_dwordx4 v[238:239], off
	v_lshl_add_u64 v[238:239], s[36:37], 0, v[132:133]
	s_mov_b32 m0, s75
	s_nop 0
	global_load_lds_dwordx4 v[238:239], off
	s_waitcnt vmcnt(8)
	s_waitcnt lgkmcnt(0)
	s_barrier
	v_mfma_f32_16x16x32_bf16 v[126:129], v[140:143], v[196:199], v[126:129]
	v_mfma_f32_16x16x32_bf16 v[86:89], v[148:151], v[196:199], v[86:89]
	v_mfma_f32_16x16x32_bf16 v[118:121], v[140:143], v[204:207], v[118:121]
	v_mfma_f32_16x16x32_bf16 v[94:97], v[148:151], v[204:207], v[94:97]
	v_mfma_f32_16x16x32_bf16 v[106:109], v[140:143], v[212:215], v[106:109]
	v_mfma_f32_16x16x32_bf16 v[102:105], v[148:151], v[212:215], v[102:105]
	v_mfma_f32_16x16x32_bf16 v[78:81], v[140:143], v[226:229], v[78:81]
	v_mfma_f32_16x16x32_bf16 v[74:77], v[148:151], v[226:229], v[74:77]
	v_mfma_f32_16x16x32_bf16 v[126:129], v[144:147], v[200:203], v[126:129]
	v_mfma_f32_16x16x32_bf16 v[86:89], v[152:155], v[200:203], v[86:89]
	v_mfma_f32_16x16x32_bf16 v[118:121], v[144:147], v[208:211], v[118:121]
	v_mfma_f32_16x16x32_bf16 v[94:97], v[152:155], v[208:211], v[94:97]
	v_mfma_f32_16x16x32_bf16 v[106:109], v[144:147], v[222:225], v[106:109]
	v_mfma_f32_16x16x32_bf16 v[102:105], v[152:155], v[222:225], v[102:105]
	v_mfma_f32_16x16x32_bf16 v[78:81], v[144:147], v[230:233], v[78:81]
	v_mfma_f32_16x16x32_bf16 v[74:77], v[152:155], v[230:233], v[74:77]
	v_mfma_f32_16x16x32_bf16 v[122:125], v[180:183], v[196:199], v[122:125]
	v_mfma_f32_16x16x32_bf16 v[98:101], v[188:191], v[196:199], v[98:101]
	v_mfma_f32_16x16x32_bf16 v[114:117], v[180:183], v[204:207], v[114:117]
	v_mfma_f32_16x16x32_bf16 v[110:113], v[188:191], v[204:207], v[110:113]
	v_mfma_f32_16x16x32_bf16 v[90:93], v[180:183], v[212:215], v[90:93]
	v_mfma_f32_16x16x32_bf16 v[82:85], v[188:191], v[212:215], v[82:85]
	v_mfma_f32_16x16x32_bf16 v[70:73], v[180:183], v[226:229], v[70:73]
	v_mfma_f32_16x16x32_bf16 v[66:69], v[188:191], v[226:229], v[66:69]
	v_mfma_f32_16x16x32_bf16 v[122:125], v[184:187], v[200:203], v[122:125]
	v_mfma_f32_16x16x32_bf16 v[98:101], v[192:195], v[200:203], v[98:101]
	v_mfma_f32_16x16x32_bf16 v[114:117], v[184:187], v[208:211], v[114:117]
	v_mfma_f32_16x16x32_bf16 v[110:113], v[192:195], v[208:211], v[110:113]
	v_mfma_f32_16x16x32_bf16 v[90:93], v[184:187], v[222:225], v[90:93]
	v_mfma_f32_16x16x32_bf16 v[82:85], v[192:195], v[222:225], v[82:85]
	v_mfma_f32_16x16x32_bf16 v[70:73], v[184:187], v[230:233], v[70:73]
	v_mfma_f32_16x16x32_bf16 v[66:69], v[192:195], v[230:233], v[66:69]
	s_barrier
	s_add_i32 s36, s38, s72
	v_lshl_add_u64 v[172:173], v[172:173], 0, s[44:45]
	s_mov_b32 m0, s36
	ds_read_b128 v[196:199], v179 offset:49152
	ds_read_b128 v[200:203], v179 offset:50176
	ds_read_b128 v[204:207], v179 offset:51200
	ds_read_b128 v[208:211], v179 offset:52224
	ds_read_b128 v[212:215], v179 offset:53248
	ds_read_b128 v[222:225], v179 offset:54272
	ds_read_b128 v[226:229], v179 offset:55296
	ds_read_b128 v[230:233], v179 offset:56320
	global_load_lds_dwordx4 v[172:173], off
	s_add_i32 m0, s36, 0x2000
	s_add_u32 s36, s60, 0x80080
	v_lshl_add_u64 v[172:173], v[216:217], 0, s[44:45]
	s_addc_u32 s37, s61, 0
	s_add_i32 s38, s39, s72
	global_load_lds_dwordx4 v[172:173], off
	v_lshl_add_u64 v[172:173], s[36:37], 0, v[162:163]
	s_mov_b32 m0, s38
	s_nop 0
	global_load_lds_dwordx4 v[172:173], off
	v_lshl_add_u64 v[172:173], s[36:37], 0, v[134:135]
	s_add_i32 m0, s38, 0x2000
	s_nop 0
	global_load_lds_dwordx4 v[172:173], off
	v_lshl_add_u64 v[172:173], v[234:235], 0, s[44:45]
	s_mov_b32 m0, s76
	s_nop 0
	global_load_lds_dwordx4 v[172:173], off
	v_lshl_add_u64 v[172:173], v[236:237], 0, s[44:45]
	s_mov_b32 m0, s77
	s_nop 0
	global_load_lds_dwordx4 v[172:173], off
	s_waitcnt vmcnt(8)
	s_waitcnt lgkmcnt(0)
	s_barrier
	v_mfma_f32_16x16x32_bf16 v[62:65], v[140:143], v[196:199], v[62:65]
	v_mfma_f32_16x16x32_bf16 v[58:61], v[148:151], v[196:199], v[58:61]
	v_mfma_f32_16x16x32_bf16 v[46:49], v[140:143], v[204:207], v[46:49]
	v_mfma_f32_16x16x32_bf16 v[42:45], v[148:151], v[204:207], v[42:45]
	v_mfma_f32_16x16x32_bf16 v[30:33], v[140:143], v[212:215], v[30:33]
	v_mfma_f32_16x16x32_bf16 v[26:29], v[148:151], v[212:215], v[26:29]
	v_mfma_f32_16x16x32_bf16 v[14:17], v[140:143], v[226:229], v[14:17]
	v_mfma_f32_16x16x32_bf16 v[10:13], v[148:151], v[226:229], v[10:13]
	v_mfma_f32_16x16x32_bf16 v[62:65], v[144:147], v[200:203], v[62:65]
	v_mfma_f32_16x16x32_bf16 v[58:61], v[152:155], v[200:203], v[58:61]
	v_mfma_f32_16x16x32_bf16 v[46:49], v[144:147], v[208:211], v[46:49]
	v_mfma_f32_16x16x32_bf16 v[42:45], v[152:155], v[208:211], v[42:45]
	v_mfma_f32_16x16x32_bf16 v[30:33], v[144:147], v[222:225], v[30:33]
	v_mfma_f32_16x16x32_bf16 v[26:29], v[152:155], v[222:225], v[26:29]
	v_mfma_f32_16x16x32_bf16 v[14:17], v[144:147], v[230:233], v[14:17]
	v_mfma_f32_16x16x32_bf16 v[10:13], v[152:155], v[230:233], v[10:13]
	v_mfma_f32_16x16x32_bf16 v[54:57], v[180:183], v[196:199], v[54:57]
	v_mfma_f32_16x16x32_bf16 v[50:53], v[188:191], v[196:199], v[50:53]
	v_mfma_f32_16x16x32_bf16 v[38:41], v[180:183], v[204:207], v[38:41]
	v_mfma_f32_16x16x32_bf16 v[34:37], v[188:191], v[204:207], v[34:37]
	v_mfma_f32_16x16x32_bf16 v[22:25], v[180:183], v[212:215], v[22:25]
	v_mfma_f32_16x16x32_bf16 v[18:21], v[188:191], v[212:215], v[18:21]
	v_mfma_f32_16x16x32_bf16 v[6:9], v[180:183], v[226:229], v[6:9]
	v_mfma_f32_16x16x32_bf16 v[2:5], v[188:191], v[226:229], v[2:5]
	v_mfma_f32_16x16x32_bf16 v[54:57], v[184:187], v[200:203], v[54:57]
	v_mfma_f32_16x16x32_bf16 v[50:53], v[192:195], v[200:203], v[50:53]
	v_mfma_f32_16x16x32_bf16 v[38:41], v[184:187], v[208:211], v[38:41]
	v_mfma_f32_16x16x32_bf16 v[34:37], v[192:195], v[208:211], v[34:37]
	v_mfma_f32_16x16x32_bf16 v[22:25], v[184:187], v[222:225], v[22:25]
	v_mfma_f32_16x16x32_bf16 v[18:21], v[192:195], v[222:225], v[18:21]
	v_mfma_f32_16x16x32_bf16 v[6:9], v[184:187], v[230:233], v[6:9]
	v_mfma_f32_16x16x32_bf16 v[2:5], v[192:195], v[230:233], v[2:5]
	s_barrier
	s_add_i32 s64, s64, 2
	s_add_u32 s21, s21, 0x100
	s_addc_u32 s57, s57, 0
	s_add_u32 s58, s58, 0x100
	s_addc_u32 s59, s59, 0
	s_cmp_gt_u32 s64, 29
	s_cbranch_scc0 .LBB0_643
	s_and_b64 vcc, exec, s[16:17]
	s_cbranch_vccz .LBB0_646
	s_barrier

.LBB0_667:
	s_and_b64 vcc, exec, s[6:7]
	s_mov_b64 s[6:7], -1
	s_cbranch_vccnz .LBB0_628
	s_ashr_i32 s21, s20, 31
	s_and_b32 s27, s82, 1
	s_lshl_b64 s[6:7], s[20:21], 11
	v_mov_b32_e32 v2, v157
	s_add_u32 s6, s29, s6
	s_addc_u32 s7, s71, s7
	s_waitcnt lgkmcnt(0)
	v_ashrrev_i32_e32 v3, 31, v2
	v_lshl_add_u64 v[2:3], v[2:3], 2, s[6:7]
	s_mul_i32 s6, s27, 0x1400
	s_add_i32 m0, s73, s6
	s_andn2_b64 vcc, exec, s[10:11]
	global_load_lds_dword v[2:3], off
	s_cbranch_vccnz .LBB0_627
	s_branch .LBB0_627

.LBB0_681:
	v_ashrrev_i32_e32 v3, 31, v141
	v_lshrrev_b32_e32 v3, 26, v3
	v_add_u32_e32 v3, v141, v3
	v_ashrrev_i32_e32 v10, 6, v3
	v_bfe_i32 v3, v141, 27, 1
	v_lshlrev_b32_e32 v2, 4, v141
	v_lshrrev_b32_e32 v3, 22, v3
	v_add_u32_e32 v3, v2, v3
	v_and_b32_e32 v3, 0xfffffc00, v3
	v_sub_u32_e32 v3, v2, v3
	v_lshrrev_b32_e32 v4, 4, v3
	v_bitop3_b32 v3, v4, v3, 32 bitop3:0x6c
	s_add_u32 s63, s8, 0x67000000
	v_ashrrev_i32_e32 v5, 31, v3
	s_addc_u32 s64, s9, 0
	v_lshrrev_b32_e32 v5, 26, v5
	s_add_u32 s65, s83, 0x5a00000
	v_add_u32_e32 v5, v3, v5
	s_addc_u32 s66, s84, 0
	s_lshl_b64 s[10:11], s[22:23], 19
	v_lshlrev_b32_e32 v4, 3, v10
	v_ashrrev_i32_e32 v11, 6, v5
	v_and_b32_e32 v5, 0xc0, v5
	s_add_u32 s26, s63, s10
	v_and_b32_e32 v4, -16, v4
	v_sub_u32_e32 v3, v3, v5
	s_addc_u32 s27, s64, s11
	s_lshl_b64 s[10:11], s[24:25], 20
	v_add_u32_e32 v4, v11, v4
	v_ashrrev_i16_sdwa v3, v219, sext(v3) dst_sel:DWORD dst_unused:UNUSED_PAD src0_sel:DWORD src1_sel:BYTE_0
	s_add_u32 s56, s65, s10
	v_lshlrev_b32_e32 v6, 5, v10
	v_bfe_i32 v12, v3, 0, 16
	v_lshlrev_b32_e32 v3, 1, v4
	v_lshrrev_b32_e32 v5, 2, v4
	v_and_b32_e32 v7, 3, v11
	s_mov_b32 s10, 0xfffe0
	v_and_b32_e32 v6, 32, v6
	v_and_b32_e32 v3, 24, v3
	v_and_b32_e32 v5, 4, v5
	v_and_or_b32 v7, v4, s10, v7
	v_or3_b32 v3, v7, v5, v3
	v_add_lshl_u32 v5, v6, v12, 1
	v_add_u32_e32 v2, 0x2000, v2
	v_lshl_add_u32 v162, v3, 12, v5
	v_ashrrev_i32_e32 v3, 31, v2
	v_lshrrev_b32_e32 v3, 22, v3
	v_add_u32_e32 v3, v2, v3
	v_ashrrev_i32_e32 v13, 10, v3
	v_mul_i32_i24_e32 v3, 0x400, v13
	v_sub_u32_e32 v2, v2, v3
	v_lshrrev_b32_e32 v3, 4, v2
	v_bitop3_b32 v2, v3, v2, 32 bitop3:0x6c
	v_lshl_add_u32 v130, v4, 11, v5
	v_ashrrev_i32_e32 v4, 31, v2
	v_lshrrev_b32_e32 v4, 26, v4
	v_add_u32_e32 v4, v2, v4
	v_lshlrev_b32_e32 v3, 3, v13
	v_ashrrev_i32_e32 v14, 6, v4
	v_and_b32_e32 v4, 0xc0, v4
	v_and_b32_e32 v3, -16, v3
	v_sub_u32_e32 v2, v2, v4
	s_addc_u32 s57, s66, s11
	v_add_u32_e32 v3, v14, v3
	v_ashrrev_i16_sdwa v2, v219, sext(v2) dst_sel:DWORD dst_unused:UNUSED_PAD src0_sel:DWORD src1_sel:BYTE_0
	s_lshl_b32 s23, s5, 10
	v_lshlrev_b32_e32 v5, 5, v13
	v_bfe_i32 v15, v2, 0, 16
	v_lshlrev_b32_e32 v2, 1, v3
	v_lshrrev_b32_e32 v4, 2, v3
	v_and_b32_e32 v6, 3, v14
	s_add_i32 s25, s23, 0
	v_and_b32_e32 v5, 32, v5
	v_and_b32_e32 v2, 24, v2
	v_and_b32_e32 v4, 4, v4
	v_and_or_b32 v6, v3, s10, v6
	s_add_i32 m0, s25, 0x10000
	s_ashr_i32 s13, s12, 8
	v_or3_b32 v2, v6, v4, v2
	v_add_lshl_u32 v4, v5, v15, 1
	global_load_lds_dwordx4 v162, s[56:57]
	s_add_i32 m0, s25, 0x12000
	v_lshl_add_u32 v134, v2, 12, v4
	s_add_u32 s10, s56, 0x80000
	global_load_lds_dwordx4 v134, s[56:57]
	s_addc_u32 s11, s57, 0
	s_add_i32 m0, s25, 0x14000
	s_add_i32 s67, s25, 0x2000
	global_load_lds_dwordx4 v162, s[10:11]
	s_add_i32 m0, s25, 0x16000
	v_lshl_add_u32 v132, v3, 11, v4
	global_load_lds_dwordx4 v134, s[10:11]
	s_mov_b32 m0, s25
	s_add_u32 s10, s26, 0x40000
	global_load_lds_dwordx4 v130, s[26:27]
	s_mov_b32 m0, s67
	s_addc_u32 s11, s27, 0
	s_add_i32 s68, s25, 0x4000
	global_load_lds_dwordx4 v132, s[26:27]
	s_mov_b32 m0, s68
	s_add_i32 s69, s25, 0x6000
	global_load_lds_dwordx4 v130, s[10:11]
	s_mov_b32 m0, s69
	v_mov_b32_e32 v135, v163
	global_load_lds_dwordx4 v132, s[10:11]
	v_mov_b32_e32 v131, v163
	v_mov_b32_e32 v133, v163
	s_cmp_eq_u32 s13, 1
	v_lshl_add_u64 v[8:9], s[56:57], 0, v[162:163]
	v_lshl_add_u64 v[6:7], s[56:57], 0, v[134:135]
	v_lshl_add_u64 v[2:3], s[26:27], 0, v[130:131]
	s_cselect_b64 s[10:11], -1, 0
	s_cmp_lg_u32 s13, 1
	v_lshl_add_u64 v[4:5], s[26:27], 0, v[132:133]
	s_movk_i32 s31, 0xc1
	s_cbranch_scc1 .LBB0_683
.LBB0_683:
	s_lshl_b32 s5, s5, 5
	s_and_b32 s70, s5, 0x60
	s_add_i32 m0, s25, 0x18000
	v_lshl_add_u64 v[8:9], v[8:9], 0, s[44:45]
	s_lshl_b32 s16, s13, 13
	s_lshl_b32 s5, s70, 7
	s_waitcnt vmcnt(2)
	s_barrier
	global_load_lds_dwordx4 v[8:9], off
	v_lshl_add_u64 v[6:7], v[6:7], 0, s[44:45]
	s_add_i32 m0, s25, 0x1a000
	s_add_i32 s71, s25, 0x8000
	s_add_i32 s72, s25, 0xa000
	global_load_lds_dwordx4 v[6:7], off
	v_lshl_add_u64 v[2:3], v[2:3], 0, s[44:45]
	s_mov_b32 m0, s71
	s_add_u32 s14, s56, 0x80080
	global_load_lds_dwordx4 v[2:3], off
	v_lshl_add_u64 v[2:3], v[4:5], 0, s[44:45]
	s_mov_b32 m0, s72
	s_addc_u32 s15, s57, 0
	global_load_lds_dwordx4 v[2:3], off
	s_add_i32 m0, s25, 0x1c000
	v_lshl_add_u64 v[2:3], s[14:15], 0, v[162:163]
	global_load_lds_dwordx4 v[2:3], off
	v_lshl_add_u64 v[2:3], s[14:15], 0, v[134:135]
	s_add_i32 m0, s25, 0x1e000
	v_lshlrev_b32_e32 v4, 2, v141
	global_load_lds_dwordx4 v[2:3], off
	v_and_b32_e32 v2, 15, v141
	v_lshrrev_b32_e32 v3, 1, v141
	v_lshl_or_b32 v143, s13, 6, v2
	v_and_b32_e32 v145, 24, v3
	v_lshlrev_b32_e32 v3, 1, v145
	v_lshlrev_b32_e32 v147, 2, v143
	v_lshl_or_b32 v2, v2, 6, v3
	v_and_b32_e32 v3, 32, v147
	v_and_b32_e32 v4, 32, v4
	v_bitop3_b32 v3, v2, s16, v3 bitop3:0xde
	v_bitop3_b32 v149, v2, s5, v4 bitop3:0xde
	v_or_b32_e32 v2, 16, v143
	v_lshlrev_b32_e32 v153, 3, v2
	v_lshlrev_b32_e32 v155, 2, v2
	v_or_b32_e32 v2, 32, v143
	v_lshlrev_b32_e32 v176, 3, v2
	v_lshlrev_b32_e32 v177, 2, v2
	v_or_b32_e32 v2, 48, v143
	v_lshlrev_b32_e32 v178, 3, v2
	v_lshlrev_b32_e32 v179, 2, v2
	v_add_u32_e32 v2, 0x80, v143
	v_lshlrev_b32_e32 v180, 3, v2
	v_lshlrev_b32_e32 v181, 2, v2
	v_add_u32_e32 v2, 0x90, v143
	v_lshlrev_b32_e32 v182, 3, v2
	v_lshlrev_b32_e32 v183, 2, v2
	v_add_u32_e32 v2, 0xa0, v143
	v_lshlrev_b32_e32 v184, 3, v2
	v_lshlrev_b32_e32 v185, 2, v2
	v_add_u32_e32 v2, 0xb0, v143
	v_lshlrev_b32_e32 v186, 3, v2
	v_lshlrev_b32_e32 v187, 2, v2
	v_lshlrev_b32_e32 v2, 14, v13
	s_and_b32 s76, s2, 7
	s_ashr_i32 s74, s2, 3
	v_and_b32_e32 v2, 0xffff8000, v2
	s_lshl_b32 s5, s76, 3
	s_and_b32 s13, s74, 7
	v_lshl_add_u32 v2, v14, 11, v2
	v_and_b32_e32 v4, 1, v13
	s_ashr_i32 s73, s2, 31
	s_or_b32 s75, s5, s13
	v_lshl_or_b32 v2, v4, 6, v2
	s_cmpk_lt_u32 s12, 0x100
	v_lshl_add_u32 v136, v15, 1, v2
	v_lshlrev_b32_e32 v2, 14, v10
	s_cselect_b64 s[12:13], -1, 0
	s_add_u32 s77, s8, 0x6b000000
	v_and_b32_e32 v2, 0xffff8000, v2
	s_waitcnt vmcnt(6)
	s_addc_u32 s78, s9, 0
	v_lshl_add_u32 v2, v11, 11, v2
	v_and_b32_e32 v4, 1, v10
	s_add_u32 s79, s8, s4
	v_lshl_or_b32 v2, v4, 6, v2
	s_mul_i32 s76, s76, 3
	v_lshlrev_b32_e32 v151, 3, v143
	s_addc_u32 s80, s9, 0
	v_or_b32_e32 v188, s70, v145
	v_mov_b32_e32 v137, v163
	v_lshl_add_u32 v138, v12, 1, v2
	v_mov_b32_e32 v139, v163
	s_mov_b32 s82, 0
	v_add_u32_e32 v189, 0, v3
	s_mov_b32 s81, 0
	s_barrier
	s_branch .LBB0_686

.LBB0_695:
	s_add_u32 s15, s56, 0x100
	s_addc_u32 s17, s57, 0
	s_add_u32 s26, s26, 0x40080
	v_mov_b32_e32 v2, 0
	s_addc_u32 s27, s27, 0
	s_mov_b32 s60, -2
	v_mov_b32_e32 v3, v2
	v_mov_b32_e32 v4, v2
	v_mov_b32_e32 v5, v2
	v_mov_b32_e32 v6, v2
	v_mov_b32_e32 v7, v2
	v_mov_b32_e32 v8, v2
	v_mov_b32_e32 v9, v2
	v_mov_b32_e32 v10, v2
	v_mov_b32_e32 v11, v2
	v_mov_b32_e32 v12, v2
	v_mov_b32_e32 v13, v2
	v_mov_b32_e32 v14, v2
	v_mov_b32_e32 v15, v2
	v_mov_b32_e32 v16, v2
	v_mov_b32_e32 v17, v2
	v_mov_b32_e32 v18, v2
	v_mov_b32_e32 v19, v2
	v_mov_b32_e32 v20, v2
	v_mov_b32_e32 v21, v2
	v_mov_b32_e32 v22, v2
	v_mov_b32_e32 v23, v2
	v_mov_b32_e32 v24, v2
	v_mov_b32_e32 v25, v2
	v_mov_b32_e32 v26, v2
	v_mov_b32_e32 v27, v2
	v_mov_b32_e32 v28, v2
	v_mov_b32_e32 v29, v2
	v_mov_b32_e32 v30, v2
	v_mov_b32_e32 v31, v2
	v_mov_b32_e32 v32, v2
	v_mov_b32_e32 v33, v2
	v_mov_b32_e32 v66, v2
	v_mov_b32_e32 v67, v2
	v_mov_b32_e32 v68, v2
	v_mov_b32_e32 v69, v2
	v_mov_b32_e32 v70, v2
	v_mov_b32_e32 v71, v2
	v_mov_b32_e32 v72, v2
	v_mov_b32_e32 v73, v2
	v_mov_b32_e32 v74, v2
	v_mov_b32_e32 v75, v2
	v_mov_b32_e32 v76, v2
	v_mov_b32_e32 v77, v2
	v_mov_b32_e32 v78, v2
	v_mov_b32_e32 v79, v2
	v_mov_b32_e32 v80, v2
	v_mov_b32_e32 v81, v2
	v_mov_b32_e32 v82, v2
	v_mov_b32_e32 v83, v2
	v_mov_b32_e32 v84, v2
	v_mov_b32_e32 v85, v2
	v_mov_b32_e32 v86, v2
	v_mov_b32_e32 v87, v2
	v_mov_b32_e32 v88, v2
	v_mov_b32_e32 v89, v2
	v_mov_b32_e32 v90, v2
	v_mov_b32_e32 v91, v2
	v_mov_b32_e32 v92, v2
	v_mov_b32_e32 v93, v2
	v_mov_b32_e32 v94, v2
	v_mov_b32_e32 v95, v2
	v_mov_b32_e32 v96, v2
	v_mov_b32_e32 v97, v2
	v_mov_b32_e32 v34, v2
	v_mov_b32_e32 v35, v2
	v_mov_b32_e32 v36, v2
	v_mov_b32_e32 v37, v2
	v_mov_b32_e32 v38, v2
	v_mov_b32_e32 v39, v2
	v_mov_b32_e32 v40, v2
	v_mov_b32_e32 v41, v2
	v_mov_b32_e32 v42, v2
	v_mov_b32_e32 v43, v2
	v_mov_b32_e32 v44, v2
	v_mov_b32_e32 v45, v2
	v_mov_b32_e32 v46, v2
	v_mov_b32_e32 v47, v2
	v_mov_b32_e32 v48, v2
	v_mov_b32_e32 v49, v2
	v_mov_b32_e32 v50, v2
	v_mov_b32_e32 v51, v2
	v_mov_b32_e32 v52, v2
	v_mov_b32_e32 v53, v2
	v_mov_b32_e32 v54, v2
	v_mov_b32_e32 v55, v2
	v_mov_b32_e32 v56, v2
	v_mov_b32_e32 v57, v2
	v_mov_b32_e32 v58, v2
	v_mov_b32_e32 v59, v2
	v_mov_b32_e32 v60, v2
	v_mov_b32_e32 v61, v2
	v_mov_b32_e32 v62, v2
	v_mov_b32_e32 v63, v2
	v_mov_b32_e32 v64, v2
	v_mov_b32_e32 v65, v2
	v_mov_b32_e32 v98, v2
	v_mov_b32_e32 v99, v2
	v_mov_b32_e32 v100, v2
	v_mov_b32_e32 v101, v2
	v_mov_b32_e32 v102, v2
	v_mov_b32_e32 v103, v2
	v_mov_b32_e32 v104, v2
	v_mov_b32_e32 v105, v2
	v_mov_b32_e32 v106, v2
	v_mov_b32_e32 v107, v2
	v_mov_b32_e32 v108, v2
	v_mov_b32_e32 v109, v2
	v_mov_b32_e32 v110, v2
	v_mov_b32_e32 v111, v2
	v_mov_b32_e32 v112, v2
	v_mov_b32_e32 v113, v2
	v_mov_b32_e32 v114, v2
	v_mov_b32_e32 v115, v2
	v_mov_b32_e32 v116, v2
	v_mov_b32_e32 v117, v2
	v_mov_b32_e32 v118, v2
	v_mov_b32_e32 v119, v2
	v_mov_b32_e32 v120, v2
	v_mov_b32_e32 v121, v2
	v_mov_b32_e32 v122, v2
	v_mov_b32_e32 v123, v2
	v_mov_b32_e32 v124, v2
	v_mov_b32_e32 v125, v2
	v_mov_b32_e32 v126, v2
	v_mov_b32_e32 v127, v2
	v_mov_b32_e32 v128, v2
	v_mov_b32_e32 v129, v2
	v_readfirstlane_b32 s100, v0
	s_nop 3
	s_bitcmp1_b32 s100, 8
	s_cbranch_scc0 .Lrb_skip3
	s_barrier
.Lrb_skip3:
.LBB0_696:
	s_add_u32 s36, s26, 0xfffc0080
	s_addc_u32 s37, s27, -1
	s_add_i32 s38, 0, 0x10000
	s_cmp_eq_u32 s60, 12
	s_cselect_b32 s59, s19, s37
	s_cselect_b32 s58, s18, s36
	v_add_u32_e32 v140, s38, v149
	s_cselect_b32 s57, s21, s17
	s_cselect_b32 s56, s20, s15
	s_add_i32 s39, 0, 0x14000
	ds_read_b128 v[156:159], v140
	ds_read_b128 v[172:175], v140 offset:1024
	ds_read_b128 v[190:193], v140 offset:2048
	ds_read_b128 v[194:197], v140 offset:3072
	v_add_u32_e32 v140, s39, v149
	ds_read_b128 v[198:201], v140
	ds_read_b128 v[202:205], v140 offset:1024
	ds_read_b128 v[206:209], v140 offset:2048
	ds_read_b128 v[210:213], v140 offset:3072
	v_lshl_add_u64 v[160:161], s[26:27], 0, v[138:139]
	s_add_i32 m0, s25, 0xc000
	ds_read_b128 v[214:217], v189
	ds_read_b128 v[222:225], v189 offset:1024
	ds_read_b128 v[226:229], v189 offset:2048
	ds_read_b128 v[230:233], v189 offset:3072
	ds_read_b128 v[234:237], v189 offset:4096
	ds_read_b128 v[238:241], v189 offset:5120
	ds_read_b128 v[242:245], v189 offset:6144
	ds_read_b128 v[246:249], v189 offset:7168
	global_load_lds_dwordx4 v[160:161], off
	v_lshl_add_u64 v[160:161], s[26:27], 0, v[136:137]
	s_add_i32 m0, s25, 0xe000
	s_nop 0
	global_load_lds_dwordx4 v[160:161], off
	s_waitcnt vmcnt(8)
	s_waitcnt lgkmcnt(0)
	s_barrier
	v_mfma_i32_16x16x64_i8 v[126:129], v[156:159], v[214:217], v[126:129]
	v_mfma_i32_16x16x64_i8 v[122:125], v[190:193], v[214:217], v[122:125]
	v_mfma_i32_16x16x64_i8 v[118:121], v[156:159], v[226:229], v[118:121]
	v_mfma_i32_16x16x64_i8 v[114:117], v[190:193], v[226:229], v[114:117]
	v_mfma_i32_16x16x64_i8 v[110:113], v[156:159], v[234:237], v[110:113]
	v_mfma_i32_16x16x64_i8 v[106:109], v[190:193], v[234:237], v[106:109]
	v_mfma_i32_16x16x64_i8 v[102:105], v[156:159], v[242:245], v[102:105]
	v_mfma_i32_16x16x64_i8 v[98:101], v[190:193], v[242:245], v[98:101]
	v_mfma_i32_16x16x64_i8 v[126:129], v[172:175], v[222:225], v[126:129]
	v_mfma_i32_16x16x64_i8 v[122:125], v[194:197], v[222:225], v[122:125]
	v_mfma_i32_16x16x64_i8 v[118:121], v[172:175], v[230:233], v[118:121]
	v_mfma_i32_16x16x64_i8 v[114:117], v[194:197], v[230:233], v[114:117]
	v_mfma_i32_16x16x64_i8 v[110:113], v[172:175], v[238:241], v[110:113]
	v_mfma_i32_16x16x64_i8 v[106:109], v[194:197], v[238:241], v[106:109]
	v_mfma_i32_16x16x64_i8 v[102:105], v[172:175], v[246:249], v[102:105]
	v_mfma_i32_16x16x64_i8 v[98:101], v[194:197], v[246:249], v[98:101]
	v_mfma_i32_16x16x64_i8 v[62:65], v[198:201], v[214:217], v[62:65]
	v_mfma_i32_16x16x64_i8 v[58:61], v[206:209], v[214:217], v[58:61]
	v_mfma_i32_16x16x64_i8 v[54:57], v[198:201], v[226:229], v[54:57]
	v_mfma_i32_16x16x64_i8 v[50:53], v[206:209], v[226:229], v[50:53]
	v_mfma_i32_16x16x64_i8 v[46:49], v[198:201], v[234:237], v[46:49]
	v_mfma_i32_16x16x64_i8 v[42:45], v[206:209], v[234:237], v[42:45]
	v_mfma_i32_16x16x64_i8 v[38:41], v[198:201], v[242:245], v[38:41]
	v_mfma_i32_16x16x64_i8 v[34:37], v[206:209], v[242:245], v[34:37]
	v_mfma_i32_16x16x64_i8 v[62:65], v[202:205], v[222:225], v[62:65]
	v_mfma_i32_16x16x64_i8 v[58:61], v[210:213], v[222:225], v[58:61]
	v_mfma_i32_16x16x64_i8 v[54:57], v[202:205], v[230:233], v[54:57]
	v_mfma_i32_16x16x64_i8 v[50:53], v[210:213], v[230:233], v[50:53]
	v_mfma_i32_16x16x64_i8 v[46:49], v[202:205], v[238:241], v[46:49]
	v_mfma_i32_16x16x64_i8 v[42:45], v[210:213], v[238:241], v[42:45]
	v_mfma_i32_16x16x64_i8 v[38:41], v[202:205], v[246:249], v[38:41]
	v_mfma_i32_16x16x64_i8 v[34:37], v[210:213], v[246:249], v[34:37]
	s_barrier
	s_add_i32 s36, s38, s23
	v_lshl_add_u64 v[160:161], s[56:57], 0, v[162:163]
	s_mov_b32 m0, s36
	ds_read_b128 v[214:217], v189 offset:16384
	ds_read_b128 v[222:225], v189 offset:17408
	ds_read_b128 v[226:229], v189 offset:18432
	ds_read_b128 v[230:233], v189 offset:19456
	ds_read_b128 v[234:237], v189 offset:20480
	ds_read_b128 v[238:241], v189 offset:21504
	ds_read_b128 v[242:245], v189 offset:22528
	ds_read_b128 v[246:249], v189 offset:23552
	global_load_lds_dwordx4 v[160:161], off
	s_add_i32 m0, s36, 0x2000
	s_add_u32 s36, s56, 0x80000
	v_lshl_add_u64 v[250:251], s[56:57], 0, v[134:135]
	s_addc_u32 s37, s57, 0
	s_add_i32 s38, s39, s23
	global_load_lds_dwordx4 v[250:251], off
	v_lshl_add_u64 v[252:253], s[36:37], 0, v[162:163]
	s_mov_b32 m0, s38
	v_lshl_add_u64 v[168:169], s[58:59], 0, v[132:133]
	global_load_lds_dwordx4 v[252:253], off
	v_lshl_add_u64 v[252:253], s[36:37], 0, v[134:135]
	s_add_i32 m0, s38, 0x2000
	s_nop 0
	global_load_lds_dwordx4 v[252:253], off
	v_lshl_add_u64 v[252:253], s[58:59], 0, v[130:131]
	s_mov_b32 m0, s25
	s_nop 0
	global_load_lds_dwordx4 v[252:253], off
	s_mov_b32 m0, s67
	s_nop 0
	global_load_lds_dwordx4 v[168:169], off
	s_waitcnt vmcnt(8)
	s_waitcnt lgkmcnt(0)
	s_barrier
	v_mfma_i32_16x16x64_i8 v[94:97], v[156:159], v[214:217], v[94:97]
	v_mfma_i32_16x16x64_i8 v[90:93], v[190:193], v[214:217], v[90:93]
	v_mfma_i32_16x16x64_i8 v[86:89], v[156:159], v[226:229], v[86:89]
	v_mfma_i32_16x16x64_i8 v[82:85], v[190:193], v[226:229], v[82:85]
	v_mfma_i32_16x16x64_i8 v[78:81], v[156:159], v[234:237], v[78:81]
	v_mfma_i32_16x16x64_i8 v[74:77], v[190:193], v[234:237], v[74:77]
	v_mfma_i32_16x16x64_i8 v[70:73], v[156:159], v[242:245], v[70:73]
	v_mfma_i32_16x16x64_i8 v[66:69], v[190:193], v[242:245], v[66:69]
	v_mfma_i32_16x16x64_i8 v[94:97], v[172:175], v[222:225], v[94:97]
	v_mfma_i32_16x16x64_i8 v[90:93], v[194:197], v[222:225], v[90:93]
	v_mfma_i32_16x16x64_i8 v[86:89], v[172:175], v[230:233], v[86:89]
	v_mfma_i32_16x16x64_i8 v[82:85], v[194:197], v[230:233], v[82:85]
	v_mfma_i32_16x16x64_i8 v[78:81], v[172:175], v[238:241], v[78:81]
	v_mfma_i32_16x16x64_i8 v[74:77], v[194:197], v[238:241], v[74:77]
	v_mfma_i32_16x16x64_i8 v[70:73], v[172:175], v[246:249], v[70:73]
	v_mfma_i32_16x16x64_i8 v[66:69], v[194:197], v[246:249], v[66:69]
	v_mfma_i32_16x16x64_i8 v[30:33], v[198:201], v[214:217], v[30:33]
	v_mfma_i32_16x16x64_i8 v[26:29], v[206:209], v[214:217], v[26:29]
	v_mfma_i32_16x16x64_i8 v[22:25], v[198:201], v[226:229], v[22:25]
	v_mfma_i32_16x16x64_i8 v[18:21], v[206:209], v[226:229], v[18:21]
	v_mfma_i32_16x16x64_i8 v[14:17], v[198:201], v[234:237], v[14:17]
	v_mfma_i32_16x16x64_i8 v[10:13], v[206:209], v[234:237], v[10:13]
	v_mfma_i32_16x16x64_i8 v[6:9], v[198:201], v[242:245], v[6:9]
	v_mfma_i32_16x16x64_i8 v[2:5], v[206:209], v[242:245], v[2:5]
	v_mfma_i32_16x16x64_i8 v[30:33], v[202:205], v[222:225], v[30:33]
	v_mfma_i32_16x16x64_i8 v[26:29], v[210:213], v[222:225], v[26:29]
	v_mfma_i32_16x16x64_i8 v[22:25], v[202:205], v[230:233], v[22:25]
	v_mfma_i32_16x16x64_i8 v[18:21], v[210:213], v[230:233], v[18:21]
	v_mfma_i32_16x16x64_i8 v[14:17], v[202:205], v[238:241], v[14:17]
	v_mfma_i32_16x16x64_i8 v[10:13], v[210:213], v[238:241], v[10:13]
	v_mfma_i32_16x16x64_i8 v[6:9], v[202:205], v[246:249], v[6:9]
	v_mfma_i32_16x16x64_i8 v[2:5], v[210:213], v[246:249], v[2:5]
	s_barrier
	s_add_i32 s38, 0, 0x18000
	v_add_u32_e32 v140, s38, v149
	s_add_i32 s39, 0, 0x1c000
	ds_read_b128 v[156:159], v140
	ds_read_b128 v[172:175], v140 offset:1024
	ds_read_b128 v[190:193], v140 offset:2048
	ds_read_b128 v[194:197], v140 offset:3072
	v_add_u32_e32 v140, s39, v149
	ds_read_b128 v[198:201], v140
	ds_read_b128 v[202:205], v140 offset:1024
	ds_read_b128 v[206:209], v140 offset:2048
	ds_read_b128 v[210:213], v140 offset:3072
	s_add_u32 s36, s58, 0x40000
	s_addc_u32 s37, s59, 0
	s_mov_b32 m0, s68
	v_lshl_add_u64 v[170:171], s[36:37], 0, v[130:131]
	ds_read_b128 v[214:217], v189 offset:32768
	ds_read_b128 v[222:225], v189 offset:33792
	ds_read_b128 v[226:229], v189 offset:34816
	ds_read_b128 v[230:233], v189 offset:35840
	ds_read_b128 v[234:237], v189 offset:36864
	ds_read_b128 v[238:241], v189 offset:37888
	ds_read_b128 v[242:245], v189 offset:38912
	ds_read_b128 v[246:249], v189 offset:39936
	global_load_lds_dwordx4 v[170:171], off
	v_lshl_add_u64 v[170:171], s[36:37], 0, v[132:133]
	s_mov_b32 m0, s69
	s_nop 0
	global_load_lds_dwordx4 v[170:171], off
	s_waitcnt vmcnt(8)
	s_waitcnt lgkmcnt(0)
	s_barrier
	v_mfma_i32_16x16x64_i8 v[126:129], v[156:159], v[214:217], v[126:129]
	v_mfma_i32_16x16x64_i8 v[122:125], v[190:193], v[214:217], v[122:125]
	v_mfma_i32_16x16x64_i8 v[118:121], v[156:159], v[226:229], v[118:121]
	v_mfma_i32_16x16x64_i8 v[114:117], v[190:193], v[226:229], v[114:117]
	v_mfma_i32_16x16x64_i8 v[110:113], v[156:159], v[234:237], v[110:113]
	v_mfma_i32_16x16x64_i8 v[106:109], v[190:193], v[234:237], v[106:109]
	v_mfma_i32_16x16x64_i8 v[102:105], v[156:159], v[242:245], v[102:105]
	v_mfma_i32_16x16x64_i8 v[98:101], v[190:193], v[242:245], v[98:101]
	v_mfma_i32_16x16x64_i8 v[126:129], v[172:175], v[222:225], v[126:129]
	v_mfma_i32_16x16x64_i8 v[122:125], v[194:197], v[222:225], v[122:125]
	v_mfma_i32_16x16x64_i8 v[118:121], v[172:175], v[230:233], v[118:121]
	v_mfma_i32_16x16x64_i8 v[114:117], v[194:197], v[230:233], v[114:117]
	v_mfma_i32_16x16x64_i8 v[110:113], v[172:175], v[238:241], v[110:113]
	v_mfma_i32_16x16x64_i8 v[106:109], v[194:197], v[238:241], v[106:109]
	v_mfma_i32_16x16x64_i8 v[102:105], v[172:175], v[246:249], v[102:105]
	v_mfma_i32_16x16x64_i8 v[98:101], v[194:197], v[246:249], v[98:101]
	v_mfma_i32_16x16x64_i8 v[62:65], v[198:201], v[214:217], v[62:65]
	v_mfma_i32_16x16x64_i8 v[58:61], v[206:209], v[214:217], v[58:61]
	v_mfma_i32_16x16x64_i8 v[54:57], v[198:201], v[226:229], v[54:57]
	v_mfma_i32_16x16x64_i8 v[50:53], v[206:209], v[226:229], v[50:53]
	v_mfma_i32_16x16x64_i8 v[46:49], v[198:201], v[234:237], v[46:49]
	v_mfma_i32_16x16x64_i8 v[42:45], v[206:209], v[234:237], v[42:45]
	v_mfma_i32_16x16x64_i8 v[38:41], v[198:201], v[242:245], v[38:41]
	v_mfma_i32_16x16x64_i8 v[34:37], v[206:209], v[242:245], v[34:37]
	v_mfma_i32_16x16x64_i8 v[62:65], v[202:205], v[222:225], v[62:65]
	v_mfma_i32_16x16x64_i8 v[58:61], v[210:213], v[222:225], v[58:61]
	v_mfma_i32_16x16x64_i8 v[54:57], v[202:205], v[230:233], v[54:57]
	v_mfma_i32_16x16x64_i8 v[50:53], v[210:213], v[230:233], v[50:53]
	v_mfma_i32_16x16x64_i8 v[46:49], v[202:205], v[238:241], v[46:49]
	v_mfma_i32_16x16x64_i8 v[42:45], v[210:213], v[238:241], v[42:45]
	v_mfma_i32_16x16x64_i8 v[38:41], v[202:205], v[246:249], v[38:41]
	v_mfma_i32_16x16x64_i8 v[34:37], v[210:213], v[246:249], v[34:37]
	s_barrier
	s_add_i32 s36, s38, s23
	v_lshl_add_u64 v[160:161], v[160:161], 0, s[44:45]
	s_mov_b32 m0, s36
	ds_read_b128 v[214:217], v189 offset:49152
	ds_read_b128 v[222:225], v189 offset:50176
	ds_read_b128 v[226:229], v189 offset:51200
	ds_read_b128 v[230:233], v189 offset:52224
	ds_read_b128 v[234:237], v189 offset:53248
	ds_read_b128 v[238:241], v189 offset:54272
	ds_read_b128 v[242:245], v189 offset:55296
	ds_read_b128 v[246:249], v189 offset:56320
	global_load_lds_dwordx4 v[160:161], off
	s_add_i32 m0, s36, 0x2000
	s_add_u32 s36, s56, 0x80080
	v_lshl_add_u64 v[160:161], v[250:251], 0, s[44:45]
	s_addc_u32 s37, s57, 0
	s_add_i32 s38, s39, s23
	global_load_lds_dwordx4 v[160:161], off
	v_lshl_add_u64 v[160:161], s[36:37], 0, v[162:163]
	s_mov_b32 m0, s38
	s_nop 0
	global_load_lds_dwordx4 v[160:161], off
	v_lshl_add_u64 v[160:161], s[36:37], 0, v[134:135]
	s_add_i32 m0, s38, 0x2000
	s_nop 0
	global_load_lds_dwordx4 v[160:161], off
	v_lshl_add_u64 v[160:161], v[252:253], 0, s[44:45]
	s_mov_b32 m0, s71
	s_nop 0
	global_load_lds_dwordx4 v[160:161], off
	v_lshl_add_u64 v[160:161], v[168:169], 0, s[44:45]
	s_mov_b32 m0, s72
	s_nop 0
	global_load_lds_dwordx4 v[160:161], off
	s_waitcnt vmcnt(8)
	s_waitcnt lgkmcnt(0)
	s_barrier
	v_mfma_i32_16x16x64_i8 v[94:97], v[156:159], v[214:217], v[94:97]
	v_mfma_i32_16x16x64_i8 v[90:93], v[190:193], v[214:217], v[90:93]
	v_mfma_i32_16x16x64_i8 v[86:89], v[156:159], v[226:229], v[86:89]
	v_mfma_i32_16x16x64_i8 v[82:85], v[190:193], v[226:229], v[82:85]
	v_mfma_i32_16x16x64_i8 v[78:81], v[156:159], v[234:237], v[78:81]
	v_mfma_i32_16x16x64_i8 v[74:77], v[190:193], v[234:237], v[74:77]
	v_mfma_i32_16x16x64_i8 v[70:73], v[156:159], v[242:245], v[70:73]
	v_mfma_i32_16x16x64_i8 v[66:69], v[190:193], v[242:245], v[66:69]
	v_mfma_i32_16x16x64_i8 v[94:97], v[172:175], v[222:225], v[94:97]
	v_mfma_i32_16x16x64_i8 v[90:93], v[194:197], v[222:225], v[90:93]
	v_mfma_i32_16x16x64_i8 v[86:89], v[172:175], v[230:233], v[86:89]
	v_mfma_i32_16x16x64_i8 v[82:85], v[194:197], v[230:233], v[82:85]
	v_mfma_i32_16x16x64_i8 v[78:81], v[172:175], v[238:241], v[78:81]
	v_mfma_i32_16x16x64_i8 v[74:77], v[194:197], v[238:241], v[74:77]
	v_mfma_i32_16x16x64_i8 v[70:73], v[172:175], v[246:249], v[70:73]
	v_mfma_i32_16x16x64_i8 v[66:69], v[194:197], v[246:249], v[66:69]
	v_mfma_i32_16x16x64_i8 v[30:33], v[198:201], v[214:217], v[30:33]
	v_mfma_i32_16x16x64_i8 v[26:29], v[206:209], v[214:217], v[26:29]
	v_mfma_i32_16x16x64_i8 v[22:25], v[198:201], v[226:229], v[22:25]
	v_mfma_i32_16x16x64_i8 v[18:21], v[206:209], v[226:229], v[18:21]
	v_mfma_i32_16x16x64_i8 v[14:17], v[198:201], v[234:237], v[14:17]
	v_mfma_i32_16x16x64_i8 v[10:13], v[206:209], v[234:237], v[10:13]
	v_mfma_i32_16x16x64_i8 v[6:9], v[198:201], v[242:245], v[6:9]
	v_mfma_i32_16x16x64_i8 v[2:5], v[206:209], v[242:245], v[2:5]
	v_mfma_i32_16x16x64_i8 v[30:33], v[202:205], v[222:225], v[30:33]
	v_mfma_i32_16x16x64_i8 v[26:29], v[210:213], v[222:225], v[26:29]
	v_mfma_i32_16x16x64_i8 v[22:25], v[202:205], v[230:233], v[22:25]
	v_mfma_i32_16x16x64_i8 v[18:21], v[210:213], v[230:233], v[18:21]
	v_mfma_i32_16x16x64_i8 v[14:17], v[202:205], v[238:241], v[14:17]
	v_mfma_i32_16x16x64_i8 v[10:13], v[210:213], v[238:241], v[10:13]
	v_mfma_i32_16x16x64_i8 v[6:9], v[202:205], v[246:249], v[6:9]
	v_mfma_i32_16x16x64_i8 v[2:5], v[210:213], v[246:249], v[2:5]
	s_barrier
	s_add_i32 s60, s60, 2
	s_add_u32 s15, s15, 0x100
	s_addc_u32 s17, s17, 0
	s_add_u32 s26, s26, 0x100
	s_addc_u32 s27, s27, 0
	s_cmp_gt_u32 s60, 13
	s_cbranch_scc0 .LBB0_696
	s_and_b64 vcc, exec, s[12:13]
	s_cbranch_vccz .LBB0_699
	s_barrier

.LBB0_702:
	s_andn2_b64 vcc, exec, s[10:11]
	s_cbranch_vccnz .LBB0_684
	s_branch .LBB0_684

.LBB0_948:
	s_and_b64 vcc, exec, s[4:5]
	s_cbranch_vccnz .LBB0_1105
	v_ashrrev_i32_e32 v3, 31, v10
	v_lshrrev_b32_e32 v3, 26, v3
	v_add_u32_e32 v3, v10, v3
	v_ashrrev_i32_e32 v11, 6, v3
	v_bfe_i32 v3, v10, 27, 1
	v_lshlrev_b32_e32 v2, 4, v10
	v_lshrrev_b32_e32 v3, 22, v3
	v_add_u32_e32 v3, v2, v3
	v_and_b32_e32 v3, 0xfffffc00, v3
	v_sub_u32_e32 v3, v2, v3
	v_lshrrev_b32_e32 v4, 4, v3
	v_bitop3_b32 v3, v4, v3, 32 bitop3:0x6c
	v_ashrrev_i32_e32 v5, 31, v3
	v_lshrrev_b32_e32 v5, 26, v5
	v_add_u32_e32 v5, v3, v5
	v_lshlrev_b32_e32 v4, 3, v11
	v_ashrrev_i32_e32 v12, 6, v5
	v_and_b32_e32 v5, 0xc0, v5
	v_and_b32_e32 v4, -16, v4
	v_sub_u32_e32 v3, v3, v5
	v_add_u32_e32 v4, v12, v4
	v_ashrrev_i16_sdwa v3, v219, sext(v3) dst_sel:DWORD dst_unused:UNUSED_PAD src0_sel:DWORD src1_sel:BYTE_0
	v_lshlrev_b32_e32 v6, 5, v11
	v_bfe_i32 v13, v3, 0, 16
	v_lshlrev_b32_e32 v3, 1, v4
	v_lshrrev_b32_e32 v5, 2, v4
	v_and_b32_e32 v7, 3, v12
	s_mov_b32 s5, 0xfffe0
	v_and_b32_e32 v6, 32, v6
	v_and_b32_e32 v3, 24, v3
	v_and_b32_e32 v5, 4, v5
	v_and_or_b32 v7, v4, s5, v7
	v_or3_b32 v3, v7, v5, v3
	v_add_lshl_u32 v5, v6, v13, 1
	v_add_u32_e32 v2, 0x2000, v2
	v_lshl_add_u32 v162, v3, 12, v5
	v_ashrrev_i32_e32 v3, 31, v2
	v_lshrrev_b32_e32 v3, 22, v3
	v_add_u32_e32 v3, v2, v3
	v_ashrrev_i32_e32 v14, 10, v3
	v_mul_i32_i24_e32 v3, 0x400, v14
	v_sub_u32_e32 v2, v2, v3
	v_lshrrev_b32_e32 v3, 4, v2
	v_bitop3_b32 v2, v3, v2, 32 bitop3:0x6c
	v_lshl_add_u32 v130, v4, 12, v5
	v_ashrrev_i32_e32 v4, 31, v2
	v_lshrrev_b32_e32 v4, 26, v4
	v_lshlrev_b32_e32 v3, 3, v14
	v_add_u32_e32 v4, v2, v4
	v_and_b32_e32 v3, -16, v3
	v_ashrrev_i32_e32 v15, 6, v4
	v_add_u32_e32 v3, v15, v3
	v_and_b32_e32 v4, 0xc0, v4
	v_and_b32_e32 v6, 3, v15
	v_sub_u32_e32 v2, v2, v4
	v_and_or_b32 v6, v3, s5, v6
	s_ashr_i32 s5, s14, 6
	v_ashrrev_i16_sdwa v2, v219, sext(v2) dst_sel:DWORD dst_unused:UNUSED_PAD src0_sel:DWORD src1_sel:BYTE_0
	s_lshl_b32 s60, s5, 10
	v_lshlrev_b32_e32 v5, 5, v14
	v_bfe_i32 v16, v2, 0, 16
	v_lshlrev_b32_e32 v2, 1, v3
	v_lshrrev_b32_e32 v4, 2, v3
	s_add_i32 s61, s60, 0
	v_and_b32_e32 v5, 32, v5
	v_and_b32_e32 v2, 24, v2
	v_and_b32_e32 v4, 4, v4
	s_add_i32 m0, s61, 0x10000
	s_ashr_i32 s4, s14, 8
	v_or3_b32 v2, v6, v4, v2
	v_add_lshl_u32 v4, v5, v16, 1
	global_load_lds_dwordx4 v162, s[24:25]
	s_add_i32 m0, s61, 0x12000
	v_lshl_add_u32 v134, v2, 12, v4
	s_add_u32 s10, s24, 0x80000
	global_load_lds_dwordx4 v134, s[24:25]
	s_addc_u32 s11, s25, 0
	s_add_i32 m0, s61, 0x14000
	s_add_i32 s62, s61, 0x2000
	global_load_lds_dwordx4 v162, s[10:11]
	s_add_i32 m0, s61, 0x16000
	v_lshl_add_u32 v132, v3, 12, v4
	global_load_lds_dwordx4 v134, s[10:11]
	s_mov_b32 m0, s61
	s_add_u32 s10, s22, 0x80000
	global_load_lds_dwordx4 v130, s[22:23]
	s_mov_b32 m0, s62
	s_addc_u32 s11, s23, 0
	s_add_i32 s63, s61, 0x4000
	global_load_lds_dwordx4 v132, s[22:23]
	s_mov_b32 m0, s63
	s_add_i32 s64, s61, 0x6000
	global_load_lds_dwordx4 v130, s[10:11]
	s_mov_b32 m0, s64
	v_mov_b32_e32 v135, v163
	global_load_lds_dwordx4 v132, s[10:11]
	v_mov_b32_e32 v131, v163
	v_mov_b32_e32 v133, v163
	s_cmp_eq_u32 s4, 1
	v_lshl_add_u64 v[8:9], s[24:25], 0, v[162:163]
	v_lshl_add_u64 v[6:7], s[24:25], 0, v[134:135]
	v_lshl_add_u64 v[2:3], s[22:23], 0, v[130:131]
	s_cselect_b64 s[10:11], -1, 0
	s_cmp_lg_u32 s4, 1
	v_lshl_add_u64 v[4:5], s[22:23], 0, v[132:133]
	s_cbranch_scc1 .LBB0_951
.LBB0_951:
	v_lshrrev_b32_e32 v18, 1, v10
	v_and_b32_e32 v18, 24, v18
	s_add_u32 s12, s16, 0x50000000
	v_and_b32_e32 v17, 15, v10
	v_lshlrev_b32_e32 v19, 1, v18
	v_lshlrev_b32_e32 v10, 2, v10
	s_addc_u32 s13, s17, 0
	v_lshl_or_b32 v210, s4, 6, v17
	v_lshl_or_b32 v17, v17, 6, v19
	s_lshl_b32 s4, s4, 13
	v_and_b32_e32 v10, 32, v10
	v_bitop3_b32 v19, v17, s4, v10 bitop3:0xde
	s_lshl_b32 s4, s5, 5
	s_and_b32 s7, s4, 0x60
	s_add_i32 m0, s61, 0x18000
	v_lshl_add_u64 v[8:9], v[8:9], 0, s[44:45]
	s_lshl_b32 s4, s7, 7
	s_waitcnt vmcnt(2)
	s_barrier
	global_load_lds_dwordx4 v[8:9], off
	v_lshl_add_u64 v[6:7], v[6:7], 0, s[44:45]
	s_add_i32 m0, s61, 0x1a000
	s_add_i32 s65, s61, 0x8000
	s_add_i32 s66, s61, 0xa000
	v_bitop3_b32 v211, v17, s4, v10 bitop3:0xde
	global_load_lds_dwordx4 v[6:7], off
	v_lshl_add_u64 v[2:3], v[2:3], 0, s[44:45]
	s_mov_b32 m0, s65
	s_add_u32 s4, s24, 0x80080
	global_load_lds_dwordx4 v[2:3], off
	v_lshl_add_u64 v[2:3], v[4:5], 0, s[44:45]
	s_mov_b32 m0, s66
	s_addc_u32 s5, s25, 0
	global_load_lds_dwordx4 v[2:3], off
	s_add_i32 m0, s61, 0x1c000
	v_lshl_add_u64 v[2:3], s[4:5], 0, v[162:163]
	global_load_lds_dwordx4 v[2:3], off
	v_lshl_add_u64 v[2:3], s[4:5], 0, v[134:135]
	s_add_i32 m0, s61, 0x1e000
	s_and_b32 s68, s2, 7
	global_load_lds_dwordx4 v[2:3], off
	v_lshlrev_b32_e32 v2, 15, v14
	v_and_b32_e32 v2, 0xffff0000, v2
	v_lshl_add_u32 v2, v15, 12, v2
	v_and_b32_e32 v3, 1, v14
	v_lshl_or_b32 v2, v3, 6, v2
	s_ashr_i32 s69, s2, 3
	v_lshl_add_u32 v136, v16, 1, v2
	v_lshlrev_b32_e32 v2, 15, v11
	s_lshl_b32 s4, s68, 3
	s_and_b32 s5, s69, 7
	v_and_b32_e32 v2, 0xffff0000, v2
	s_ashr_i32 s67, s2, 31
	s_or_b32 s29, s4, s5
	v_lshl_add_u32 v2, v12, 12, v2
	v_and_b32_e32 v3, 1, v11
	s_waitcnt vmcnt(6)
	s_cmpk_lt_u32 s14, 0x100
	v_lshl_or_b32 v2, v3, 6, v2
	s_cselect_b64 s[14:15], -1, 0
	s_add_u32 s16, s16, 0x32002000
	v_lshl_add_u32 v138, v13, 1, v2
	v_mov_b32_e32 v2, 0
	s_addc_u32 s17, s17, 0
	v_or_b32_e32 v212, s7, v18
	v_mov_b32_e32 v137, v163
	v_mov_b32_e32 v139, v163
	s_mov_b32 s9, 16
	s_mov_b32 s7, 0
	v_mov_b32_e32 v215, 1
	v_add_u32_e32 v213, 0, v19
	s_mov_b32 s71, 0
	v_mov_b32_e32 v3, v2
	v_mov_b32_e32 v4, v2
	v_mov_b32_e32 v5, v2
	v_mov_b32_e32 v6, v2
	v_mov_b32_e32 v7, v2
	v_mov_b32_e32 v8, v2
	v_mov_b32_e32 v9, v2
	v_mov_b32_e32 v10, v2
	v_mov_b32_e32 v11, v2
	v_mov_b32_e32 v12, v2
	v_mov_b32_e32 v13, v2
	v_mov_b32_e32 v14, v2
	v_mov_b32_e32 v15, v2
	v_mov_b32_e32 v16, v2
	v_mov_b32_e32 v17, v2
	v_mov_b32_e32 v18, v2
	v_mov_b32_e32 v19, v2
	v_mov_b32_e32 v20, v2
	v_mov_b32_e32 v21, v2
	v_mov_b32_e32 v22, v2
	v_mov_b32_e32 v23, v2
	v_mov_b32_e32 v24, v2
	v_mov_b32_e32 v25, v2
	v_mov_b32_e32 v26, v2
	v_mov_b32_e32 v27, v2
	v_mov_b32_e32 v28, v2
	v_mov_b32_e32 v29, v2
	v_mov_b32_e32 v30, v2
	v_mov_b32_e32 v31, v2
	v_mov_b32_e32 v32, v2
	v_mov_b32_e32 v33, v2
	v_mov_b32_e32 v34, v2
	v_mov_b32_e32 v35, v2
	v_mov_b32_e32 v36, v2
	v_mov_b32_e32 v37, v2
	v_mov_b32_e32 v38, v2
	v_mov_b32_e32 v39, v2
	v_mov_b32_e32 v40, v2
	v_mov_b32_e32 v41, v2
	v_mov_b32_e32 v42, v2
	v_mov_b32_e32 v43, v2
	v_mov_b32_e32 v44, v2
	v_mov_b32_e32 v45, v2
	v_mov_b32_e32 v46, v2
	v_mov_b32_e32 v47, v2
	v_mov_b32_e32 v48, v2
	v_mov_b32_e32 v49, v2
	v_mov_b32_e32 v50, v2
	v_mov_b32_e32 v51, v2
	v_mov_b32_e32 v52, v2
	v_mov_b32_e32 v53, v2
	v_mov_b32_e32 v54, v2
	v_mov_b32_e32 v55, v2
	v_mov_b32_e32 v56, v2
	v_mov_b32_e32 v57, v2
	v_mov_b32_e32 v58, v2
	v_mov_b32_e32 v59, v2
	v_mov_b32_e32 v60, v2
	v_mov_b32_e32 v61, v2
	v_mov_b32_e32 v62, v2
	v_mov_b32_e32 v63, v2
	v_mov_b32_e32 v64, v2
	v_mov_b32_e32 v65, v2
	v_mov_b32_e32 v66, v2
	v_mov_b32_e32 v67, v2
	v_mov_b32_e32 v68, v2
	v_mov_b32_e32 v69, v2
	v_mov_b32_e32 v70, v2
	v_mov_b32_e32 v71, v2
	v_mov_b32_e32 v72, v2
	v_mov_b32_e32 v73, v2
	v_mov_b32_e32 v74, v2
	v_mov_b32_e32 v75, v2
	v_mov_b32_e32 v76, v2
	v_mov_b32_e32 v77, v2
	v_mov_b32_e32 v78, v2
	v_mov_b32_e32 v79, v2
	v_mov_b32_e32 v80, v2
	v_mov_b32_e32 v81, v2
	v_mov_b32_e32 v82, v2
	v_mov_b32_e32 v83, v2
	v_mov_b32_e32 v84, v2
	v_mov_b32_e32 v85, v2
	v_mov_b32_e32 v86, v2
	v_mov_b32_e32 v87, v2
	v_mov_b32_e32 v88, v2
	v_mov_b32_e32 v89, v2
	v_mov_b32_e32 v90, v2
	v_mov_b32_e32 v91, v2
	v_mov_b32_e32 v92, v2
	v_mov_b32_e32 v93, v2
	v_mov_b32_e32 v94, v2
	v_mov_b32_e32 v95, v2
	v_mov_b32_e32 v96, v2
	v_mov_b32_e32 v97, v2
	v_mov_b32_e32 v98, v2
	v_mov_b32_e32 v99, v2
	v_mov_b32_e32 v100, v2
	v_mov_b32_e32 v101, v2
	v_mov_b32_e32 v102, v2
	v_mov_b32_e32 v103, v2
	v_mov_b32_e32 v104, v2
	v_mov_b32_e32 v105, v2
	v_mov_b32_e32 v106, v2
	v_mov_b32_e32 v107, v2
	v_mov_b32_e32 v108, v2
	v_mov_b32_e32 v109, v2
	v_mov_b32_e32 v110, v2
	v_mov_b32_e32 v111, v2
	v_mov_b32_e32 v112, v2
	v_mov_b32_e32 v113, v2
	v_mov_b32_e32 v114, v2
	v_mov_b32_e32 v115, v2
	v_mov_b32_e32 v116, v2
	v_mov_b32_e32 v117, v2
	v_mov_b32_e32 v118, v2
	v_mov_b32_e32 v119, v2
	v_mov_b32_e32 v120, v2
	v_mov_b32_e32 v121, v2
	v_mov_b32_e32 v122, v2
	v_mov_b32_e32 v123, v2
	v_mov_b32_e32 v124, v2
	v_mov_b32_e32 v125, v2
	v_mov_b32_e32 v126, v2
	v_mov_b32_e32 v127, v2
	v_mov_b32_e32 v128, v2
	v_mov_b32_e32 v129, v2
	s_barrier
	s_branch .LBB0_954

.LBB0_967:
	s_add_i32 s56, s9, -2
	s_add_u32 s74, s24, 0x100
	s_addc_u32 s75, s25, 0
	s_add_u32 s22, s22, 0x80080
	s_addc_u32 s23, s23, 0
	s_mov_b32 s24, 0
	v_readfirstlane_b32 s100, v0
	s_nop 3
	s_bitcmp1_b32 s100, 8
	s_cbranch_scc0 .Lrb_skip4
	s_barrier
.Lrb_skip4:
.LBB0_968:
	s_add_i32 s76, s24, 2
	s_add_u32 s25, s22, 0xfff80080
	s_addc_u32 s26, s23, -1
	s_add_i32 s36, 0, 0x10000
	s_cmp_eq_u32 s56, s24
	s_cselect_b32 s27, s19, s26
	s_cselect_b32 s26, s18, s25
	s_cselect_b32 s25, s21, s75
	s_cselect_b32 s24, s20, s74
	s_add_i32 s38, 0, 0x14000
	v_add_u32_e32 v152, s36, v211
	v_add_u32_e32 v160, s38, v211
	ds_read_b128 v[140:143], v152
	ds_read_b128 v[144:147], v152 offset:1024
	ds_read_b128 v[148:151], v152 offset:2048
	ds_read_b128 v[152:155], v152 offset:3072
	ds_read_b128 v[156:159], v160
	ds_read_b128 v[172:175], v160 offset:1024
	ds_read_b128 v[176:179], v160 offset:2048
	ds_read_b128 v[180:183], v160 offset:3072
	v_lshl_add_u64 v[160:161], s[22:23], 0, v[138:139]
	s_add_i32 m0, s61, 0xc000
	ds_read_b128 v[184:187], v213
	ds_read_b128 v[188:191], v213 offset:1024
	ds_read_b128 v[192:195], v213 offset:2048
	ds_read_b128 v[196:199], v213 offset:3072
	ds_read_b128 v[200:203], v213 offset:4096
	ds_read_b128 v[204:207], v213 offset:5120
	ds_read_b128 v[222:225], v213 offset:6144
	ds_read_b128 v[226:229], v213 offset:7168
	global_load_lds_dwordx4 v[160:161], off
	v_lshl_add_u64 v[160:161], s[22:23], 0, v[136:137]
	s_add_i32 m0, s61, 0xe000
	s_nop 0
	global_load_lds_dwordx4 v[160:161], off
	s_waitcnt vmcnt(8)
	s_waitcnt lgkmcnt(0)
	s_barrier
	v_mfma_f32_16x16x32_bf16 v[126:129], v[140:143], v[184:187], v[126:129]
	v_mfma_f32_16x16x32_bf16 v[122:125], v[148:151], v[184:187], v[122:125]
	v_mfma_f32_16x16x32_bf16 v[118:121], v[140:143], v[192:195], v[118:121]
	v_mfma_f32_16x16x32_bf16 v[114:117], v[148:151], v[192:195], v[114:117]
	v_mfma_f32_16x16x32_bf16 v[110:113], v[140:143], v[200:203], v[110:113]
	v_mfma_f32_16x16x32_bf16 v[106:109], v[148:151], v[200:203], v[106:109]
	v_mfma_f32_16x16x32_bf16 v[102:105], v[140:143], v[222:225], v[102:105]
	v_mfma_f32_16x16x32_bf16 v[98:101], v[148:151], v[222:225], v[98:101]
	v_mfma_f32_16x16x32_bf16 v[126:129], v[144:147], v[188:191], v[126:129]
	v_mfma_f32_16x16x32_bf16 v[122:125], v[152:155], v[188:191], v[122:125]
	v_mfma_f32_16x16x32_bf16 v[118:121], v[144:147], v[196:199], v[118:121]
	v_mfma_f32_16x16x32_bf16 v[114:117], v[152:155], v[196:199], v[114:117]
	v_mfma_f32_16x16x32_bf16 v[110:113], v[144:147], v[204:207], v[110:113]
	v_mfma_f32_16x16x32_bf16 v[106:109], v[152:155], v[204:207], v[106:109]
	v_mfma_f32_16x16x32_bf16 v[102:105], v[144:147], v[226:229], v[102:105]
	v_mfma_f32_16x16x32_bf16 v[98:101], v[152:155], v[226:229], v[98:101]
	v_mfma_f32_16x16x32_bf16 v[94:97], v[156:159], v[184:187], v[94:97]
	v_mfma_f32_16x16x32_bf16 v[90:93], v[176:179], v[184:187], v[90:93]
	v_mfma_f32_16x16x32_bf16 v[86:89], v[156:159], v[192:195], v[86:89]
	v_mfma_f32_16x16x32_bf16 v[82:85], v[176:179], v[192:195], v[82:85]
	v_mfma_f32_16x16x32_bf16 v[78:81], v[156:159], v[200:203], v[78:81]
	v_mfma_f32_16x16x32_bf16 v[74:77], v[176:179], v[200:203], v[74:77]
	v_mfma_f32_16x16x32_bf16 v[70:73], v[156:159], v[222:225], v[70:73]
	v_mfma_f32_16x16x32_bf16 v[66:69], v[176:179], v[222:225], v[66:69]
	v_mfma_f32_16x16x32_bf16 v[94:97], v[172:175], v[188:191], v[94:97]
	v_mfma_f32_16x16x32_bf16 v[90:93], v[180:183], v[188:191], v[90:93]
	v_mfma_f32_16x16x32_bf16 v[86:89], v[172:175], v[196:199], v[86:89]
	v_mfma_f32_16x16x32_bf16 v[82:85], v[180:183], v[196:199], v[82:85]
	v_mfma_f32_16x16x32_bf16 v[78:81], v[172:175], v[204:207], v[78:81]
	v_mfma_f32_16x16x32_bf16 v[74:77], v[180:183], v[204:207], v[74:77]
	v_mfma_f32_16x16x32_bf16 v[70:73], v[172:175], v[226:229], v[70:73]
	v_mfma_f32_16x16x32_bf16 v[66:69], v[180:183], v[226:229], v[66:69]
	s_barrier
	s_add_i32 s36, s36, s60
	v_lshl_add_u64 v[160:161], s[24:25], 0, v[162:163]
	s_mov_b32 m0, s36
	ds_read_b128 v[184:187], v213 offset:16384
	ds_read_b128 v[188:191], v213 offset:17408
	ds_read_b128 v[192:195], v213 offset:18432
	ds_read_b128 v[196:199], v213 offset:19456
	ds_read_b128 v[200:203], v213 offset:20480
	ds_read_b128 v[204:207], v213 offset:21504
	ds_read_b128 v[222:225], v213 offset:22528
	ds_read_b128 v[226:229], v213 offset:23552
	global_load_lds_dwordx4 v[160:161], off
	s_add_i32 m0, s36, 0x2000
	s_add_u32 s36, s24, 0x80000
	v_lshl_add_u64 v[168:169], s[24:25], 0, v[134:135]
	s_addc_u32 s37, s25, 0
	s_add_i32 s38, s38, s60
	global_load_lds_dwordx4 v[168:169], off
	v_lshl_add_u64 v[170:171], s[36:37], 0, v[162:163]
	s_mov_b32 m0, s38
	v_lshl_add_u64 v[208:209], s[26:27], 0, v[132:133]
	global_load_lds_dwordx4 v[170:171], off
	v_lshl_add_u64 v[170:171], s[36:37], 0, v[134:135]
	s_add_i32 m0, s38, 0x2000
	s_nop 0
	global_load_lds_dwordx4 v[170:171], off
	v_lshl_add_u64 v[170:171], s[26:27], 0, v[130:131]
	s_mov_b32 m0, s61
	s_nop 0
	global_load_lds_dwordx4 v[170:171], off
	s_mov_b32 m0, s62
	s_nop 0
	global_load_lds_dwordx4 v[208:209], off
	s_waitcnt vmcnt(8)
	s_waitcnt lgkmcnt(0)
	s_barrier
	v_mfma_f32_16x16x32_bf16 v[62:65], v[140:143], v[184:187], v[62:65]
	v_mfma_f32_16x16x32_bf16 v[58:61], v[148:151], v[184:187], v[58:61]
	v_mfma_f32_16x16x32_bf16 v[54:57], v[140:143], v[192:195], v[54:57]
	v_mfma_f32_16x16x32_bf16 v[50:53], v[148:151], v[192:195], v[50:53]
	v_mfma_f32_16x16x32_bf16 v[46:49], v[140:143], v[200:203], v[46:49]
	v_mfma_f32_16x16x32_bf16 v[42:45], v[148:151], v[200:203], v[42:45]
	v_mfma_f32_16x16x32_bf16 v[38:41], v[140:143], v[222:225], v[38:41]
	v_mfma_f32_16x16x32_bf16 v[34:37], v[148:151], v[222:225], v[34:37]
	v_mfma_f32_16x16x32_bf16 v[62:65], v[144:147], v[188:191], v[62:65]
	v_mfma_f32_16x16x32_bf16 v[58:61], v[152:155], v[188:191], v[58:61]
	v_mfma_f32_16x16x32_bf16 v[54:57], v[144:147], v[196:199], v[54:57]
	v_mfma_f32_16x16x32_bf16 v[50:53], v[152:155], v[196:199], v[50:53]
	v_mfma_f32_16x16x32_bf16 v[46:49], v[144:147], v[204:207], v[46:49]
	v_mfma_f32_16x16x32_bf16 v[42:45], v[152:155], v[204:207], v[42:45]
	v_mfma_f32_16x16x32_bf16 v[38:41], v[144:147], v[226:229], v[38:41]
	v_mfma_f32_16x16x32_bf16 v[34:37], v[152:155], v[226:229], v[34:37]
	v_mfma_f32_16x16x32_bf16 v[30:33], v[156:159], v[184:187], v[30:33]
	v_mfma_f32_16x16x32_bf16 v[26:29], v[176:179], v[184:187], v[26:29]
	v_mfma_f32_16x16x32_bf16 v[22:25], v[156:159], v[192:195], v[22:25]
	v_mfma_f32_16x16x32_bf16 v[18:21], v[176:179], v[192:195], v[18:21]
	v_mfma_f32_16x16x32_bf16 v[14:17], v[156:159], v[200:203], v[14:17]
	v_mfma_f32_16x16x32_bf16 v[10:13], v[176:179], v[200:203], v[10:13]
	v_mfma_f32_16x16x32_bf16 v[6:9], v[156:159], v[222:225], v[6:9]
	v_mfma_f32_16x16x32_bf16 v[2:5], v[176:179], v[222:225], v[2:5]
	v_mfma_f32_16x16x32_bf16 v[30:33], v[172:175], v[188:191], v[30:33]
	v_mfma_f32_16x16x32_bf16 v[26:29], v[180:183], v[188:191], v[26:29]
	v_mfma_f32_16x16x32_bf16 v[22:25], v[172:175], v[196:199], v[22:25]
	v_mfma_f32_16x16x32_bf16 v[18:21], v[180:183], v[196:199], v[18:21]
	v_mfma_f32_16x16x32_bf16 v[14:17], v[172:175], v[204:207], v[14:17]
	v_mfma_f32_16x16x32_bf16 v[10:13], v[180:183], v[204:207], v[10:13]
	v_mfma_f32_16x16x32_bf16 v[6:9], v[172:175], v[226:229], v[6:9]
	v_mfma_f32_16x16x32_bf16 v[2:5], v[180:183], v[226:229], v[2:5]
	s_barrier
	s_add_i32 s36, 0, 0x18000
	s_add_i32 s37, 0, 0x1c000
	v_add_u32_e32 v152, s36, v211
	v_add_u32_e32 v180, s37, v211
	ds_read_b128 v[140:143], v152
	ds_read_b128 v[144:147], v152 offset:1024
	ds_read_b128 v[148:151], v152 offset:2048
	ds_read_b128 v[152:155], v152 offset:3072
	ds_read_b128 v[156:159], v180
	ds_read_b128 v[172:175], v180 offset:1024
	ds_read_b128 v[176:179], v180 offset:2048
	ds_read_b128 v[180:183], v180 offset:3072
	s_add_u32 s26, s26, 0x80000
	s_addc_u32 s27, s27, 0
	s_mov_b32 m0, s63
	v_lshl_add_u64 v[216:217], s[26:27], 0, v[130:131]
	ds_read_b128 v[184:187], v213 offset:32768
	ds_read_b128 v[188:191], v213 offset:33792
	ds_read_b128 v[192:195], v213 offset:34816
	ds_read_b128 v[196:199], v213 offset:35840
	ds_read_b128 v[200:203], v213 offset:36864
	ds_read_b128 v[204:207], v213 offset:37888
	ds_read_b128 v[222:225], v213 offset:38912
	ds_read_b128 v[226:229], v213 offset:39936
	global_load_lds_dwordx4 v[216:217], off
	v_lshl_add_u64 v[216:217], s[26:27], 0, v[132:133]
	s_mov_b32 m0, s64
	s_nop 0
	global_load_lds_dwordx4 v[216:217], off
	s_waitcnt vmcnt(8)
	s_waitcnt lgkmcnt(0)
	s_barrier
	v_mfma_f32_16x16x32_bf16 v[126:129], v[140:143], v[184:187], v[126:129]
	v_mfma_f32_16x16x32_bf16 v[122:125], v[148:151], v[184:187], v[122:125]
	v_mfma_f32_16x16x32_bf16 v[118:121], v[140:143], v[192:195], v[118:121]
	v_mfma_f32_16x16x32_bf16 v[114:117], v[148:151], v[192:195], v[114:117]
	v_mfma_f32_16x16x32_bf16 v[110:113], v[140:143], v[200:203], v[110:113]
	v_mfma_f32_16x16x32_bf16 v[106:109], v[148:151], v[200:203], v[106:109]
	v_mfma_f32_16x16x32_bf16 v[102:105], v[140:143], v[222:225], v[102:105]
	v_mfma_f32_16x16x32_bf16 v[98:101], v[148:151], v[222:225], v[98:101]
	v_mfma_f32_16x16x32_bf16 v[126:129], v[144:147], v[188:191], v[126:129]
	v_mfma_f32_16x16x32_bf16 v[122:125], v[152:155], v[188:191], v[122:125]
	v_mfma_f32_16x16x32_bf16 v[118:121], v[144:147], v[196:199], v[118:121]
	v_mfma_f32_16x16x32_bf16 v[114:117], v[152:155], v[196:199], v[114:117]
	v_mfma_f32_16x16x32_bf16 v[110:113], v[144:147], v[204:207], v[110:113]
	v_mfma_f32_16x16x32_bf16 v[106:109], v[152:155], v[204:207], v[106:109]
	v_mfma_f32_16x16x32_bf16 v[102:105], v[144:147], v[226:229], v[102:105]
	v_mfma_f32_16x16x32_bf16 v[98:101], v[152:155], v[226:229], v[98:101]
	v_mfma_f32_16x16x32_bf16 v[94:97], v[156:159], v[184:187], v[94:97]
	v_mfma_f32_16x16x32_bf16 v[90:93], v[176:179], v[184:187], v[90:93]
	v_mfma_f32_16x16x32_bf16 v[86:89], v[156:159], v[192:195], v[86:89]
	v_mfma_f32_16x16x32_bf16 v[82:85], v[176:179], v[192:195], v[82:85]
	v_mfma_f32_16x16x32_bf16 v[78:81], v[156:159], v[200:203], v[78:81]
	v_mfma_f32_16x16x32_bf16 v[74:77], v[176:179], v[200:203], v[74:77]
	v_mfma_f32_16x16x32_bf16 v[70:73], v[156:159], v[222:225], v[70:73]
	v_mfma_f32_16x16x32_bf16 v[66:69], v[176:179], v[222:225], v[66:69]
	v_mfma_f32_16x16x32_bf16 v[94:97], v[172:175], v[188:191], v[94:97]
	v_mfma_f32_16x16x32_bf16 v[90:93], v[180:183], v[188:191], v[90:93]
	v_mfma_f32_16x16x32_bf16 v[86:89], v[172:175], v[196:199], v[86:89]
	v_mfma_f32_16x16x32_bf16 v[82:85], v[180:183], v[196:199], v[82:85]
	v_mfma_f32_16x16x32_bf16 v[78:81], v[172:175], v[204:207], v[78:81]
	v_mfma_f32_16x16x32_bf16 v[74:77], v[180:183], v[204:207], v[74:77]
	v_mfma_f32_16x16x32_bf16 v[70:73], v[172:175], v[226:229], v[70:73]
	v_mfma_f32_16x16x32_bf16 v[66:69], v[180:183], v[226:229], v[66:69]
	s_barrier
	s_add_i32 s26, s36, s60
	v_lshl_add_u64 v[160:161], v[160:161], 0, s[44:45]
	s_mov_b32 m0, s26
	ds_read_b128 v[184:187], v213 offset:49152
	ds_read_b128 v[188:191], v213 offset:50176
	ds_read_b128 v[192:195], v213 offset:51200
	ds_read_b128 v[196:199], v213 offset:52224
	ds_read_b128 v[200:203], v213 offset:53248
	ds_read_b128 v[204:207], v213 offset:54272
	ds_read_b128 v[222:225], v213 offset:55296
	ds_read_b128 v[226:229], v213 offset:56320
	global_load_lds_dwordx4 v[160:161], off
	s_add_i32 m0, s26, 0x2000
	s_add_u32 s24, s24, 0x80080
	v_lshl_add_u64 v[160:161], v[168:169], 0, s[44:45]
	s_addc_u32 s25, s25, 0
	s_add_i32 s26, s37, s60
	global_load_lds_dwordx4 v[160:161], off
	v_lshl_add_u64 v[160:161], s[24:25], 0, v[162:163]
	s_mov_b32 m0, s26
	s_nop 0
	global_load_lds_dwordx4 v[160:161], off
	v_lshl_add_u64 v[160:161], s[24:25], 0, v[134:135]
	s_add_i32 m0, s26, 0x2000
	s_nop 0
	global_load_lds_dwordx4 v[160:161], off
	v_lshl_add_u64 v[160:161], v[170:171], 0, s[44:45]
	s_mov_b32 m0, s65
	s_nop 0
	global_load_lds_dwordx4 v[160:161], off
	v_lshl_add_u64 v[160:161], v[208:209], 0, s[44:45]
	s_mov_b32 m0, s66
	s_nop 0
	global_load_lds_dwordx4 v[160:161], off
	s_waitcnt vmcnt(8)
	s_waitcnt lgkmcnt(0)
	s_barrier
	v_mfma_f32_16x16x32_bf16 v[62:65], v[140:143], v[184:187], v[62:65]
	v_mfma_f32_16x16x32_bf16 v[58:61], v[148:151], v[184:187], v[58:61]
	v_mfma_f32_16x16x32_bf16 v[54:57], v[140:143], v[192:195], v[54:57]
	v_mfma_f32_16x16x32_bf16 v[50:53], v[148:151], v[192:195], v[50:53]
	v_mfma_f32_16x16x32_bf16 v[46:49], v[140:143], v[200:203], v[46:49]
	v_mfma_f32_16x16x32_bf16 v[42:45], v[148:151], v[200:203], v[42:45]
	v_mfma_f32_16x16x32_bf16 v[38:41], v[140:143], v[222:225], v[38:41]
	v_mfma_f32_16x16x32_bf16 v[34:37], v[148:151], v[222:225], v[34:37]
	v_mfma_f32_16x16x32_bf16 v[62:65], v[144:147], v[188:191], v[62:65]
	v_mfma_f32_16x16x32_bf16 v[58:61], v[152:155], v[188:191], v[58:61]
	v_mfma_f32_16x16x32_bf16 v[54:57], v[144:147], v[196:199], v[54:57]
	v_mfma_f32_16x16x32_bf16 v[50:53], v[152:155], v[196:199], v[50:53]
	v_mfma_f32_16x16x32_bf16 v[46:49], v[144:147], v[204:207], v[46:49]
	v_mfma_f32_16x16x32_bf16 v[42:45], v[152:155], v[204:207], v[42:45]
	v_mfma_f32_16x16x32_bf16 v[38:41], v[144:147], v[226:229], v[38:41]
	v_mfma_f32_16x16x32_bf16 v[34:37], v[152:155], v[226:229], v[34:37]
	v_mfma_f32_16x16x32_bf16 v[30:33], v[156:159], v[184:187], v[30:33]
	v_mfma_f32_16x16x32_bf16 v[26:29], v[176:179], v[184:187], v[26:29]
	v_mfma_f32_16x16x32_bf16 v[22:25], v[156:159], v[192:195], v[22:25]
	v_mfma_f32_16x16x32_bf16 v[18:21], v[176:179], v[192:195], v[18:21]
	v_mfma_f32_16x16x32_bf16 v[14:17], v[156:159], v[200:203], v[14:17]
	v_mfma_f32_16x16x32_bf16 v[10:13], v[176:179], v[200:203], v[10:13]
	v_mfma_f32_16x16x32_bf16 v[6:9], v[156:159], v[222:225], v[6:9]
	v_mfma_f32_16x16x32_bf16 v[2:5], v[176:179], v[222:225], v[2:5]
	v_mfma_f32_16x16x32_bf16 v[30:33], v[172:175], v[188:191], v[30:33]
	v_mfma_f32_16x16x32_bf16 v[26:29], v[180:183], v[188:191], v[26:29]
	v_mfma_f32_16x16x32_bf16 v[22:25], v[172:175], v[196:199], v[22:25]
	v_mfma_f32_16x16x32_bf16 v[18:21], v[180:183], v[196:199], v[18:21]
	v_mfma_f32_16x16x32_bf16 v[14:17], v[172:175], v[204:207], v[14:17]
	v_mfma_f32_16x16x32_bf16 v[10:13], v[180:183], v[204:207], v[10:13]
	v_mfma_f32_16x16x32_bf16 v[6:9], v[172:175], v[226:229], v[6:9]
	v_mfma_f32_16x16x32_bf16 v[2:5], v[180:183], v[226:229], v[2:5]
	s_barrier
	s_add_u32 s74, s74, 0x100
	s_addc_u32 s75, s75, 0
	s_add_u32 s22, s22, 0x100
	s_addc_u32 s23, s23, 0
	s_cmp_ge_i32 s76, s9
	s_mov_b32 s24, s76
	s_cbranch_scc0 .LBB0_968
	s_and_b64 vcc, exec, s[14:15]
	s_cbranch_vccz .LBB0_971
	s_barrier

.LBB0_1102:
	v_mov_b32_e32 v2, 0
	v_mov_b32_e32 v3, v2
	v_mov_b32_e32 v4, v2
	v_mov_b32_e32 v5, v2
	v_mov_b32_e32 v6, v2
	v_mov_b32_e32 v7, v2
	v_mov_b32_e32 v8, v2
	v_mov_b32_e32 v9, v2
	v_mov_b32_e32 v10, v2
	v_mov_b32_e32 v11, v2
	v_mov_b32_e32 v12, v2
	v_mov_b32_e32 v13, v2
	v_mov_b32_e32 v14, v2
	v_mov_b32_e32 v15, v2
	v_mov_b32_e32 v16, v2
	v_mov_b32_e32 v17, v2
	v_mov_b32_e32 v18, v2
	v_mov_b32_e32 v19, v2
	v_mov_b32_e32 v20, v2
	v_mov_b32_e32 v21, v2
	v_mov_b32_e32 v22, v2
	v_mov_b32_e32 v23, v2
	v_mov_b32_e32 v24, v2
	v_mov_b32_e32 v25, v2
	v_mov_b32_e32 v26, v2
	v_mov_b32_e32 v27, v2
	v_mov_b32_e32 v28, v2
	v_mov_b32_e32 v29, v2
	v_mov_b32_e32 v30, v2
	v_mov_b32_e32 v31, v2
	v_mov_b32_e32 v32, v2
	v_mov_b32_e32 v33, v2
	v_mov_b32_e32 v34, v2
	v_mov_b32_e32 v35, v2
	v_mov_b32_e32 v36, v2
	v_mov_b32_e32 v37, v2
	v_mov_b32_e32 v38, v2
	v_mov_b32_e32 v39, v2
	v_mov_b32_e32 v40, v2
	v_mov_b32_e32 v41, v2
	v_mov_b32_e32 v42, v2
	v_mov_b32_e32 v43, v2
	v_mov_b32_e32 v44, v2
	v_mov_b32_e32 v45, v2
	v_mov_b32_e32 v46, v2
	v_mov_b32_e32 v47, v2
	v_mov_b32_e32 v48, v2
	v_mov_b32_e32 v49, v2
	v_mov_b32_e32 v50, v2
	v_mov_b32_e32 v51, v2
	v_mov_b32_e32 v52, v2
	v_mov_b32_e32 v53, v2
	v_mov_b32_e32 v54, v2
	v_mov_b32_e32 v55, v2
	v_mov_b32_e32 v56, v2
	v_mov_b32_e32 v57, v2
	v_mov_b32_e32 v58, v2
	v_mov_b32_e32 v59, v2
	v_mov_b32_e32 v60, v2
	v_mov_b32_e32 v61, v2
	v_mov_b32_e32 v62, v2
	v_mov_b32_e32 v63, v2
	v_mov_b32_e32 v64, v2
	v_mov_b32_e32 v65, v2
	v_mov_b32_e32 v66, v2
	v_mov_b32_e32 v67, v2
	v_mov_b32_e32 v68, v2
	v_mov_b32_e32 v69, v2
	v_mov_b32_e32 v70, v2
	v_mov_b32_e32 v71, v2
	v_mov_b32_e32 v72, v2
	v_mov_b32_e32 v73, v2
	v_mov_b32_e32 v74, v2
	v_mov_b32_e32 v75, v2
	v_mov_b32_e32 v76, v2
	v_mov_b32_e32 v77, v2
	v_mov_b32_e32 v78, v2
	v_mov_b32_e32 v79, v2
	v_mov_b32_e32 v80, v2
	v_mov_b32_e32 v81, v2
	v_mov_b32_e32 v82, v2
	v_mov_b32_e32 v83, v2
	v_mov_b32_e32 v84, v2
	v_mov_b32_e32 v85, v2
	v_mov_b32_e32 v86, v2
	v_mov_b32_e32 v87, v2
	v_mov_b32_e32 v88, v2
	v_mov_b32_e32 v89, v2
	v_mov_b32_e32 v90, v2
	v_mov_b32_e32 v91, v2
	v_mov_b32_e32 v92, v2
	v_mov_b32_e32 v93, v2
	v_mov_b32_e32 v94, v2
	v_mov_b32_e32 v95, v2
	v_mov_b32_e32 v96, v2
	v_mov_b32_e32 v97, v2
	v_mov_b32_e32 v98, v2
	v_mov_b32_e32 v99, v2
	v_mov_b32_e32 v100, v2
	v_mov_b32_e32 v101, v2
	v_mov_b32_e32 v102, v2
	v_mov_b32_e32 v103, v2
	v_mov_b32_e32 v104, v2
	v_mov_b32_e32 v105, v2
	v_mov_b32_e32 v106, v2
	v_mov_b32_e32 v107, v2
	v_mov_b32_e32 v108, v2
	v_mov_b32_e32 v109, v2
	v_mov_b32_e32 v110, v2
	v_mov_b32_e32 v111, v2
	v_mov_b32_e32 v112, v2
	v_mov_b32_e32 v113, v2
	v_mov_b32_e32 v114, v2
	v_mov_b32_e32 v115, v2
	v_mov_b32_e32 v116, v2
	v_mov_b32_e32 v117, v2
	v_mov_b32_e32 v118, v2
	v_mov_b32_e32 v119, v2
	v_mov_b32_e32 v120, v2
	v_mov_b32_e32 v121, v2
	v_mov_b32_e32 v122, v2
	v_mov_b32_e32 v123, v2
	v_mov_b32_e32 v124, v2
	v_mov_b32_e32 v125, v2
	v_mov_b32_e32 v126, v2
	v_mov_b32_e32 v127, v2
	v_mov_b32_e32 v128, v2
	v_mov_b32_e32 v129, v2
	s_andn2_b64 vcc, exec, s[10:11]
	s_cbranch_vccnz .LBB0_952
.LBB0_1103:
	s_branch .LBB0_952
.LBB0_1104:
	s_waitcnt vmcnt(0)
	v_readlane_b32 s72, v254, 4
	v_readlane_b32 s38, v255, 10
	v_readlane_b32 s70, v255, 12
	v_readlane_b32 s73, v254, 5
	v_readlane_b32 s39, v255, 11
	v_readlane_b32 s71, v255, 13
	s_barrier

.LBB0_1191:
	s_and_b64 vcc, exec, s[4:5]
	v_readlane_b32 s4, v255, 23
	s_or_b32 s54, s4, 0x8000
	v_readlane_b32 s5, v255, 24
	s_cbranch_vccnz .LBB0_1234
	v_ashrrev_i32_e32 v3, 31, v10
	v_lshrrev_b32_e32 v3, 26, v3
	v_add_u32_e32 v3, v10, v3
	v_ashrrev_i32_e32 v11, 6, v3
	v_bfe_i32 v3, v10, 27, 1
	v_lshlrev_b32_e32 v2, 4, v10
	v_lshrrev_b32_e32 v3, 22, v3
	v_add_u32_e32 v3, v2, v3
	v_and_b32_e32 v3, 0xfffffc00, v3
	v_sub_u32_e32 v3, v2, v3
	v_lshrrev_b32_e32 v4, 4, v3
	v_bitop3_b32 v3, v4, v3, 32 bitop3:0x6c
	v_ashrrev_i32_e32 v5, 31, v3
	v_lshrrev_b32_e32 v5, 26, v5
	v_add_u32_e32 v5, v3, v5
	v_lshlrev_b32_e32 v4, 3, v11
	v_ashrrev_i32_e32 v12, 6, v5
	v_and_b32_e32 v5, 0xc0, v5
	v_and_b32_e32 v4, -16, v4
	v_sub_u32_e32 v3, v3, v5
	v_add_u32_e32 v4, v12, v4
	v_ashrrev_i16_sdwa v3, v219, sext(v3) dst_sel:DWORD dst_unused:UNUSED_PAD src0_sel:DWORD src1_sel:BYTE_0
	v_lshlrev_b32_e32 v6, 5, v11
	v_bfe_i32 v13, v3, 0, 16
	v_lshlrev_b32_e32 v3, 1, v4
	v_lshrrev_b32_e32 v5, 2, v4
	v_and_b32_e32 v7, 3, v12
	s_mov_b32 s5, 0xfffe0
	v_and_b32_e32 v6, 32, v6
	v_and_b32_e32 v3, 24, v3
	v_and_b32_e32 v5, 4, v5
	v_and_or_b32 v7, v4, s5, v7
	v_or3_b32 v3, v7, v5, v3
	v_add_lshl_u32 v5, v6, v13, 1
	v_add_u32_e32 v2, 0x2000, v2
	v_lshl_add_u32 v162, v3, 12, v5
	v_ashrrev_i32_e32 v3, 31, v2
	v_lshrrev_b32_e32 v3, 22, v3
	v_add_u32_e32 v3, v2, v3
	v_ashrrev_i32_e32 v14, 10, v3
	v_mul_i32_i24_e32 v3, 0x400, v14
	v_sub_u32_e32 v2, v2, v3
	v_lshrrev_b32_e32 v3, 4, v2
	v_bitop3_b32 v2, v3, v2, 32 bitop3:0x6c
	v_lshl_add_u32 v154, v4, 12, v5
	v_ashrrev_i32_e32 v4, 31, v2
	v_lshrrev_b32_e32 v4, 26, v4
	v_lshlrev_b32_e32 v3, 3, v14
	v_add_u32_e32 v4, v2, v4
	v_and_b32_e32 v3, -16, v3
	v_ashrrev_i32_e32 v15, 6, v4
	v_add_u32_e32 v3, v15, v3
	v_and_b32_e32 v4, 0xc0, v4
	v_and_b32_e32 v6, 3, v15
	v_sub_u32_e32 v2, v2, v4
	v_and_or_b32 v6, v3, s5, v6
	s_ashr_i32 s5, s18, 6
	v_ashrrev_i16_sdwa v2, v219, sext(v2) dst_sel:DWORD dst_unused:UNUSED_PAD src0_sel:DWORD src1_sel:BYTE_0
	s_lshl_b32 s27, s5, 10
	v_lshlrev_b32_e32 v5, 5, v14
	v_bfe_i32 v16, v2, 0, 16
	v_lshlrev_b32_e32 v2, 1, v3
	v_lshrrev_b32_e32 v4, 2, v3
	s_add_i32 s66, s27, 0
	v_and_b32_e32 v5, 32, v5
	v_and_b32_e32 v2, 24, v2
	v_and_b32_e32 v4, 4, v4
	s_add_i32 m0, s66, 0x10000
	s_ashr_i32 s4, s18, 8
	v_or3_b32 v2, v6, v4, v2
	v_add_lshl_u32 v4, v5, v16, 1
	global_load_lds_dwordx4 v162, s[58:59]
	s_add_i32 m0, s66, 0x12000
	v_lshl_add_u32 v158, v2, 12, v4
	s_add_u32 s8, s58, 0x80000
	global_load_lds_dwordx4 v158, s[58:59]
	s_addc_u32 s9, s59, 0
	s_add_i32 m0, s66, 0x14000
	s_add_i32 s67, s66, 0x2000
	global_load_lds_dwordx4 v162, s[8:9]
	s_add_i32 m0, s66, 0x16000
	v_lshl_add_u32 v156, v3, 12, v4
	global_load_lds_dwordx4 v158, s[8:9]
	s_mov_b32 m0, s66
	s_add_u32 s8, s56, 0x80000
	global_load_lds_dwordx4 v154, s[56:57]
	s_mov_b32 m0, s67
	s_addc_u32 s9, s57, 0
	s_add_i32 s68, s66, 0x4000
	global_load_lds_dwordx4 v156, s[56:57]
	s_mov_b32 m0, s68
	s_add_i32 s69, s66, 0x6000
	global_load_lds_dwordx4 v154, s[8:9]
	s_mov_b32 m0, s69
	v_mov_b32_e32 v159, v163
	global_load_lds_dwordx4 v156, s[8:9]
	v_mov_b32_e32 v155, v163
	v_mov_b32_e32 v157, v163
	s_cmp_eq_u32 s4, 1
	v_lshl_add_u64 v[8:9], s[58:59], 0, v[162:163]
	v_lshl_add_u64 v[6:7], s[58:59], 0, v[158:159]
	v_lshl_add_u64 v[2:3], s[56:57], 0, v[154:155]
	s_cselect_b64 s[8:9], -1, 0
	s_cmp_lg_u32 s4, 1
	v_lshl_add_u64 v[4:5], s[56:57], 0, v[156:157]
	s_cbranch_scc1 .LBB0_1194
.LBB0_1194:
	s_add_u32 s10, s6, 0x44000000
	s_addc_u32 s11, s7, 0
	s_add_u32 s16, s6, 0x100000
	s_addc_u32 s17, s7, 0
	s_lshl_b64 s[12:13], s[54:55], 3
	s_add_u32 s12, s16, s12
	s_addc_u32 s13, s17, s13
	s_add_u32 s14, s6, 0x69000000
	s_addc_u32 s15, s7, 0
	v_readlane_b32 s6, v255, 28
	v_bfe_u32 v18, v10, 4, 2
	v_readlane_b32 s7, v255, 29
	s_add_u32 s16, s16, s6
	v_and_b32_e32 v17, 15, v10
	v_lshlrev_b32_e32 v19, 4, v18
	v_lshlrev_b32_e32 v10, 2, v10
	s_addc_u32 s17, s17, s7
	v_lshl_or_b32 v200, s4, 6, v17
	v_lshl_or_b32 v17, v17, 6, v19
	s_lshl_b32 s4, s4, 13
	v_and_b32_e32 v10, 32, v10
	v_bitop3_b32 v19, v17, s4, v10 bitop3:0xde
	s_lshl_b32 s4, s5, 5
	s_and_b32 s6, s4, 0x60
	s_add_i32 m0, s66, 0x18000
	v_lshl_add_u64 v[8:9], v[8:9], 0, s[44:45]
	s_lshl_b32 s4, s6, 7
	s_waitcnt vmcnt(2)
	s_barrier
	global_load_lds_dwordx4 v[8:9], off
	v_lshl_add_u64 v[6:7], v[6:7], 0, s[44:45]
	s_add_i32 m0, s66, 0x1a000
	s_add_i32 s70, s66, 0x8000
	s_add_i32 s71, s66, 0xa000
	v_bitop3_b32 v201, v17, s4, v10 bitop3:0xde
	global_load_lds_dwordx4 v[6:7], off
	v_lshl_add_u64 v[2:3], v[2:3], 0, s[44:45]
	s_mov_b32 m0, s70
	s_add_u32 s4, s58, 0x80080
	global_load_lds_dwordx4 v[2:3], off
	v_lshl_add_u64 v[2:3], v[4:5], 0, s[44:45]
	s_mov_b32 m0, s71
	s_addc_u32 s5, s59, 0
	global_load_lds_dwordx4 v[2:3], off
	s_add_i32 m0, s66, 0x1c000
	v_lshl_add_u64 v[2:3], s[4:5], 0, v[162:163]
	global_load_lds_dwordx4 v[2:3], off
	v_lshl_add_u64 v[2:3], s[4:5], 0, v[158:159]
	s_add_i32 m0, s66, 0x1e000
	s_and_b32 s73, s2, 7
	global_load_lds_dwordx4 v[2:3], off
	v_lshlrev_b32_e32 v2, 15, v14
	v_and_b32_e32 v2, 0xffff0000, v2
	v_lshl_add_u32 v2, v15, 12, v2
	v_and_b32_e32 v3, 1, v14
	v_lshl_or_b32 v2, v3, 6, v2
	s_ashr_i32 s74, s2, 3
	v_lshl_add_u32 v160, v16, 1, v2
	v_lshlrev_b32_e32 v2, 15, v11
	s_lshl_b32 s4, s73, 3
	s_and_b32 s5, s74, 7
	v_and_b32_e32 v2, 0xffff0000, v2
	s_waitcnt vmcnt(6)
	s_ashr_i32 s72, s2, 31
	s_or_b32 s75, s4, s5
	v_lshl_add_u32 v2, v12, 12, v2
	v_and_b32_e32 v3, 1, v11
	s_cmpk_lt_u32 s18, 0x100
	v_lshl_or_b32 v2, v3, 6, v2
	s_cselect_b64 s[18:19], -1, 0
	s_mov_b32 s76, 0
	v_cmp_eq_u32_e64 s[4:5], 0, v18
	v_lshl_or_b32 v202, v18, 3, s6
	v_mov_b32_e32 v161, v163
	v_lshl_add_u32 v172, v13, 1, v2
	v_mov_b32_e32 v173, v163
	v_add_u32_e32 v203, 0, v19
	s_barrier
	s_branch .LBB0_1197

.LBB0_1210:
	s_add_u32 s25, s58, 0x100
	s_addc_u32 s62, s59, 0
	s_add_u32 s56, s56, 0x80080
	v_mov_b32_e32 v2, 0
	s_addc_u32 s57, s57, 0
	s_mov_b32 s78, -2
	s_waitcnt lgkmcnt(0)
	v_mov_b32_e32 v3, v2
	v_mov_b32_e32 v4, v2
	v_mov_b32_e32 v5, v2
	v_mov_b32_e32 v6, v2
	v_mov_b32_e32 v7, v2
	v_mov_b32_e32 v8, v2
	v_mov_b32_e32 v9, v2
	v_mov_b32_e32 v18, v2
	v_mov_b32_e32 v19, v2
	v_mov_b32_e32 v20, v2
	v_mov_b32_e32 v21, v2
	v_mov_b32_e32 v22, v2
	v_mov_b32_e32 v23, v2
	v_mov_b32_e32 v24, v2
	v_mov_b32_e32 v25, v2
	v_mov_b32_e32 v34, v2
	v_mov_b32_e32 v35, v2
	v_mov_b32_e32 v36, v2
	v_mov_b32_e32 v37, v2
	v_mov_b32_e32 v38, v2
	v_mov_b32_e32 v39, v2
	v_mov_b32_e32 v40, v2
	v_mov_b32_e32 v41, v2
	v_mov_b32_e32 v50, v2
	v_mov_b32_e32 v51, v2
	v_mov_b32_e32 v52, v2
	v_mov_b32_e32 v53, v2
	v_mov_b32_e32 v54, v2
	v_mov_b32_e32 v55, v2
	v_mov_b32_e32 v56, v2
	v_mov_b32_e32 v57, v2
	v_mov_b32_e32 v10, v2
	v_mov_b32_e32 v11, v2
	v_mov_b32_e32 v12, v2
	v_mov_b32_e32 v13, v2
	v_mov_b32_e32 v14, v2
	v_mov_b32_e32 v15, v2
	v_mov_b32_e32 v16, v2
	v_mov_b32_e32 v17, v2
	v_mov_b32_e32 v26, v2
	v_mov_b32_e32 v27, v2
	v_mov_b32_e32 v28, v2
	v_mov_b32_e32 v29, v2
	v_mov_b32_e32 v30, v2
	v_mov_b32_e32 v31, v2
	v_mov_b32_e32 v32, v2
	v_mov_b32_e32 v33, v2
	v_mov_b32_e32 v42, v2
	v_mov_b32_e32 v43, v2
	v_mov_b32_e32 v44, v2
	v_mov_b32_e32 v45, v2
	v_mov_b32_e32 v46, v2
	v_mov_b32_e32 v47, v2
	v_mov_b32_e32 v48, v2
	v_mov_b32_e32 v49, v2
	v_mov_b32_e32 v58, v2
	v_mov_b32_e32 v59, v2
	v_mov_b32_e32 v60, v2
	v_mov_b32_e32 v61, v2
	v_mov_b32_e32 v62, v2
	v_mov_b32_e32 v63, v2
	v_mov_b32_e32 v64, v2
	v_mov_b32_e32 v65, v2
	v_mov_b32_e32 v66, v2
	v_mov_b32_e32 v67, v2
	v_mov_b32_e32 v68, v2
	v_mov_b32_e32 v69, v2
	v_mov_b32_e32 v70, v2
	v_mov_b32_e32 v71, v2
	v_mov_b32_e32 v72, v2
	v_mov_b32_e32 v73, v2
	v_mov_b32_e32 v82, v2
	v_mov_b32_e32 v83, v2
	v_mov_b32_e32 v84, v2
	v_mov_b32_e32 v85, v2
	v_mov_b32_e32 v86, v2
	v_mov_b32_e32 v87, v2
	v_mov_b32_e32 v88, v2
	v_mov_b32_e32 v89, v2
	v_mov_b32_e32 v98, v2
	v_mov_b32_e32 v99, v2
	v_mov_b32_e32 v100, v2
	v_mov_b32_e32 v101, v2
	v_mov_b32_e32 v102, v2
	v_mov_b32_e32 v103, v2
	v_mov_b32_e32 v104, v2
	v_mov_b32_e32 v105, v2
	v_mov_b32_e32 v122, v2
	v_mov_b32_e32 v123, v2
	v_mov_b32_e32 v124, v2
	v_mov_b32_e32 v125, v2
	v_mov_b32_e32 v126, v2
	v_mov_b32_e32 v127, v2
	v_mov_b32_e32 v128, v2
	v_mov_b32_e32 v129, v2
	v_mov_b32_e32 v74, v2
	v_mov_b32_e32 v75, v2
	v_mov_b32_e32 v76, v2
	v_mov_b32_e32 v77, v2
	v_mov_b32_e32 v78, v2
	v_mov_b32_e32 v79, v2
	v_mov_b32_e32 v80, v2
	v_mov_b32_e32 v81, v2
	v_mov_b32_e32 v90, v2
	v_mov_b32_e32 v91, v2
	v_mov_b32_e32 v92, v2
	v_mov_b32_e32 v93, v2
	v_mov_b32_e32 v94, v2
	v_mov_b32_e32 v95, v2
	v_mov_b32_e32 v96, v2
	v_mov_b32_e32 v97, v2
	v_mov_b32_e32 v106, v2
	v_mov_b32_e32 v107, v2
	v_mov_b32_e32 v108, v2
	v_mov_b32_e32 v109, v2
	v_mov_b32_e32 v114, v2
	v_mov_b32_e32 v115, v2
	v_mov_b32_e32 v116, v2
	v_mov_b32_e32 v117, v2
	v_mov_b32_e32 v130, v2
	v_mov_b32_e32 v131, v2
	v_mov_b32_e32 v132, v2
	v_mov_b32_e32 v133, v2
	v_mov_b32_e32 v134, v2
	v_mov_b32_e32 v135, v2
	v_mov_b32_e32 v136, v2
	v_mov_b32_e32 v137, v2
	v_readfirstlane_b32 s100, v0
	s_nop 3
	s_bitcmp1_b32 s100, 8
	s_cbranch_scc0 .Lrb_skip5
	s_barrier
.Lrb_skip5:
.LBB0_1211:
	s_add_u32 s36, s56, 0xfff80080
	s_addc_u32 s37, s57, -1
	s_add_i32 s38, 0, 0x10000
	s_cmp_eq_u32 s78, 28
	s_cselect_b32 s61, s21, s37
	s_cselect_b32 s60, s20, s36
	s_cselect_b32 s59, s23, s62
	s_cselect_b32 s58, s22, s25
	s_add_i32 s39, 0, 0x14000
	v_add_u32_e32 v142, s38, v201
	v_add_u32_e32 v168, s39, v201
	ds_read_b128 v[110:113], v142
	ds_read_b128 v[118:121], v142 offset:1024
	ds_read_b128 v[138:141], v142 offset:2048
	ds_read_b128 v[142:145], v142 offset:3072
	ds_read_b128 v[146:149], v168
	ds_read_b128 v[150:153], v168 offset:1024
	ds_read_b128 v[174:177], v168 offset:2048
	ds_read_b128 v[178:181], v168 offset:3072
	v_lshl_add_u64 v[168:169], s[56:57], 0, v[172:173]
	s_add_i32 m0, s66, 0xc000
	ds_read_b128 v[182:185], v203
	ds_read_b128 v[186:189], v203 offset:1024
	ds_read_b128 v[190:193], v203 offset:2048
	ds_read_b128 v[194:197], v203 offset:3072
	ds_read_b128 v[204:207], v203 offset:4096
	ds_read_b128 v[208:211], v203 offset:5120
	ds_read_b128 v[212:215], v203 offset:6144
	ds_read_b128 v[222:225], v203 offset:7168
	global_load_lds_dwordx4 v[168:169], off
	v_lshl_add_u64 v[168:169], s[56:57], 0, v[160:161]
	s_add_i32 m0, s66, 0xe000
	s_nop 0
	global_load_lds_dwordx4 v[168:169], off
	s_waitcnt vmcnt(8)
	s_waitcnt lgkmcnt(0)
	s_barrier
	v_mfma_f32_16x16x32_bf16 v[134:137], v[110:113], v[182:185], v[134:137]
	v_mfma_f32_16x16x32_bf16 v[130:133], v[138:141], v[182:185], v[130:133]
	v_mfma_f32_16x16x32_bf16 v[114:117], v[110:113], v[190:193], v[114:117]
	v_mfma_f32_16x16x32_bf16 v[106:109], v[138:141], v[190:193], v[106:109]
	v_mfma_f32_16x16x32_bf16 v[94:97], v[110:113], v[204:207], v[94:97]
	v_mfma_f32_16x16x32_bf16 v[90:93], v[138:141], v[204:207], v[90:93]
	v_mfma_f32_16x16x32_bf16 v[78:81], v[110:113], v[212:215], v[78:81]
	v_mfma_f32_16x16x32_bf16 v[74:77], v[138:141], v[212:215], v[74:77]
	v_mfma_f32_16x16x32_bf16 v[134:137], v[118:121], v[186:189], v[134:137]
	v_mfma_f32_16x16x32_bf16 v[130:133], v[142:145], v[186:189], v[130:133]
	v_mfma_f32_16x16x32_bf16 v[114:117], v[118:121], v[194:197], v[114:117]
	v_mfma_f32_16x16x32_bf16 v[106:109], v[142:145], v[194:197], v[106:109]
	v_mfma_f32_16x16x32_bf16 v[94:97], v[118:121], v[208:211], v[94:97]
	v_mfma_f32_16x16x32_bf16 v[90:93], v[142:145], v[208:211], v[90:93]
	v_mfma_f32_16x16x32_bf16 v[78:81], v[118:121], v[222:225], v[78:81]
	v_mfma_f32_16x16x32_bf16 v[74:77], v[142:145], v[222:225], v[74:77]
	v_mfma_f32_16x16x32_bf16 v[126:129], v[146:149], v[182:185], v[126:129]
	v_mfma_f32_16x16x32_bf16 v[122:125], v[174:177], v[182:185], v[122:125]
	v_mfma_f32_16x16x32_bf16 v[102:105], v[146:149], v[190:193], v[102:105]
	v_mfma_f32_16x16x32_bf16 v[98:101], v[174:177], v[190:193], v[98:101]
	v_mfma_f32_16x16x32_bf16 v[86:89], v[146:149], v[204:207], v[86:89]
	v_mfma_f32_16x16x32_bf16 v[82:85], v[174:177], v[204:207], v[82:85]
	v_mfma_f32_16x16x32_bf16 v[70:73], v[146:149], v[212:215], v[70:73]
	v_mfma_f32_16x16x32_bf16 v[66:69], v[174:177], v[212:215], v[66:69]
	v_mfma_f32_16x16x32_bf16 v[126:129], v[150:153], v[186:189], v[126:129]
	v_mfma_f32_16x16x32_bf16 v[122:125], v[178:181], v[186:189], v[122:125]
	v_mfma_f32_16x16x32_bf16 v[102:105], v[150:153], v[194:197], v[102:105]
	v_mfma_f32_16x16x32_bf16 v[98:101], v[178:181], v[194:197], v[98:101]
	v_mfma_f32_16x16x32_bf16 v[86:89], v[150:153], v[208:211], v[86:89]
	v_mfma_f32_16x16x32_bf16 v[82:85], v[178:181], v[208:211], v[82:85]
	v_mfma_f32_16x16x32_bf16 v[70:73], v[150:153], v[222:225], v[70:73]
	v_mfma_f32_16x16x32_bf16 v[66:69], v[178:181], v[222:225], v[66:69]
	s_barrier
	s_add_i32 s36, s38, s27
	v_lshl_add_u64 v[168:169], s[58:59], 0, v[162:163]
	s_mov_b32 m0, s36
	ds_read_b128 v[182:185], v203 offset:16384
	ds_read_b128 v[186:189], v203 offset:17408
	ds_read_b128 v[190:193], v203 offset:18432
	ds_read_b128 v[194:197], v203 offset:19456
	ds_read_b128 v[204:207], v203 offset:20480
	ds_read_b128 v[208:211], v203 offset:21504
	ds_read_b128 v[212:215], v203 offset:22528
	ds_read_b128 v[222:225], v203 offset:23552
	global_load_lds_dwordx4 v[168:169], off
	s_add_i32 m0, s36, 0x2000
	s_add_u32 s36, s58, 0x80000
	v_lshl_add_u64 v[170:171], s[58:59], 0, v[158:159]
	s_addc_u32 s37, s59, 0
	s_add_i32 s38, s39, s27
	global_load_lds_dwordx4 v[170:171], off
	v_lshl_add_u64 v[198:199], s[36:37], 0, v[162:163]
	s_mov_b32 m0, s38
	v_lshl_add_u64 v[216:217], s[60:61], 0, v[156:157]
	global_load_lds_dwordx4 v[198:199], off
	v_lshl_add_u64 v[198:199], s[36:37], 0, v[158:159]
	s_add_i32 m0, s38, 0x2000
	s_nop 0
	global_load_lds_dwordx4 v[198:199], off
	v_lshl_add_u64 v[198:199], s[60:61], 0, v[154:155]
	s_mov_b32 m0, s66
	s_nop 0
	global_load_lds_dwordx4 v[198:199], off
	s_mov_b32 m0, s67
	s_nop 0
	global_load_lds_dwordx4 v[216:217], off
	s_waitcnt vmcnt(8)
	s_waitcnt lgkmcnt(0)
	s_barrier
	v_mfma_f32_16x16x32_bf16 v[62:65], v[110:113], v[182:185], v[62:65]
	v_mfma_f32_16x16x32_bf16 v[58:61], v[138:141], v[182:185], v[58:61]
	v_mfma_f32_16x16x32_bf16 v[46:49], v[110:113], v[190:193], v[46:49]
	v_mfma_f32_16x16x32_bf16 v[42:45], v[138:141], v[190:193], v[42:45]
	v_mfma_f32_16x16x32_bf16 v[30:33], v[110:113], v[204:207], v[30:33]
	v_mfma_f32_16x16x32_bf16 v[26:29], v[138:141], v[204:207], v[26:29]
	v_mfma_f32_16x16x32_bf16 v[14:17], v[110:113], v[212:215], v[14:17]
	v_mfma_f32_16x16x32_bf16 v[10:13], v[138:141], v[212:215], v[10:13]
	v_mfma_f32_16x16x32_bf16 v[62:65], v[118:121], v[186:189], v[62:65]
	v_mfma_f32_16x16x32_bf16 v[58:61], v[142:145], v[186:189], v[58:61]
	v_mfma_f32_16x16x32_bf16 v[46:49], v[118:121], v[194:197], v[46:49]
	v_mfma_f32_16x16x32_bf16 v[42:45], v[142:145], v[194:197], v[42:45]
	v_mfma_f32_16x16x32_bf16 v[30:33], v[118:121], v[208:211], v[30:33]
	v_mfma_f32_16x16x32_bf16 v[26:29], v[142:145], v[208:211], v[26:29]
	v_mfma_f32_16x16x32_bf16 v[14:17], v[118:121], v[222:225], v[14:17]
	v_mfma_f32_16x16x32_bf16 v[10:13], v[142:145], v[222:225], v[10:13]
	v_mfma_f32_16x16x32_bf16 v[54:57], v[146:149], v[182:185], v[54:57]
	v_mfma_f32_16x16x32_bf16 v[50:53], v[174:177], v[182:185], v[50:53]
	v_mfma_f32_16x16x32_bf16 v[38:41], v[146:149], v[190:193], v[38:41]
	v_mfma_f32_16x16x32_bf16 v[34:37], v[174:177], v[190:193], v[34:37]
	v_mfma_f32_16x16x32_bf16 v[22:25], v[146:149], v[204:207], v[22:25]
	v_mfma_f32_16x16x32_bf16 v[18:21], v[174:177], v[204:207], v[18:21]
	v_mfma_f32_16x16x32_bf16 v[6:9], v[146:149], v[212:215], v[6:9]
	v_mfma_f32_16x16x32_bf16 v[2:5], v[174:177], v[212:215], v[2:5]
	v_mfma_f32_16x16x32_bf16 v[54:57], v[150:153], v[186:189], v[54:57]
	v_mfma_f32_16x16x32_bf16 v[50:53], v[178:181], v[186:189], v[50:53]
	v_mfma_f32_16x16x32_bf16 v[38:41], v[150:153], v[194:197], v[38:41]
	v_mfma_f32_16x16x32_bf16 v[34:37], v[178:181], v[194:197], v[34:37]
	v_mfma_f32_16x16x32_bf16 v[22:25], v[150:153], v[208:211], v[22:25]
	v_mfma_f32_16x16x32_bf16 v[18:21], v[178:181], v[208:211], v[18:21]
	v_mfma_f32_16x16x32_bf16 v[6:9], v[150:153], v[222:225], v[6:9]
	v_mfma_f32_16x16x32_bf16 v[2:5], v[178:181], v[222:225], v[2:5]
	s_barrier
	s_add_i32 s38, 0, 0x18000
	s_add_i32 s39, 0, 0x1c000
	v_add_u32_e32 v142, s38, v201
	v_add_u32_e32 v178, s39, v201
	ds_read_b128 v[110:113], v142
	ds_read_b128 v[118:121], v142 offset:1024
	ds_read_b128 v[138:141], v142 offset:2048
	ds_read_b128 v[142:145], v142 offset:3072
	ds_read_b128 v[146:149], v178
	ds_read_b128 v[150:153], v178 offset:1024
	ds_read_b128 v[174:177], v178 offset:2048
	ds_read_b128 v[178:181], v178 offset:3072
	s_add_u32 s36, s60, 0x80000
	s_addc_u32 s37, s61, 0
	s_mov_b32 m0, s68
	v_lshl_add_u64 v[226:227], s[36:37], 0, v[154:155]
	ds_read_b128 v[182:185], v203 offset:32768
	ds_read_b128 v[186:189], v203 offset:33792
	ds_read_b128 v[190:193], v203 offset:34816
	ds_read_b128 v[194:197], v203 offset:35840
	ds_read_b128 v[204:207], v203 offset:36864
	ds_read_b128 v[208:211], v203 offset:37888
	ds_read_b128 v[212:215], v203 offset:38912
	ds_read_b128 v[222:225], v203 offset:39936
	global_load_lds_dwordx4 v[226:227], off
	v_lshl_add_u64 v[226:227], s[36:37], 0, v[156:157]
	s_mov_b32 m0, s69
	s_nop 0
	global_load_lds_dwordx4 v[226:227], off
	s_waitcnt vmcnt(8)
	s_waitcnt lgkmcnt(0)
	s_barrier
	v_mfma_f32_16x16x32_bf16 v[134:137], v[110:113], v[182:185], v[134:137]
	v_mfma_f32_16x16x32_bf16 v[130:133], v[138:141], v[182:185], v[130:133]
	v_mfma_f32_16x16x32_bf16 v[114:117], v[110:113], v[190:193], v[114:117]
	v_mfma_f32_16x16x32_bf16 v[106:109], v[138:141], v[190:193], v[106:109]
	v_mfma_f32_16x16x32_bf16 v[94:97], v[110:113], v[204:207], v[94:97]
	v_mfma_f32_16x16x32_bf16 v[90:93], v[138:141], v[204:207], v[90:93]
	v_mfma_f32_16x16x32_bf16 v[78:81], v[110:113], v[212:215], v[78:81]
	v_mfma_f32_16x16x32_bf16 v[74:77], v[138:141], v[212:215], v[74:77]
	v_mfma_f32_16x16x32_bf16 v[134:137], v[118:121], v[186:189], v[134:137]
	v_mfma_f32_16x16x32_bf16 v[130:133], v[142:145], v[186:189], v[130:133]
	v_mfma_f32_16x16x32_bf16 v[114:117], v[118:121], v[194:197], v[114:117]
	v_mfma_f32_16x16x32_bf16 v[106:109], v[142:145], v[194:197], v[106:109]
	v_mfma_f32_16x16x32_bf16 v[94:97], v[118:121], v[208:211], v[94:97]
	v_mfma_f32_16x16x32_bf16 v[90:93], v[142:145], v[208:211], v[90:93]
	v_mfma_f32_16x16x32_bf16 v[78:81], v[118:121], v[222:225], v[78:81]
	v_mfma_f32_16x16x32_bf16 v[74:77], v[142:145], v[222:225], v[74:77]
	v_mfma_f32_16x16x32_bf16 v[126:129], v[146:149], v[182:185], v[126:129]
	v_mfma_f32_16x16x32_bf16 v[122:125], v[174:177], v[182:185], v[122:125]
	v_mfma_f32_16x16x32_bf16 v[102:105], v[146:149], v[190:193], v[102:105]
	v_mfma_f32_16x16x32_bf16 v[98:101], v[174:177], v[190:193], v[98:101]
	v_mfma_f32_16x16x32_bf16 v[86:89], v[146:149], v[204:207], v[86:89]
	v_mfma_f32_16x16x32_bf16 v[82:85], v[174:177], v[204:207], v[82:85]
	v_mfma_f32_16x16x32_bf16 v[70:73], v[146:149], v[212:215], v[70:73]
	v_mfma_f32_16x16x32_bf16 v[66:69], v[174:177], v[212:215], v[66:69]
	v_mfma_f32_16x16x32_bf16 v[126:129], v[150:153], v[186:189], v[126:129]
	v_mfma_f32_16x16x32_bf16 v[122:125], v[178:181], v[186:189], v[122:125]
	v_mfma_f32_16x16x32_bf16 v[102:105], v[150:153], v[194:197], v[102:105]
	v_mfma_f32_16x16x32_bf16 v[98:101], v[178:181], v[194:197], v[98:101]
	v_mfma_f32_16x16x32_bf16 v[86:89], v[150:153], v[208:211], v[86:89]
	v_mfma_f32_16x16x32_bf16 v[82:85], v[178:181], v[208:211], v[82:85]
	v_mfma_f32_16x16x32_bf16 v[70:73], v[150:153], v[222:225], v[70:73]
	v_mfma_f32_16x16x32_bf16 v[66:69], v[178:181], v[222:225], v[66:69]
	s_barrier
	s_add_i32 s36, s38, s27
	v_lshl_add_u64 v[168:169], v[168:169], 0, s[44:45]
	s_mov_b32 m0, s36
	ds_read_b128 v[182:185], v203 offset:49152
	ds_read_b128 v[186:189], v203 offset:50176
	ds_read_b128 v[190:193], v203 offset:51200
	ds_read_b128 v[194:197], v203 offset:52224
	ds_read_b128 v[204:207], v203 offset:53248
	ds_read_b128 v[208:211], v203 offset:54272
	ds_read_b128 v[212:215], v203 offset:55296
	ds_read_b128 v[222:225], v203 offset:56320
	global_load_lds_dwordx4 v[168:169], off
	s_add_i32 m0, s36, 0x2000
	s_add_u32 s36, s58, 0x80080
	v_lshl_add_u64 v[168:169], v[170:171], 0, s[44:45]
	s_addc_u32 s37, s59, 0
	s_add_i32 s38, s39, s27
	global_load_lds_dwordx4 v[168:169], off
	v_lshl_add_u64 v[168:169], s[36:37], 0, v[162:163]
	s_mov_b32 m0, s38
	s_nop 0
	global_load_lds_dwordx4 v[168:169], off
	v_lshl_add_u64 v[168:169], s[36:37], 0, v[158:159]
	s_add_i32 m0, s38, 0x2000
	s_nop 0
	global_load_lds_dwordx4 v[168:169], off
	v_lshl_add_u64 v[168:169], v[198:199], 0, s[44:45]
	s_mov_b32 m0, s70
	s_nop 0
	global_load_lds_dwordx4 v[168:169], off
	v_lshl_add_u64 v[168:169], v[216:217], 0, s[44:45]
	s_mov_b32 m0, s71
	s_nop 0
	global_load_lds_dwordx4 v[168:169], off
	s_waitcnt vmcnt(8)
	s_waitcnt lgkmcnt(0)
	s_barrier
	v_mfma_f32_16x16x32_bf16 v[62:65], v[110:113], v[182:185], v[62:65]
	v_mfma_f32_16x16x32_bf16 v[58:61], v[138:141], v[182:185], v[58:61]
	v_mfma_f32_16x16x32_bf16 v[46:49], v[110:113], v[190:193], v[46:49]
	v_mfma_f32_16x16x32_bf16 v[42:45], v[138:141], v[190:193], v[42:45]
	v_mfma_f32_16x16x32_bf16 v[30:33], v[110:113], v[204:207], v[30:33]
	v_mfma_f32_16x16x32_bf16 v[26:29], v[138:141], v[204:207], v[26:29]
	v_mfma_f32_16x16x32_bf16 v[14:17], v[110:113], v[212:215], v[14:17]
	v_mfma_f32_16x16x32_bf16 v[10:13], v[138:141], v[212:215], v[10:13]
	v_mfma_f32_16x16x32_bf16 v[62:65], v[118:121], v[186:189], v[62:65]
	v_mfma_f32_16x16x32_bf16 v[58:61], v[142:145], v[186:189], v[58:61]
	v_mfma_f32_16x16x32_bf16 v[46:49], v[118:121], v[194:197], v[46:49]
	v_mfma_f32_16x16x32_bf16 v[42:45], v[142:145], v[194:197], v[42:45]
	v_mfma_f32_16x16x32_bf16 v[30:33], v[118:121], v[208:211], v[30:33]
	v_mfma_f32_16x16x32_bf16 v[26:29], v[142:145], v[208:211], v[26:29]
	v_mfma_f32_16x16x32_bf16 v[14:17], v[118:121], v[222:225], v[14:17]
	v_mfma_f32_16x16x32_bf16 v[10:13], v[142:145], v[222:225], v[10:13]
	v_mfma_f32_16x16x32_bf16 v[54:57], v[146:149], v[182:185], v[54:57]
	v_mfma_f32_16x16x32_bf16 v[50:53], v[174:177], v[182:185], v[50:53]
	v_mfma_f32_16x16x32_bf16 v[38:41], v[146:149], v[190:193], v[38:41]
	v_mfma_f32_16x16x32_bf16 v[34:37], v[174:177], v[190:193], v[34:37]
	v_mfma_f32_16x16x32_bf16 v[22:25], v[146:149], v[204:207], v[22:25]
	v_mfma_f32_16x16x32_bf16 v[18:21], v[174:177], v[204:207], v[18:21]
	v_mfma_f32_16x16x32_bf16 v[6:9], v[146:149], v[212:215], v[6:9]
	v_mfma_f32_16x16x32_bf16 v[2:5], v[174:177], v[212:215], v[2:5]
	v_mfma_f32_16x16x32_bf16 v[54:57], v[150:153], v[186:189], v[54:57]
	v_mfma_f32_16x16x32_bf16 v[50:53], v[178:181], v[186:189], v[50:53]
	v_mfma_f32_16x16x32_bf16 v[38:41], v[150:153], v[194:197], v[38:41]
	v_mfma_f32_16x16x32_bf16 v[34:37], v[178:181], v[194:197], v[34:37]
	v_mfma_f32_16x16x32_bf16 v[22:25], v[150:153], v[208:211], v[22:25]
	v_mfma_f32_16x16x32_bf16 v[18:21], v[178:181], v[208:211], v[18:21]
	v_mfma_f32_16x16x32_bf16 v[6:9], v[150:153], v[222:225], v[6:9]
	v_mfma_f32_16x16x32_bf16 v[2:5], v[178:181], v[222:225], v[2:5]
	s_barrier
	s_add_i32 s78, s78, 2
	s_add_u32 s25, s25, 0x100
	s_addc_u32 s62, s62, 0
	s_add_u32 s56, s56, 0x100
	s_addc_u32 s57, s57, 0
	s_cmp_gt_u32 s78, 29
	s_cbranch_scc0 .LBB0_1211
	s_and_b64 vcc, exec, s[18:19]
	s_cbranch_vccz .LBB0_1214
	s_barrier

.LBB0_1318:
	v_ashrrev_i32_e32 v3, 31, v143
	v_lshrrev_b32_e32 v3, 26, v3
	v_add_u32_e32 v3, v143, v3
	v_ashrrev_i32_e32 v10, 6, v3
	v_bfe_i32 v3, v143, 27, 1
	v_lshlrev_b32_e32 v2, 4, v143
	v_lshrrev_b32_e32 v3, 22, v3
	v_add_u32_e32 v3, v2, v3
	v_and_b32_e32 v3, 0xfffffc00, v3
	v_sub_u32_e32 v3, v2, v3
	s_add_u32 s65, s4, 0x69000000
	v_lshrrev_b32_e32 v4, 4, v3
	s_addc_u32 s66, s5, 0
	v_readlane_b32 s8, v255, 22
	v_bitop3_b32 v3, v4, v3, 32 bitop3:0x6c
	s_add_u32 s8, s4, s8
	v_ashrrev_i32_e32 v5, 31, v3
	s_addc_u32 s9, s5, s77
	v_lshrrev_b32_e32 v5, 26, v5
	s_add_u32 s67, s8, 0x8200000
	v_add_u32_e32 v5, v3, v5
	s_addc_u32 s68, s9, 0
	s_lshl_b64 s[8:9], s[20:21], 19
	v_lshlrev_b32_e32 v4, 3, v10
	v_ashrrev_i32_e32 v11, 6, v5
	v_and_b32_e32 v5, 0xc0, v5
	s_add_u32 s24, s65, s8
	v_and_b32_e32 v4, -16, v4
	v_sub_u32_e32 v3, v3, v5
	s_addc_u32 s25, s66, s9
	s_lshl_b64 s[8:9], s[22:23], 20
	v_add_u32_e32 v4, v11, v4
	v_ashrrev_i16_sdwa v3, v219, sext(v3) dst_sel:DWORD dst_unused:UNUSED_PAD src0_sel:DWORD src1_sel:BYTE_0
	s_add_u32 s26, s67, s8
	v_lshlrev_b32_e32 v6, 5, v10
	v_bfe_i32 v12, v3, 0, 16
	v_lshlrev_b32_e32 v3, 1, v4
	v_lshrrev_b32_e32 v5, 2, v4
	v_and_b32_e32 v7, 3, v11
	s_mov_b32 s8, 0xfffe0
	v_and_b32_e32 v6, 32, v6
	v_and_b32_e32 v3, 24, v3
	v_and_b32_e32 v5, 4, v5
	v_and_or_b32 v7, v4, s8, v7
	v_or3_b32 v3, v7, v5, v3
	v_add_lshl_u32 v5, v6, v12, 1
	v_add_u32_e32 v2, 0x2000, v2
	v_lshl_add_u32 v162, v3, 12, v5
	v_ashrrev_i32_e32 v3, 31, v2
	v_lshrrev_b32_e32 v3, 22, v3
	v_add_u32_e32 v3, v2, v3
	v_ashrrev_i32_e32 v13, 10, v3
	v_mul_i32_i24_e32 v3, 0x400, v13
	v_sub_u32_e32 v2, v2, v3
	v_lshrrev_b32_e32 v3, 4, v2
	v_bitop3_b32 v2, v3, v2, 32 bitop3:0x6c
	v_lshl_add_u32 v130, v4, 11, v5
	v_ashrrev_i32_e32 v4, 31, v2
	v_lshrrev_b32_e32 v4, 26, v4
	v_add_u32_e32 v4, v2, v4
	v_lshlrev_b32_e32 v3, 3, v13
	v_ashrrev_i32_e32 v14, 6, v4
	v_and_b32_e32 v4, 0xc0, v4
	v_and_b32_e32 v3, -16, v3
	v_sub_u32_e32 v2, v2, v4
	s_addc_u32 s27, s68, s9
	v_add_u32_e32 v3, v14, v3
	v_ashrrev_i16_sdwa v2, v219, sext(v2) dst_sel:DWORD dst_unused:UNUSED_PAD src0_sel:DWORD src1_sel:BYTE_0
	s_lshl_b32 s23, s12, 10
	v_lshlrev_b32_e32 v5, 5, v13
	v_bfe_i32 v15, v2, 0, 16
	v_lshlrev_b32_e32 v2, 1, v3
	v_lshrrev_b32_e32 v4, 2, v3
	v_and_b32_e32 v6, 3, v14
	s_add_i32 s69, s23, 0
	v_and_b32_e32 v5, 32, v5
	v_and_b32_e32 v2, 24, v2
	v_and_b32_e32 v4, 4, v4
	v_and_or_b32 v6, v3, s8, v6
	s_add_i32 m0, s69, 0x10000
	v_or3_b32 v2, v6, v4, v2
	v_add_lshl_u32 v4, v5, v15, 1
	s_ashr_i32 s10, s14, 8
	global_load_lds_dwordx4 v162, s[26:27]
	s_add_i32 m0, s69, 0x12000
	v_lshl_add_u32 v134, v2, 12, v4
	s_add_u32 s8, s26, 0x80000
	global_load_lds_dwordx4 v134, s[26:27]
	s_addc_u32 s9, s27, 0
	s_add_i32 m0, s69, 0x14000
	s_add_i32 s70, s69, 0x2000
	global_load_lds_dwordx4 v162, s[8:9]
	s_add_i32 m0, s69, 0x16000
	v_lshl_add_u32 v132, v3, 11, v4
	global_load_lds_dwordx4 v134, s[8:9]
	s_mov_b32 m0, s69
	s_add_u32 s8, s24, 0x40000
	global_load_lds_dwordx4 v130, s[24:25]
	s_mov_b32 m0, s70
	s_addc_u32 s9, s25, 0
	s_add_i32 s71, s69, 0x4000
	global_load_lds_dwordx4 v132, s[24:25]
	s_mov_b32 m0, s71
	s_add_i32 s72, s69, 0x6000
	global_load_lds_dwordx4 v130, s[8:9]
	s_mov_b32 m0, s72
	v_mov_b32_e32 v135, v163
	global_load_lds_dwordx4 v132, s[8:9]
	v_mov_b32_e32 v131, v163
	v_mov_b32_e32 v133, v163
	s_cmp_eq_u32 s10, 1
	v_lshl_add_u64 v[8:9], s[26:27], 0, v[162:163]
	v_lshl_add_u64 v[6:7], s[26:27], 0, v[134:135]
	v_lshl_add_u64 v[2:3], s[24:25], 0, v[130:131]
	s_cselect_b64 s[8:9], -1, 0
	s_cmp_lg_u32 s10, 1
	v_lshl_add_u64 v[4:5], s[24:25], 0, v[132:133]
	s_movk_i32 s31, 0x161
	s_cbranch_scc1 .LBB0_1320
.LBB0_1320:
	s_and_b32 s13, s12, 3
	s_add_i32 m0, s69, 0x18000
	v_lshl_add_u64 v[8:9], v[8:9], 0, s[44:45]
	s_lshl_b32 s15, s10, 6
	s_lshl_b32 s16, s10, 13
	s_lshl_b32 s17, s13, 12
	s_waitcnt vmcnt(2)
	s_barrier
	global_load_lds_dwordx4 v[8:9], off
	v_lshl_add_u64 v[6:7], v[6:7], 0, s[44:45]
	s_add_i32 m0, s69, 0x1a000
	s_add_i32 s73, s69, 0x8000
	s_add_i32 s74, s69, 0xa000
	global_load_lds_dwordx4 v[6:7], off
	v_lshl_add_u64 v[2:3], v[2:3], 0, s[44:45]
	s_mov_b32 m0, s73
	s_add_u32 s10, s26, 0x80080
	global_load_lds_dwordx4 v[2:3], off
	v_lshl_add_u64 v[2:3], v[4:5], 0, s[44:45]
	s_mov_b32 m0, s74
	s_addc_u32 s11, s27, 0
	global_load_lds_dwordx4 v[2:3], off
	s_add_i32 m0, s69, 0x1c000
	v_lshl_add_u64 v[2:3], s[10:11], 0, v[162:163]
	global_load_lds_dwordx4 v[2:3], off
	v_lshl_add_u64 v[2:3], s[10:11], 0, v[134:135]
	s_add_i32 m0, s69, 0x1e000
	s_and_b32 s10, s2, 7
	global_load_lds_dwordx4 v[2:3], off
	s_lshl_b32 s11, s10, 3
	s_ashr_i32 s76, s2, 6
	s_bfe_u32 s78, s2, 0x30003
	s_mul_i32 s10, s10, 44
	s_ashr_i32 s75, s2, 31
	s_add_i32 s77, s11, s76
	s_or_b32 s79, s11, s78
	s_lshr_b32 s80, s10, 3
	v_lshrrev_b32_e32 v4, 1, v143
	s_cmpk_lt_u32 s14, 0x100
	v_and_b32_e32 v159, 24, v4
	s_cselect_b64 s[10:11], -1, 0
	s_bfe_u32 s81, s12, 0x10001
	s_lshl_b32 s12, s12, 6
	v_and_b32_e32 v3, 15, v143
	v_lshlrev_b32_e32 v4, 1, v159
	v_lshlrev_b32_e32 v5, 2, v143
	s_ashr_i32 s14, s15, 31
	s_lshl_b32 s82, s13, 7
	s_and_b32 s12, s12, 64
	v_or_b32_e32 v2, s15, v3
	v_lshl_or_b32 v3, v3, 6, v4
	v_and_b32_e32 v5, 32, v5
	s_add_u32 s4, s4, s12
	v_bitop3_b32 v6, v3, s16, v5 bitop3:0xde
	v_bitop3_b32 v161, v3, s17, v5 bitop3:0xde
	v_mov_b32_e32 v3, s14
	s_addc_u32 s5, s5, 0
	v_mov_b32_e32 v5, v163
	v_lshlrev_b32_e32 v173, 3, v2
	v_lshl_add_u64 v[4:5], s[4:5], 0, v[4:5]
	v_lshlrev_b64 v[2:3], 7, v[2:3]
	v_lshl_add_u64 v[2:3], v[4:5], 0, v[2:3]
	s_mov_b64 s[4:5], 0x58000000
	v_lshl_add_u64 v[136:137], v[2:3], 0, s[4:5]
	v_lshlrev_b32_e32 v2, 14, v13
	v_and_b32_e32 v2, 0xffff8000, v2
	v_lshl_add_u32 v2, v14, 11, v2
	v_and_b32_e32 v3, 1, v13
	v_lshl_or_b32 v2, v3, 6, v2
	v_lshl_add_u32 v138, v15, 1, v2
	v_lshlrev_b32_e32 v2, 14, v10
	v_and_b32_e32 v2, 0xffff8000, v2
	s_waitcnt vmcnt(6)
	v_lshl_add_u32 v2, v11, 11, v2
	v_and_b32_e32 v3, 1, v10
	v_lshl_or_b32 v2, v3, 6, v2
	v_mov_b32_e32 v139, v163
	v_lshl_add_u32 v140, v12, 1, v2
	v_mov_b32_e32 v141, v163
	s_mov_b32 s84, 0
	v_add_u32_e32 v177, 0, v6
	s_mov_b32 s83, 0
	s_barrier
	s_branch .LBB0_1323

.Lrb_skip6:
.LBB0_1332:
	s_add_u32 s26, s24, 0xfffc0080
	s_addc_u32 s27, s25, -1
	s_add_i32 s36, 0, 0x10000
	s_cmp_eq_u32 s21, 12
	s_cselect_b32 s57, s17, s27
	s_cselect_b32 s56, s16, s26
	v_add_u32_e32 v142, s36, v161
	s_cselect_b32 s27, s19, s15
	s_cselect_b32 s26, s18, s13
	s_add_i32 s38, 0, 0x14000
	ds_read_b128 v[144:147], v142
	ds_read_b128 v[148:151], v142 offset:1024
	ds_read_b128 v[152:155], v142 offset:2048
	ds_read_b128 v[178:181], v142 offset:3072
	v_add_u32_e32 v142, s38, v161
	ds_read_b128 v[182:185], v142
	ds_read_b128 v[186:189], v142 offset:1024
	ds_read_b128 v[190:193], v142 offset:2048
	ds_read_b128 v[194:197], v142 offset:3072
	v_lshl_add_u64 v[156:157], s[24:25], 0, v[140:141]
	s_add_i32 m0, s69, 0xc000
	ds_read_b128 v[198:201], v177
	ds_read_b128 v[202:205], v177 offset:1024
	ds_read_b128 v[206:209], v177 offset:2048
	ds_read_b128 v[210:213], v177 offset:3072
	ds_read_b128 v[214:217], v177 offset:4096
	ds_read_b128 v[222:225], v177 offset:5120
	ds_read_b128 v[226:229], v177 offset:6144
	ds_read_b128 v[230:233], v177 offset:7168
	global_load_lds_dwordx4 v[156:157], off
	v_lshl_add_u64 v[156:157], s[24:25], 0, v[138:139]
	s_add_i32 m0, s69, 0xe000
	s_nop 0
	global_load_lds_dwordx4 v[156:157], off
	s_waitcnt vmcnt(8)
	s_waitcnt lgkmcnt(0)
	s_barrier
	v_mfma_i32_16x16x64_i8 v[126:129], v[144:147], v[198:201], v[126:129]
	v_mfma_i32_16x16x64_i8 v[118:121], v[152:155], v[198:201], v[118:121]
	v_mfma_i32_16x16x64_i8 v[110:113], v[144:147], v[206:209], v[110:113]
	v_mfma_i32_16x16x64_i8 v[102:105], v[152:155], v[206:209], v[102:105]
	v_mfma_i32_16x16x64_i8 v[94:97], v[144:147], v[214:217], v[94:97]
	v_mfma_i32_16x16x64_i8 v[86:89], v[152:155], v[214:217], v[86:89]
	v_mfma_i32_16x16x64_i8 v[78:81], v[144:147], v[226:229], v[78:81]
	v_mfma_i32_16x16x64_i8 v[70:73], v[152:155], v[226:229], v[70:73]
	v_mfma_i32_16x16x64_i8 v[126:129], v[148:151], v[202:205], v[126:129]
	v_mfma_i32_16x16x64_i8 v[118:121], v[178:181], v[202:205], v[118:121]
	v_mfma_i32_16x16x64_i8 v[110:113], v[148:151], v[210:213], v[110:113]
	v_mfma_i32_16x16x64_i8 v[102:105], v[178:181], v[210:213], v[102:105]
	v_mfma_i32_16x16x64_i8 v[94:97], v[148:151], v[222:225], v[94:97]
	v_mfma_i32_16x16x64_i8 v[86:89], v[178:181], v[222:225], v[86:89]
	v_mfma_i32_16x16x64_i8 v[78:81], v[148:151], v[230:233], v[78:81]
	v_mfma_i32_16x16x64_i8 v[70:73], v[178:181], v[230:233], v[70:73]
	v_mfma_i32_16x16x64_i8 v[122:125], v[182:185], v[198:201], v[122:125]
	v_mfma_i32_16x16x64_i8 v[114:117], v[190:193], v[198:201], v[114:117]
	v_mfma_i32_16x16x64_i8 v[106:109], v[182:185], v[206:209], v[106:109]
	v_mfma_i32_16x16x64_i8 v[98:101], v[190:193], v[206:209], v[98:101]
	v_mfma_i32_16x16x64_i8 v[90:93], v[182:185], v[214:217], v[90:93]
	v_mfma_i32_16x16x64_i8 v[82:85], v[190:193], v[214:217], v[82:85]
	v_mfma_i32_16x16x64_i8 v[74:77], v[182:185], v[226:229], v[74:77]
	v_mfma_i32_16x16x64_i8 v[66:69], v[190:193], v[226:229], v[66:69]
	v_mfma_i32_16x16x64_i8 v[122:125], v[186:189], v[202:205], v[122:125]
	v_mfma_i32_16x16x64_i8 v[114:117], v[194:197], v[202:205], v[114:117]
	v_mfma_i32_16x16x64_i8 v[106:109], v[186:189], v[210:213], v[106:109]
	v_mfma_i32_16x16x64_i8 v[98:101], v[194:197], v[210:213], v[98:101]
	v_mfma_i32_16x16x64_i8 v[90:93], v[186:189], v[222:225], v[90:93]
	v_mfma_i32_16x16x64_i8 v[82:85], v[194:197], v[222:225], v[82:85]
	v_mfma_i32_16x16x64_i8 v[74:77], v[186:189], v[230:233], v[74:77]
	v_mfma_i32_16x16x64_i8 v[66:69], v[194:197], v[230:233], v[66:69]
	s_barrier
	s_add_i32 s36, s36, s23
	v_lshl_add_u64 v[156:157], s[26:27], 0, v[162:163]
	s_mov_b32 m0, s36
	ds_read_b128 v[198:201], v177 offset:16384
	ds_read_b128 v[202:205], v177 offset:17408
	ds_read_b128 v[206:209], v177 offset:18432
	ds_read_b128 v[210:213], v177 offset:19456
	ds_read_b128 v[214:217], v177 offset:20480
	ds_read_b128 v[222:225], v177 offset:21504
	ds_read_b128 v[226:229], v177 offset:22528
	ds_read_b128 v[230:233], v177 offset:23552
	global_load_lds_dwordx4 v[156:157], off
	s_add_i32 m0, s36, 0x2000
	s_add_u32 s36, s26, 0x80000
	v_lshl_add_u64 v[168:169], s[26:27], 0, v[134:135]
	s_addc_u32 s37, s27, 0
	s_add_i32 s38, s38, s23
	global_load_lds_dwordx4 v[168:169], off
	v_lshl_add_u64 v[170:171], s[36:37], 0, v[162:163]
	s_mov_b32 m0, s38
	v_lshl_add_u64 v[174:175], s[56:57], 0, v[132:133]
	global_load_lds_dwordx4 v[170:171], off
	v_lshl_add_u64 v[170:171], s[36:37], 0, v[134:135]
	s_add_i32 m0, s38, 0x2000
	s_nop 0
	global_load_lds_dwordx4 v[170:171], off
	v_lshl_add_u64 v[170:171], s[56:57], 0, v[130:131]
	s_mov_b32 m0, s69
	s_nop 0
	global_load_lds_dwordx4 v[170:171], off
	s_mov_b32 m0, s70
	s_nop 0
	global_load_lds_dwordx4 v[174:175], off
	s_waitcnt vmcnt(8)
	s_waitcnt lgkmcnt(0)
	s_barrier
	v_mfma_i32_16x16x64_i8 v[62:65], v[144:147], v[198:201], v[62:65]
	v_mfma_i32_16x16x64_i8 v[54:57], v[152:155], v[198:201], v[54:57]
	v_mfma_i32_16x16x64_i8 v[46:49], v[144:147], v[206:209], v[46:49]
	v_mfma_i32_16x16x64_i8 v[38:41], v[152:155], v[206:209], v[38:41]
	v_mfma_i32_16x16x64_i8 v[30:33], v[144:147], v[214:217], v[30:33]
	v_mfma_i32_16x16x64_i8 v[22:25], v[152:155], v[214:217], v[22:25]
	v_mfma_i32_16x16x64_i8 v[14:17], v[144:147], v[226:229], v[14:17]
	v_mfma_i32_16x16x64_i8 v[6:9], v[152:155], v[226:229], v[6:9]
	v_mfma_i32_16x16x64_i8 v[62:65], v[148:151], v[202:205], v[62:65]
	v_mfma_i32_16x16x64_i8 v[54:57], v[178:181], v[202:205], v[54:57]
	v_mfma_i32_16x16x64_i8 v[46:49], v[148:151], v[210:213], v[46:49]
	v_mfma_i32_16x16x64_i8 v[38:41], v[178:181], v[210:213], v[38:41]
	v_mfma_i32_16x16x64_i8 v[30:33], v[148:151], v[222:225], v[30:33]
	v_mfma_i32_16x16x64_i8 v[22:25], v[178:181], v[222:225], v[22:25]
	v_mfma_i32_16x16x64_i8 v[14:17], v[148:151], v[230:233], v[14:17]
	v_mfma_i32_16x16x64_i8 v[6:9], v[178:181], v[230:233], v[6:9]
	v_mfma_i32_16x16x64_i8 v[58:61], v[182:185], v[198:201], v[58:61]
	v_mfma_i32_16x16x64_i8 v[50:53], v[190:193], v[198:201], v[50:53]
	v_mfma_i32_16x16x64_i8 v[42:45], v[182:185], v[206:209], v[42:45]
	v_mfma_i32_16x16x64_i8 v[34:37], v[190:193], v[206:209], v[34:37]
	v_mfma_i32_16x16x64_i8 v[26:29], v[182:185], v[214:217], v[26:29]
	v_mfma_i32_16x16x64_i8 v[18:21], v[190:193], v[214:217], v[18:21]
	v_mfma_i32_16x16x64_i8 v[10:13], v[182:185], v[226:229], v[10:13]
	v_mfma_i32_16x16x64_i8 v[2:5], v[190:193], v[226:229], v[2:5]
	v_mfma_i32_16x16x64_i8 v[58:61], v[186:189], v[202:205], v[58:61]
	v_mfma_i32_16x16x64_i8 v[50:53], v[194:197], v[202:205], v[50:53]
	v_mfma_i32_16x16x64_i8 v[42:45], v[186:189], v[210:213], v[42:45]
	v_mfma_i32_16x16x64_i8 v[34:37], v[194:197], v[210:213], v[34:37]
	v_mfma_i32_16x16x64_i8 v[26:29], v[186:189], v[222:225], v[26:29]
	v_mfma_i32_16x16x64_i8 v[18:21], v[194:197], v[222:225], v[18:21]
	v_mfma_i32_16x16x64_i8 v[10:13], v[186:189], v[230:233], v[10:13]
	v_mfma_i32_16x16x64_i8 v[2:5], v[194:197], v[230:233], v[2:5]
	s_barrier
	s_add_i32 s38, 0, 0x18000
	v_add_u32_e32 v142, s38, v161
	s_add_i32 s39, 0, 0x1c000
	ds_read_b128 v[144:147], v142
	ds_read_b128 v[148:151], v142 offset:1024
	ds_read_b128 v[152:155], v142 offset:2048
	ds_read_b128 v[178:181], v142 offset:3072
	v_add_u32_e32 v142, s39, v161
	ds_read_b128 v[182:185], v142
	ds_read_b128 v[186:189], v142 offset:1024
	ds_read_b128 v[190:193], v142 offset:2048
	ds_read_b128 v[194:197], v142 offset:3072
	s_add_u32 s36, s56, 0x40000
	s_addc_u32 s37, s57, 0
	s_mov_b32 m0, s71
	v_lshl_add_u64 v[234:235], s[36:37], 0, v[130:131]
	ds_read_b128 v[198:201], v177 offset:32768
	ds_read_b128 v[202:205], v177 offset:33792
	ds_read_b128 v[206:209], v177 offset:34816
	ds_read_b128 v[210:213], v177 offset:35840
	ds_read_b128 v[214:217], v177 offset:36864
	ds_read_b128 v[222:225], v177 offset:37888
	ds_read_b128 v[226:229], v177 offset:38912
	ds_read_b128 v[230:233], v177 offset:39936
	global_load_lds_dwordx4 v[234:235], off
	v_lshl_add_u64 v[234:235], s[36:37], 0, v[132:133]
	s_mov_b32 m0, s72
	s_nop 0
	global_load_lds_dwordx4 v[234:235], off
	s_waitcnt vmcnt(8)
	s_waitcnt lgkmcnt(0)
	s_barrier
	v_mfma_i32_16x16x64_i8 v[126:129], v[144:147], v[198:201], v[126:129]
	v_mfma_i32_16x16x64_i8 v[118:121], v[152:155], v[198:201], v[118:121]
	v_mfma_i32_16x16x64_i8 v[110:113], v[144:147], v[206:209], v[110:113]
	v_mfma_i32_16x16x64_i8 v[102:105], v[152:155], v[206:209], v[102:105]
	v_mfma_i32_16x16x64_i8 v[94:97], v[144:147], v[214:217], v[94:97]
	v_mfma_i32_16x16x64_i8 v[86:89], v[152:155], v[214:217], v[86:89]
	v_mfma_i32_16x16x64_i8 v[78:81], v[144:147], v[226:229], v[78:81]
	v_mfma_i32_16x16x64_i8 v[70:73], v[152:155], v[226:229], v[70:73]
	v_mfma_i32_16x16x64_i8 v[126:129], v[148:151], v[202:205], v[126:129]
	v_mfma_i32_16x16x64_i8 v[118:121], v[178:181], v[202:205], v[118:121]
	v_mfma_i32_16x16x64_i8 v[110:113], v[148:151], v[210:213], v[110:113]
	v_mfma_i32_16x16x64_i8 v[102:105], v[178:181], v[210:213], v[102:105]
	v_mfma_i32_16x16x64_i8 v[94:97], v[148:151], v[222:225], v[94:97]
	v_mfma_i32_16x16x64_i8 v[86:89], v[178:181], v[222:225], v[86:89]
	v_mfma_i32_16x16x64_i8 v[78:81], v[148:151], v[230:233], v[78:81]
	v_mfma_i32_16x16x64_i8 v[70:73], v[178:181], v[230:233], v[70:73]
	v_mfma_i32_16x16x64_i8 v[122:125], v[182:185], v[198:201], v[122:125]
	v_mfma_i32_16x16x64_i8 v[114:117], v[190:193], v[198:201], v[114:117]
	v_mfma_i32_16x16x64_i8 v[106:109], v[182:185], v[206:209], v[106:109]
	v_mfma_i32_16x16x64_i8 v[98:101], v[190:193], v[206:209], v[98:101]
	v_mfma_i32_16x16x64_i8 v[90:93], v[182:185], v[214:217], v[90:93]
	v_mfma_i32_16x16x64_i8 v[82:85], v[190:193], v[214:217], v[82:85]
	v_mfma_i32_16x16x64_i8 v[74:77], v[182:185], v[226:229], v[74:77]
	v_mfma_i32_16x16x64_i8 v[66:69], v[190:193], v[226:229], v[66:69]
	v_mfma_i32_16x16x64_i8 v[122:125], v[186:189], v[202:205], v[122:125]
	v_mfma_i32_16x16x64_i8 v[114:117], v[194:197], v[202:205], v[114:117]
	v_mfma_i32_16x16x64_i8 v[106:109], v[186:189], v[210:213], v[106:109]
	v_mfma_i32_16x16x64_i8 v[98:101], v[194:197], v[210:213], v[98:101]
	v_mfma_i32_16x16x64_i8 v[90:93], v[186:189], v[222:225], v[90:93]
	v_mfma_i32_16x16x64_i8 v[82:85], v[194:197], v[222:225], v[82:85]
	v_mfma_i32_16x16x64_i8 v[74:77], v[186:189], v[230:233], v[74:77]
	v_mfma_i32_16x16x64_i8 v[66:69], v[194:197], v[230:233], v[66:69]
	s_barrier
	s_add_i32 s36, s38, s23
	v_lshl_add_u64 v[156:157], v[156:157], 0, s[44:45]
	s_mov_b32 m0, s36
	ds_read_b128 v[198:201], v177 offset:49152
	ds_read_b128 v[202:205], v177 offset:50176
	ds_read_b128 v[206:209], v177 offset:51200
	ds_read_b128 v[210:213], v177 offset:52224
	ds_read_b128 v[214:217], v177 offset:53248
	ds_read_b128 v[222:225], v177 offset:54272
	ds_read_b128 v[226:229], v177 offset:55296
	ds_read_b128 v[230:233], v177 offset:56320
	global_load_lds_dwordx4 v[156:157], off
	s_add_i32 m0, s36, 0x2000
	s_add_u32 s26, s26, 0x80080
	v_lshl_add_u64 v[156:157], v[168:169], 0, s[44:45]
	s_addc_u32 s27, s27, 0
	s_add_i32 s36, s39, s23
	global_load_lds_dwordx4 v[156:157], off
	v_lshl_add_u64 v[156:157], s[26:27], 0, v[162:163]
	s_mov_b32 m0, s36
	s_nop 0
	global_load_lds_dwordx4 v[156:157], off
	v_lshl_add_u64 v[156:157], s[26:27], 0, v[134:135]
	s_add_i32 m0, s36, 0x2000
	s_nop 0
	global_load_lds_dwordx4 v[156:157], off
	v_lshl_add_u64 v[156:157], v[170:171], 0, s[44:45]
	s_mov_b32 m0, s73
	s_nop 0
	global_load_lds_dwordx4 v[156:157], off
	v_lshl_add_u64 v[156:157], v[174:175], 0, s[44:45]
	s_mov_b32 m0, s74
	s_nop 0
	global_load_lds_dwordx4 v[156:157], off
	s_waitcnt vmcnt(8)
	s_waitcnt lgkmcnt(0)
	s_barrier
	v_mfma_i32_16x16x64_i8 v[62:65], v[144:147], v[198:201], v[62:65]
	v_mfma_i32_16x16x64_i8 v[54:57], v[152:155], v[198:201], v[54:57]
	v_mfma_i32_16x16x64_i8 v[46:49], v[144:147], v[206:209], v[46:49]
	v_mfma_i32_16x16x64_i8 v[38:41], v[152:155], v[206:209], v[38:41]
	v_mfma_i32_16x16x64_i8 v[30:33], v[144:147], v[214:217], v[30:33]
	v_mfma_i32_16x16x64_i8 v[22:25], v[152:155], v[214:217], v[22:25]
	v_mfma_i32_16x16x64_i8 v[14:17], v[144:147], v[226:229], v[14:17]
	v_mfma_i32_16x16x64_i8 v[6:9], v[152:155], v[226:229], v[6:9]
	v_mfma_i32_16x16x64_i8 v[62:65], v[148:151], v[202:205], v[62:65]
	v_mfma_i32_16x16x64_i8 v[54:57], v[178:181], v[202:205], v[54:57]
	v_mfma_i32_16x16x64_i8 v[46:49], v[148:151], v[210:213], v[46:49]
	v_mfma_i32_16x16x64_i8 v[38:41], v[178:181], v[210:213], v[38:41]
	v_mfma_i32_16x16x64_i8 v[30:33], v[148:151], v[222:225], v[30:33]
	v_mfma_i32_16x16x64_i8 v[22:25], v[178:181], v[222:225], v[22:25]
	v_mfma_i32_16x16x64_i8 v[14:17], v[148:151], v[230:233], v[14:17]
	v_mfma_i32_16x16x64_i8 v[6:9], v[178:181], v[230:233], v[6:9]
	v_mfma_i32_16x16x64_i8 v[58:61], v[182:185], v[198:201], v[58:61]
	v_mfma_i32_16x16x64_i8 v[50:53], v[190:193], v[198:201], v[50:53]
	v_mfma_i32_16x16x64_i8 v[42:45], v[182:185], v[206:209], v[42:45]
	v_mfma_i32_16x16x64_i8 v[34:37], v[190:193], v[206:209], v[34:37]
	v_mfma_i32_16x16x64_i8 v[26:29], v[182:185], v[214:217], v[26:29]
	v_mfma_i32_16x16x64_i8 v[18:21], v[190:193], v[214:217], v[18:21]
	v_mfma_i32_16x16x64_i8 v[10:13], v[182:185], v[226:229], v[10:13]
	v_mfma_i32_16x16x64_i8 v[2:5], v[190:193], v[226:229], v[2:5]
	v_mfma_i32_16x16x64_i8 v[58:61], v[186:189], v[202:205], v[58:61]
	v_mfma_i32_16x16x64_i8 v[50:53], v[194:197], v[202:205], v[50:53]
	v_mfma_i32_16x16x64_i8 v[42:45], v[186:189], v[210:213], v[42:45]
	v_mfma_i32_16x16x64_i8 v[34:37], v[194:197], v[210:213], v[34:37]
	v_mfma_i32_16x16x64_i8 v[26:29], v[186:189], v[222:225], v[26:29]
	v_mfma_i32_16x16x64_i8 v[18:21], v[194:197], v[222:225], v[18:21]
	v_mfma_i32_16x16x64_i8 v[10:13], v[186:189], v[230:233], v[10:13]
	v_mfma_i32_16x16x64_i8 v[2:5], v[194:197], v[230:233], v[2:5]
	s_barrier
	s_add_i32 s21, s21, 2
	s_add_u32 s13, s13, 0x100
	s_addc_u32 s15, s15, 0
	s_add_u32 s24, s24, 0x100
	s_addc_u32 s25, s25, 0
	s_cmp_gt_u32 s21, 13
	s_cbranch_scc0 .LBB0_1332
	s_and_b64 vcc, exec, s[10:11]
	s_cbranch_vccz .LBB0_1335
	s_barrier

.LBB0_1427:
	v_readlane_b32 s8, v255, 23
	v_readlane_b32 s9, v255, 24
	s_or_b32 s8, s8, 0xc000
	s_mov_b32 s9, s55
	v_writelane_b32 v255, s8, 25
	s_and_b64 vcc, exec, s[4:5]
	s_nop 0
	v_writelane_b32 v255, s9, 26
	s_cbranch_vccnz .LBB0_1469
	v_ashrrev_i32_e32 v3, 31, v6
	v_lshrrev_b32_e32 v3, 26, v3
	v_add_u32_e32 v3, v6, v3
	v_ashrrev_i32_e32 v7, 6, v3
	v_bfe_i32 v3, v6, 27, 1
	v_lshlrev_b32_e32 v2, 4, v6
	v_lshrrev_b32_e32 v3, 22, v3
	v_add_u32_e32 v3, v2, v3
	v_and_b32_e32 v3, 0xfffffc00, v3
	v_sub_u32_e32 v3, v2, v3
	v_lshrrev_b32_e32 v4, 4, v3
	v_bitop3_b32 v3, v4, v3, 32 bitop3:0x6c
	v_ashrrev_i32_e32 v5, 31, v3
	v_lshrrev_b32_e32 v5, 26, v5
	v_add_u32_e32 v5, v3, v5
	v_ashrrev_i32_e32 v8, 6, v5
	v_and_b32_e32 v5, 0xc0, v5
	v_lshlrev_b32_e32 v4, 3, v7
	v_sub_u32_e32 v3, v3, v5
	v_and_b32_e32 v4, -16, v4
	v_lshlrev_b32_e32 v9, 5, v7
	v_ashrrev_i16_sdwa v3, v219, sext(v3) dst_sel:DWORD dst_unused:UNUSED_PAD src0_sel:DWORD src1_sel:BYTE_0
	v_add_u32_e32 v4, v8, v4
	v_and_b32_e32 v10, 32, v9
	v_bfe_i32 v9, v3, 0, 16
	v_add_u32_e32 v3, v10, v9
	v_lshlrev_b32_e32 v5, 1, v4
	v_lshrrev_b32_e32 v10, 2, v4
	v_and_b32_e32 v11, 3, v8
	s_mov_b32 s5, 0x7fffe0
	v_and_b32_e32 v5, 24, v5
	v_and_b32_e32 v10, 4, v10
	v_and_or_b32 v11, v4, s5, v11
	v_or3_b32 v5, v11, v10, v5
	v_lshlrev_b32_e32 v4, 7, v4
	v_lshl_add_u32 v154, v3, 1, v4
	v_mul_u32_u24_e32 v4, 0x1600, v5
	v_add_u32_e32 v2, 0x2000, v2
	v_add_lshl_u32 v162, v4, v3, 1
	v_ashrrev_i32_e32 v3, 31, v2
	v_lshrrev_b32_e32 v3, 22, v3
	v_add_u32_e32 v3, v2, v3
	v_ashrrev_i32_e32 v10, 10, v3
	v_mul_i32_i24_e32 v3, 0x400, v10
	v_sub_u32_e32 v2, v2, v3
	v_lshrrev_b32_e32 v3, 4, v2
	v_bitop3_b32 v2, v3, v2, 32 bitop3:0x6c
	v_ashrrev_i32_e32 v4, 31, v2
	v_lshrrev_b32_e32 v4, 26, v4
	v_add_u32_e32 v4, v2, v4
	v_lshlrev_b32_e32 v3, 3, v10
	v_ashrrev_i32_e32 v11, 6, v4
	v_and_b32_e32 v4, 0xc0, v4
	v_and_b32_e32 v3, -16, v3
	v_sub_u32_e32 v2, v2, v4
	v_add_u32_e32 v3, v11, v3
	v_lshlrev_b32_e32 v5, 5, v10
	v_ashrrev_i16_sdwa v2, v219, sext(v2) dst_sel:DWORD dst_unused:UNUSED_PAD src0_sel:DWORD src1_sel:BYTE_0
	v_and_b32_e32 v13, 3, v11
	v_and_b32_e32 v5, 32, v5
	v_bfe_i32 v12, v2, 0, 16
	v_and_or_b32 v13, v3, s5, v13
	s_ashr_i32 s5, s20, 6
	v_add_u32_e32 v2, v5, v12
	v_lshlrev_b32_e32 v4, 1, v3
	v_lshrrev_b32_e32 v5, 2, v3
	s_lshl_b32 s64, s5, 10
	v_and_b32_e32 v4, 24, v4
	v_and_b32_e32 v5, 4, v5
	s_add_i32 s65, s64, 0
	v_or3_b32 v4, v13, v5, v4
	v_lshlrev_b32_e32 v3, 7, v3
	s_add_i32 m0, s65, 0x10000
	s_ashr_i32 s4, s20, 8
	v_lshl_add_u32 v156, v2, 1, v3
	v_mul_u32_u24_e32 v3, 0x1600, v4
	global_load_lds_dwordx4 v162, s[56:57]
	s_add_i32 m0, s65, 0x12000
	v_add_lshl_u32 v158, v3, v2, 1
	s_add_u32 s8, s56, 0x160000
	global_load_lds_dwordx4 v158, s[56:57]
	s_addc_u32 s9, s57, 0
	s_add_i32 m0, s65, 0x14000
	s_add_i32 s66, s65, 0x2000
	global_load_lds_dwordx4 v162, s[8:9]
	s_add_i32 m0, s65, 0x16000
	v_mov_b32_e32 v159, v163
	global_load_lds_dwordx4 v158, s[8:9]
	s_mov_b32 m0, s65
	s_add_u32 s8, s26, 0x4000
	global_load_lds_dwordx4 v154, s[26:27]
	s_mov_b32 m0, s66
	s_addc_u32 s9, s27, 0
	s_add_i32 s67, s65, 0x4000
	global_load_lds_dwordx4 v156, s[26:27]
	s_mov_b32 m0, s67
	s_add_i32 s68, s65, 0x6000
	global_load_lds_dwordx4 v154, s[8:9]
	s_mov_b32 m0, s68
	s_cmp_eq_u32 s4, 1
	global_load_lds_dwordx4 v156, s[8:9]
	v_lshl_add_u64 v[2:3], s[56:57], 0, v[162:163]
	s_cselect_b64 s[10:11], -1, 0
	s_cmp_lg_u32 s4, 1
	v_lshl_add_u64 v[4:5], s[56:57], 0, v[158:159]
	s_cbranch_scc1 .LBB0_1430
.LBB0_1430:
	s_add_u32 s12, s6, 0x44000000
	s_addc_u32 s13, s7, 0
	v_readlane_b32 s8, v255, 25
	s_add_u32 s18, s6, 0x100000
	v_readlane_b32 s9, v255, 26
	s_addc_u32 s19, s7, 0
	s_lshl_b64 s[8:9], s[8:9], 3
	s_add_u32 s14, s18, s8
	s_addc_u32 s15, s19, s9
	s_add_u32 s16, s6, 0x67000000
	s_addc_u32 s17, s7, 0
	s_lshl_b64 s[6:7], s[54:55], 3
	v_bfe_u32 v14, v6, 4, 2
	s_add_u32 s18, s18, s6
	v_and_b32_e32 v13, 15, v6
	v_lshlrev_b32_e32 v15, 4, v14
	v_lshlrev_b32_e32 v6, 2, v6
	s_addc_u32 s19, s19, s7
	v_lshl_or_b32 v200, s4, 6, v13
	v_lshl_or_b32 v13, v13, 6, v15
	s_lshl_b32 s4, s4, 13
	v_and_b32_e32 v6, 32, v6
	v_bitop3_b32 v15, v13, s4, v6 bitop3:0xde
	s_lshl_b32 s4, s5, 5
	s_and_b32 s6, s4, 0x60
	s_add_i32 m0, s65, 0x18000
	v_lshl_add_u64 v[2:3], v[2:3], 0, s[44:45]
	s_lshl_b32 s4, s6, 7
	s_waitcnt vmcnt(2)
	s_barrier
	global_load_lds_dwordx4 v[2:3], off
	s_add_i32 m0, s65, 0x1a000
	v_bitop3_b32 v201, v13, s4, v6 bitop3:0xde
	s_add_u32 s4, s26, 0x8000
	v_mov_b32_e32 v155, v163
	v_lshl_add_u64 v[2:3], v[4:5], 0, s[44:45]
	s_addc_u32 s5, s27, 0
	s_add_i32 s69, s65, 0x8000
	v_mov_b32_e32 v157, v163
	global_load_lds_dwordx4 v[2:3], off
	v_lshl_add_u64 v[2:3], s[4:5], 0, v[154:155]
	s_mov_b32 m0, s69
	s_add_i32 s70, s65, 0xa000
	global_load_lds_dwordx4 v[2:3], off
	v_lshl_add_u64 v[2:3], s[4:5], 0, v[156:157]
	s_add_u32 s4, s56, 0x160080
	s_mov_b32 m0, s70
	s_addc_u32 s5, s57, 0
	global_load_lds_dwordx4 v[2:3], off
	s_add_i32 m0, s65, 0x1c000
	v_lshl_add_u64 v[2:3], s[4:5], 0, v[162:163]
	global_load_lds_dwordx4 v[2:3], off
	v_lshl_add_u64 v[2:3], s[4:5], 0, v[158:159]
	s_add_i32 m0, s65, 0x1e000
	s_and_b32 s72, s2, 7
	global_load_lds_dwordx4 v[2:3], off
	v_lshlrev_b32_e32 v2, 10, v10
	v_and_b32_e32 v2, 0xfffff800, v2
	v_lshl_add_u32 v2, v11, 7, v2
	v_and_b32_e32 v3, 1, v10
	v_lshl_or_b32 v2, v3, 6, v2
	v_lshl_add_u32 v160, v12, 1, v2
	v_lshlrev_b32_e32 v2, 10, v7
	s_lshl_b32 s4, s72, 3
	s_ashr_i32 s73, s2, 6
	s_bfe_u32 s75, s2, 0x30003
	v_and_b32_e32 v2, 0xfffff800, v2
	s_waitcnt vmcnt(6)
	s_ashr_i32 s71, s2, 31
	s_add_i32 s74, s4, s73
	s_or_b32 s76, s4, s75
	v_lshl_add_u32 v2, v8, 7, v2
	v_and_b32_e32 v3, 1, v7
	s_cmpk_lt_u32 s20, 0x100
	v_lshl_or_b32 v2, v3, 6, v2
	s_cselect_b64 s[20:21], -1, 0
	s_mov_b32 s77, 0
	v_cmp_eq_u32_e64 s[4:5], 0, v14
	v_lshl_or_b32 v202, v14, 3, s6
	v_mov_b32_e32 v161, v163
	v_lshl_add_u32 v172, v9, 1, v2
	v_mov_b32_e32 v173, v163
	v_add_u32_e32 v203, 0, v15
	s_barrier
	s_branch .LBB0_1433

.LBB0_1445:
	s_add_u32 s26, s26, 0xc000
	s_addc_u32 s27, s27, 0
	s_add_u32 s82, s56, 0x100
	v_mov_b32_e32 v2, 0
	s_addc_u32 s83, s57, 0
	s_mov_b32 s84, -2
	s_waitcnt lgkmcnt(0)
	v_mov_b32_e32 v3, v2
	v_mov_b32_e32 v4, v2
	v_mov_b32_e32 v5, v2
	v_mov_b32_e32 v6, v2
	v_mov_b32_e32 v7, v2
	v_mov_b32_e32 v8, v2
	v_mov_b32_e32 v9, v2
	v_mov_b32_e32 v18, v2
	v_mov_b32_e32 v19, v2
	v_mov_b32_e32 v20, v2
	v_mov_b32_e32 v21, v2
	v_mov_b32_e32 v22, v2
	v_mov_b32_e32 v23, v2
	v_mov_b32_e32 v24, v2
	v_mov_b32_e32 v25, v2
	v_mov_b32_e32 v34, v2
	v_mov_b32_e32 v35, v2
	v_mov_b32_e32 v36, v2
	v_mov_b32_e32 v37, v2
	v_mov_b32_e32 v38, v2
	v_mov_b32_e32 v39, v2
	v_mov_b32_e32 v40, v2
	v_mov_b32_e32 v41, v2
	v_mov_b32_e32 v50, v2
	v_mov_b32_e32 v51, v2
	v_mov_b32_e32 v52, v2
	v_mov_b32_e32 v53, v2
	v_mov_b32_e32 v54, v2
	v_mov_b32_e32 v55, v2
	v_mov_b32_e32 v56, v2
	v_mov_b32_e32 v57, v2
	v_mov_b32_e32 v10, v2
	v_mov_b32_e32 v11, v2
	v_mov_b32_e32 v12, v2
	v_mov_b32_e32 v13, v2
	v_mov_b32_e32 v14, v2
	v_mov_b32_e32 v15, v2
	v_mov_b32_e32 v16, v2
	v_mov_b32_e32 v17, v2
	v_mov_b32_e32 v26, v2
	v_mov_b32_e32 v27, v2
	v_mov_b32_e32 v28, v2
	v_mov_b32_e32 v29, v2
	v_mov_b32_e32 v30, v2
	v_mov_b32_e32 v31, v2
	v_mov_b32_e32 v32, v2
	v_mov_b32_e32 v33, v2
	v_mov_b32_e32 v42, v2
	v_mov_b32_e32 v43, v2
	v_mov_b32_e32 v44, v2
	v_mov_b32_e32 v45, v2
	v_mov_b32_e32 v46, v2
	v_mov_b32_e32 v47, v2
	v_mov_b32_e32 v48, v2
	v_mov_b32_e32 v49, v2
	v_mov_b32_e32 v58, v2
	v_mov_b32_e32 v59, v2
	v_mov_b32_e32 v60, v2
	v_mov_b32_e32 v61, v2
	v_mov_b32_e32 v62, v2
	v_mov_b32_e32 v63, v2
	v_mov_b32_e32 v64, v2
	v_mov_b32_e32 v65, v2
	v_mov_b32_e32 v66, v2
	v_mov_b32_e32 v67, v2
	v_mov_b32_e32 v68, v2
	v_mov_b32_e32 v69, v2
	v_mov_b32_e32 v70, v2
	v_mov_b32_e32 v71, v2
	v_mov_b32_e32 v72, v2
	v_mov_b32_e32 v73, v2
	v_mov_b32_e32 v82, v2
	v_mov_b32_e32 v83, v2
	v_mov_b32_e32 v84, v2
	v_mov_b32_e32 v85, v2
	v_mov_b32_e32 v86, v2
	v_mov_b32_e32 v87, v2
	v_mov_b32_e32 v88, v2
	v_mov_b32_e32 v89, v2
	v_mov_b32_e32 v98, v2
	v_mov_b32_e32 v99, v2
	v_mov_b32_e32 v100, v2
	v_mov_b32_e32 v101, v2
	v_mov_b32_e32 v102, v2
	v_mov_b32_e32 v103, v2
	v_mov_b32_e32 v104, v2
	v_mov_b32_e32 v105, v2
	v_mov_b32_e32 v122, v2
	v_mov_b32_e32 v123, v2
	v_mov_b32_e32 v124, v2
	v_mov_b32_e32 v125, v2
	v_mov_b32_e32 v126, v2
	v_mov_b32_e32 v127, v2
	v_mov_b32_e32 v128, v2
	v_mov_b32_e32 v129, v2
	v_mov_b32_e32 v74, v2
	v_mov_b32_e32 v75, v2
	v_mov_b32_e32 v76, v2
	v_mov_b32_e32 v77, v2
	v_mov_b32_e32 v78, v2
	v_mov_b32_e32 v79, v2
	v_mov_b32_e32 v80, v2
	v_mov_b32_e32 v81, v2
	v_mov_b32_e32 v90, v2
	v_mov_b32_e32 v91, v2
	v_mov_b32_e32 v92, v2
	v_mov_b32_e32 v93, v2
	v_mov_b32_e32 v94, v2
	v_mov_b32_e32 v95, v2
	v_mov_b32_e32 v96, v2
	v_mov_b32_e32 v97, v2
	v_mov_b32_e32 v106, v2
	v_mov_b32_e32 v107, v2
	v_mov_b32_e32 v108, v2
	v_mov_b32_e32 v109, v2
	v_mov_b32_e32 v114, v2
	v_mov_b32_e32 v115, v2
	v_mov_b32_e32 v116, v2
	v_mov_b32_e32 v117, v2
	v_mov_b32_e32 v130, v2
	v_mov_b32_e32 v131, v2
	v_mov_b32_e32 v132, v2
	v_mov_b32_e32 v133, v2
	v_mov_b32_e32 v134, v2
	v_mov_b32_e32 v135, v2
	v_mov_b32_e32 v136, v2
	v_mov_b32_e32 v137, v2
	v_readfirstlane_b32 s100, v0
	s_nop 3
	s_bitcmp1_b32 s100, 8
	s_cbranch_scc0 .Lrb_skip7
	s_barrier
.Lrb_skip7:
.LBB0_1446:
	s_add_u32 s8, s26, 0x4000
	s_addc_u32 s9, s27, 0
	s_cmpk_eq_i32 s84, 0x54
	s_cselect_b32 s60, s22, s8
	s_cselect_b32 s61, s23, s9
	s_cselect_b32 s58, s24, s82
	s_cselect_b32 s59, s25, s83
	s_add_u32 s56, s60, 0x8000
	s_addc_u32 s57, s61, 0
	s_add_i32 s8, 0, 0x10000
	s_add_i32 s36, 0, 0x14000
	v_add_u32_e32 v142, s8, v201
	v_add_u32_e32 v168, s36, v201
	ds_read_b128 v[110:113], v142
	ds_read_b128 v[118:121], v142 offset:1024
	ds_read_b128 v[138:141], v142 offset:2048
	ds_read_b128 v[142:145], v142 offset:3072
	ds_read_b128 v[146:149], v168
	ds_read_b128 v[150:153], v168 offset:1024
	ds_read_b128 v[174:177], v168 offset:2048
	ds_read_b128 v[178:181], v168 offset:3072
	v_lshl_add_u64 v[168:169], s[26:27], 0, v[172:173]
	s_add_i32 m0, s65, 0xc000
	ds_read_b128 v[182:185], v203
	ds_read_b128 v[186:189], v203 offset:1024
	ds_read_b128 v[190:193], v203 offset:2048
	ds_read_b128 v[194:197], v203 offset:3072
	ds_read_b128 v[204:207], v203 offset:4096
	ds_read_b128 v[208:211], v203 offset:5120
	ds_read_b128 v[212:215], v203 offset:6144
	ds_read_b128 v[222:225], v203 offset:7168
	global_load_lds_dwordx4 v[168:169], off
	v_lshl_add_u64 v[168:169], s[26:27], 0, v[160:161]
	s_add_i32 m0, s65, 0xe000
	s_nop 0
	global_load_lds_dwordx4 v[168:169], off
	s_waitcnt vmcnt(8)
	s_waitcnt lgkmcnt(0)
	s_barrier
	v_mfma_f32_16x16x32_bf16 v[134:137], v[110:113], v[182:185], v[134:137]
	v_mfma_f32_16x16x32_bf16 v[130:133], v[138:141], v[182:185], v[130:133]
	v_mfma_f32_16x16x32_bf16 v[114:117], v[110:113], v[190:193], v[114:117]
	v_mfma_f32_16x16x32_bf16 v[106:109], v[138:141], v[190:193], v[106:109]
	v_mfma_f32_16x16x32_bf16 v[94:97], v[110:113], v[204:207], v[94:97]
	v_mfma_f32_16x16x32_bf16 v[90:93], v[138:141], v[204:207], v[90:93]
	v_mfma_f32_16x16x32_bf16 v[78:81], v[110:113], v[212:215], v[78:81]
	v_mfma_f32_16x16x32_bf16 v[74:77], v[138:141], v[212:215], v[74:77]
	v_mfma_f32_16x16x32_bf16 v[134:137], v[118:121], v[186:189], v[134:137]
	v_mfma_f32_16x16x32_bf16 v[130:133], v[142:145], v[186:189], v[130:133]
	v_mfma_f32_16x16x32_bf16 v[114:117], v[118:121], v[194:197], v[114:117]
	v_mfma_f32_16x16x32_bf16 v[106:109], v[142:145], v[194:197], v[106:109]
	v_mfma_f32_16x16x32_bf16 v[94:97], v[118:121], v[208:211], v[94:97]
	v_mfma_f32_16x16x32_bf16 v[90:93], v[142:145], v[208:211], v[90:93]
	v_mfma_f32_16x16x32_bf16 v[78:81], v[118:121], v[222:225], v[78:81]
	v_mfma_f32_16x16x32_bf16 v[74:77], v[142:145], v[222:225], v[74:77]
	v_mfma_f32_16x16x32_bf16 v[126:129], v[146:149], v[182:185], v[126:129]
	v_mfma_f32_16x16x32_bf16 v[122:125], v[174:177], v[182:185], v[122:125]
	v_mfma_f32_16x16x32_bf16 v[102:105], v[146:149], v[190:193], v[102:105]
	v_mfma_f32_16x16x32_bf16 v[98:101], v[174:177], v[190:193], v[98:101]
	v_mfma_f32_16x16x32_bf16 v[86:89], v[146:149], v[204:207], v[86:89]
	v_mfma_f32_16x16x32_bf16 v[82:85], v[174:177], v[204:207], v[82:85]
	v_mfma_f32_16x16x32_bf16 v[70:73], v[146:149], v[212:215], v[70:73]
	v_mfma_f32_16x16x32_bf16 v[66:69], v[174:177], v[212:215], v[66:69]
	v_mfma_f32_16x16x32_bf16 v[126:129], v[150:153], v[186:189], v[126:129]
	v_mfma_f32_16x16x32_bf16 v[122:125], v[178:181], v[186:189], v[122:125]
	v_mfma_f32_16x16x32_bf16 v[102:105], v[150:153], v[194:197], v[102:105]
	v_mfma_f32_16x16x32_bf16 v[98:101], v[178:181], v[194:197], v[98:101]
	v_mfma_f32_16x16x32_bf16 v[86:89], v[150:153], v[208:211], v[86:89]
	v_mfma_f32_16x16x32_bf16 v[82:85], v[178:181], v[208:211], v[82:85]
	v_mfma_f32_16x16x32_bf16 v[70:73], v[150:153], v[222:225], v[70:73]
	v_mfma_f32_16x16x32_bf16 v[66:69], v[178:181], v[222:225], v[66:69]
	s_barrier
	s_add_i32 s8, s8, s64
	v_lshl_add_u64 v[168:169], s[58:59], 0, v[162:163]
	s_mov_b32 m0, s8
	ds_read_b128 v[182:185], v203 offset:16384
	ds_read_b128 v[186:189], v203 offset:17408
	ds_read_b128 v[190:193], v203 offset:18432
	ds_read_b128 v[194:197], v203 offset:19456
	ds_read_b128 v[204:207], v203 offset:20480
	ds_read_b128 v[208:211], v203 offset:21504
	ds_read_b128 v[212:215], v203 offset:22528
	ds_read_b128 v[222:225], v203 offset:23552
	global_load_lds_dwordx4 v[168:169], off
	s_add_i32 m0, s8, 0x2000
	s_add_u32 s8, s58, 0x160000
	v_lshl_add_u64 v[170:171], s[58:59], 0, v[158:159]
	s_addc_u32 s9, s59, 0
	s_add_i32 s36, s36, s64
	global_load_lds_dwordx4 v[170:171], off
	v_lshl_add_u64 v[198:199], s[8:9], 0, v[162:163]
	s_mov_b32 m0, s36
	s_nop 0
	global_load_lds_dwordx4 v[198:199], off
	v_lshl_add_u64 v[198:199], s[8:9], 0, v[158:159]
	s_add_i32 m0, s36, 0x2000
	s_nop 0
	global_load_lds_dwordx4 v[198:199], off
	v_lshl_add_u64 v[198:199], s[60:61], 0, v[154:155]
	s_mov_b32 m0, s65
	s_nop 0
	global_load_lds_dwordx4 v[198:199], off
	v_lshl_add_u64 v[198:199], s[60:61], 0, v[156:157]
	s_mov_b32 m0, s66
	s_nop 0
	global_load_lds_dwordx4 v[198:199], off
	s_waitcnt vmcnt(8)
	s_waitcnt lgkmcnt(0)
	s_barrier
	v_mfma_f32_16x16x32_bf16 v[62:65], v[110:113], v[182:185], v[62:65]
	v_mfma_f32_16x16x32_bf16 v[58:61], v[138:141], v[182:185], v[58:61]
	v_mfma_f32_16x16x32_bf16 v[46:49], v[110:113], v[190:193], v[46:49]
	v_mfma_f32_16x16x32_bf16 v[42:45], v[138:141], v[190:193], v[42:45]
	v_mfma_f32_16x16x32_bf16 v[30:33], v[110:113], v[204:207], v[30:33]
	v_mfma_f32_16x16x32_bf16 v[26:29], v[138:141], v[204:207], v[26:29]
	v_mfma_f32_16x16x32_bf16 v[14:17], v[110:113], v[212:215], v[14:17]
	v_mfma_f32_16x16x32_bf16 v[10:13], v[138:141], v[212:215], v[10:13]
	v_mfma_f32_16x16x32_bf16 v[62:65], v[118:121], v[186:189], v[62:65]
	v_mfma_f32_16x16x32_bf16 v[58:61], v[142:145], v[186:189], v[58:61]
	v_mfma_f32_16x16x32_bf16 v[46:49], v[118:121], v[194:197], v[46:49]
	v_mfma_f32_16x16x32_bf16 v[42:45], v[142:145], v[194:197], v[42:45]
	v_mfma_f32_16x16x32_bf16 v[30:33], v[118:121], v[208:211], v[30:33]
	v_mfma_f32_16x16x32_bf16 v[26:29], v[142:145], v[208:211], v[26:29]
	v_mfma_f32_16x16x32_bf16 v[14:17], v[118:121], v[222:225], v[14:17]
	v_mfma_f32_16x16x32_bf16 v[10:13], v[142:145], v[222:225], v[10:13]
	v_mfma_f32_16x16x32_bf16 v[54:57], v[146:149], v[182:185], v[54:57]
	v_mfma_f32_16x16x32_bf16 v[50:53], v[174:177], v[182:185], v[50:53]
	v_mfma_f32_16x16x32_bf16 v[38:41], v[146:149], v[190:193], v[38:41]
	v_mfma_f32_16x16x32_bf16 v[34:37], v[174:177], v[190:193], v[34:37]
	v_mfma_f32_16x16x32_bf16 v[22:25], v[146:149], v[204:207], v[22:25]
	v_mfma_f32_16x16x32_bf16 v[18:21], v[174:177], v[204:207], v[18:21]
	v_mfma_f32_16x16x32_bf16 v[6:9], v[146:149], v[212:215], v[6:9]
	v_mfma_f32_16x16x32_bf16 v[2:5], v[174:177], v[212:215], v[2:5]
	v_mfma_f32_16x16x32_bf16 v[54:57], v[150:153], v[186:189], v[54:57]
	v_mfma_f32_16x16x32_bf16 v[50:53], v[178:181], v[186:189], v[50:53]
	v_mfma_f32_16x16x32_bf16 v[38:41], v[150:153], v[194:197], v[38:41]
	v_mfma_f32_16x16x32_bf16 v[34:37], v[178:181], v[194:197], v[34:37]
	v_mfma_f32_16x16x32_bf16 v[22:25], v[150:153], v[208:211], v[22:25]
	v_mfma_f32_16x16x32_bf16 v[18:21], v[178:181], v[208:211], v[18:21]
	v_mfma_f32_16x16x32_bf16 v[6:9], v[150:153], v[222:225], v[6:9]
	v_mfma_f32_16x16x32_bf16 v[2:5], v[178:181], v[222:225], v[2:5]
	s_barrier
	s_add_i32 s36, 0, 0x18000
	s_add_i32 s37, 0, 0x1c000
	v_add_u32_e32 v142, s36, v201
	v_add_u32_e32 v178, s37, v201
	ds_read_b128 v[110:113], v142
	ds_read_b128 v[118:121], v142 offset:1024
	ds_read_b128 v[138:141], v142 offset:2048
	ds_read_b128 v[142:145], v142 offset:3072
	ds_read_b128 v[146:149], v178
	ds_read_b128 v[150:153], v178 offset:1024
	ds_read_b128 v[174:177], v178 offset:2048
	ds_read_b128 v[178:181], v178 offset:3072
	s_add_u32 s8, s60, 0x4000
	s_addc_u32 s9, s61, 0
	s_mov_b32 m0, s67
	v_lshl_add_u64 v[198:199], s[8:9], 0, v[154:155]
	ds_read_b128 v[182:185], v203 offset:32768
	ds_read_b128 v[186:189], v203 offset:33792
	ds_read_b128 v[190:193], v203 offset:34816
	ds_read_b128 v[194:197], v203 offset:35840
	ds_read_b128 v[204:207], v203 offset:36864
	ds_read_b128 v[208:211], v203 offset:37888
	ds_read_b128 v[212:215], v203 offset:38912
	ds_read_b128 v[222:225], v203 offset:39936
	global_load_lds_dwordx4 v[198:199], off
	v_lshl_add_u64 v[198:199], s[8:9], 0, v[156:157]
	s_mov_b32 m0, s68
	s_nop 0
	global_load_lds_dwordx4 v[198:199], off
	s_waitcnt vmcnt(8)
	s_waitcnt lgkmcnt(0)
	s_barrier
	v_mfma_f32_16x16x32_bf16 v[134:137], v[110:113], v[182:185], v[134:137]
	v_mfma_f32_16x16x32_bf16 v[130:133], v[138:141], v[182:185], v[130:133]
	v_mfma_f32_16x16x32_bf16 v[114:117], v[110:113], v[190:193], v[114:117]
	v_mfma_f32_16x16x32_bf16 v[106:109], v[138:141], v[190:193], v[106:109]
	v_mfma_f32_16x16x32_bf16 v[94:97], v[110:113], v[204:207], v[94:97]
	v_mfma_f32_16x16x32_bf16 v[90:93], v[138:141], v[204:207], v[90:93]
	v_mfma_f32_16x16x32_bf16 v[78:81], v[110:113], v[212:215], v[78:81]
	v_mfma_f32_16x16x32_bf16 v[74:77], v[138:141], v[212:215], v[74:77]
	v_mfma_f32_16x16x32_bf16 v[134:137], v[118:121], v[186:189], v[134:137]
	v_mfma_f32_16x16x32_bf16 v[130:133], v[142:145], v[186:189], v[130:133]
	v_mfma_f32_16x16x32_bf16 v[114:117], v[118:121], v[194:197], v[114:117]
	v_mfma_f32_16x16x32_bf16 v[106:109], v[142:145], v[194:197], v[106:109]
	v_mfma_f32_16x16x32_bf16 v[94:97], v[118:121], v[208:211], v[94:97]
	v_mfma_f32_16x16x32_bf16 v[90:93], v[142:145], v[208:211], v[90:93]
	v_mfma_f32_16x16x32_bf16 v[78:81], v[118:121], v[222:225], v[78:81]
	v_mfma_f32_16x16x32_bf16 v[74:77], v[142:145], v[222:225], v[74:77]
	v_mfma_f32_16x16x32_bf16 v[126:129], v[146:149], v[182:185], v[126:129]
	v_mfma_f32_16x16x32_bf16 v[122:125], v[174:177], v[182:185], v[122:125]
	v_mfma_f32_16x16x32_bf16 v[102:105], v[146:149], v[190:193], v[102:105]
	v_mfma_f32_16x16x32_bf16 v[98:101], v[174:177], v[190:193], v[98:101]
	v_mfma_f32_16x16x32_bf16 v[86:89], v[146:149], v[204:207], v[86:89]
	v_mfma_f32_16x16x32_bf16 v[82:85], v[174:177], v[204:207], v[82:85]
	v_mfma_f32_16x16x32_bf16 v[70:73], v[146:149], v[212:215], v[70:73]
	v_mfma_f32_16x16x32_bf16 v[66:69], v[174:177], v[212:215], v[66:69]
	v_mfma_f32_16x16x32_bf16 v[126:129], v[150:153], v[186:189], v[126:129]
	v_mfma_f32_16x16x32_bf16 v[122:125], v[178:181], v[186:189], v[122:125]
	v_mfma_f32_16x16x32_bf16 v[102:105], v[150:153], v[194:197], v[102:105]
	v_mfma_f32_16x16x32_bf16 v[98:101], v[178:181], v[194:197], v[98:101]
	v_mfma_f32_16x16x32_bf16 v[86:89], v[150:153], v[208:211], v[86:89]
	v_mfma_f32_16x16x32_bf16 v[82:85], v[178:181], v[208:211], v[82:85]
	v_mfma_f32_16x16x32_bf16 v[70:73], v[150:153], v[222:225], v[70:73]
	v_mfma_f32_16x16x32_bf16 v[66:69], v[178:181], v[222:225], v[66:69]
	s_barrier
	s_add_i32 s8, s36, s64
	v_lshl_add_u64 v[168:169], v[168:169], 0, s[44:45]
	s_mov_b32 m0, s8
	ds_read_b128 v[182:185], v203 offset:49152
	ds_read_b128 v[186:189], v203 offset:50176
	ds_read_b128 v[190:193], v203 offset:51200
	ds_read_b128 v[194:197], v203 offset:52224
	ds_read_b128 v[204:207], v203 offset:53248
	ds_read_b128 v[208:211], v203 offset:54272
	ds_read_b128 v[212:215], v203 offset:55296
	ds_read_b128 v[222:225], v203 offset:56320
	global_load_lds_dwordx4 v[168:169], off
	s_add_i32 m0, s8, 0x2000
	s_add_u32 s8, s58, 0x160080
	v_lshl_add_u64 v[168:169], v[170:171], 0, s[44:45]
	s_addc_u32 s9, s59, 0
	s_add_i32 s36, s37, s64
	global_load_lds_dwordx4 v[168:169], off
	v_lshl_add_u64 v[168:169], s[8:9], 0, v[162:163]
	s_mov_b32 m0, s36
	s_nop 0
	global_load_lds_dwordx4 v[168:169], off
	v_lshl_add_u64 v[168:169], s[8:9], 0, v[158:159]
	s_add_i32 m0, s36, 0x2000
	s_nop 0
	global_load_lds_dwordx4 v[168:169], off
	v_lshl_add_u64 v[168:169], s[56:57], 0, v[154:155]
	s_mov_b32 m0, s69
	s_nop 0
	global_load_lds_dwordx4 v[168:169], off
	v_lshl_add_u64 v[168:169], s[56:57], 0, v[156:157]
	s_mov_b32 m0, s70
	s_nop 0
	global_load_lds_dwordx4 v[168:169], off
	s_waitcnt vmcnt(8)
	s_waitcnt lgkmcnt(0)
	s_barrier
	v_mfma_f32_16x16x32_bf16 v[62:65], v[110:113], v[182:185], v[62:65]
	v_mfma_f32_16x16x32_bf16 v[58:61], v[138:141], v[182:185], v[58:61]
	v_mfma_f32_16x16x32_bf16 v[46:49], v[110:113], v[190:193], v[46:49]
	v_mfma_f32_16x16x32_bf16 v[42:45], v[138:141], v[190:193], v[42:45]
	v_mfma_f32_16x16x32_bf16 v[30:33], v[110:113], v[204:207], v[30:33]
	v_mfma_f32_16x16x32_bf16 v[26:29], v[138:141], v[204:207], v[26:29]
	v_mfma_f32_16x16x32_bf16 v[14:17], v[110:113], v[212:215], v[14:17]
	v_mfma_f32_16x16x32_bf16 v[10:13], v[138:141], v[212:215], v[10:13]
	v_mfma_f32_16x16x32_bf16 v[62:65], v[118:121], v[186:189], v[62:65]
	v_mfma_f32_16x16x32_bf16 v[58:61], v[142:145], v[186:189], v[58:61]
	v_mfma_f32_16x16x32_bf16 v[46:49], v[118:121], v[194:197], v[46:49]
	v_mfma_f32_16x16x32_bf16 v[42:45], v[142:145], v[194:197], v[42:45]
	v_mfma_f32_16x16x32_bf16 v[30:33], v[118:121], v[208:211], v[30:33]
	v_mfma_f32_16x16x32_bf16 v[26:29], v[142:145], v[208:211], v[26:29]
	v_mfma_f32_16x16x32_bf16 v[14:17], v[118:121], v[222:225], v[14:17]
	v_mfma_f32_16x16x32_bf16 v[10:13], v[142:145], v[222:225], v[10:13]
	v_mfma_f32_16x16x32_bf16 v[54:57], v[146:149], v[182:185], v[54:57]
	v_mfma_f32_16x16x32_bf16 v[50:53], v[174:177], v[182:185], v[50:53]
	v_mfma_f32_16x16x32_bf16 v[38:41], v[146:149], v[190:193], v[38:41]
	v_mfma_f32_16x16x32_bf16 v[34:37], v[174:177], v[190:193], v[34:37]
	v_mfma_f32_16x16x32_bf16 v[22:25], v[146:149], v[204:207], v[22:25]
	v_mfma_f32_16x16x32_bf16 v[18:21], v[174:177], v[204:207], v[18:21]
	v_mfma_f32_16x16x32_bf16 v[6:9], v[146:149], v[212:215], v[6:9]
	v_mfma_f32_16x16x32_bf16 v[2:5], v[174:177], v[212:215], v[2:5]
	v_mfma_f32_16x16x32_bf16 v[54:57], v[150:153], v[186:189], v[54:57]
	v_mfma_f32_16x16x32_bf16 v[50:53], v[178:181], v[186:189], v[50:53]
	v_mfma_f32_16x16x32_bf16 v[38:41], v[150:153], v[194:197], v[38:41]
	v_mfma_f32_16x16x32_bf16 v[34:37], v[178:181], v[194:197], v[34:37]
	v_mfma_f32_16x16x32_bf16 v[22:25], v[150:153], v[208:211], v[22:25]
	v_mfma_f32_16x16x32_bf16 v[18:21], v[178:181], v[208:211], v[18:21]
	v_mfma_f32_16x16x32_bf16 v[6:9], v[150:153], v[222:225], v[6:9]
	v_mfma_f32_16x16x32_bf16 v[2:5], v[178:181], v[222:225], v[2:5]
	s_barrier
	s_add_i32 s84, s84, 2
	s_add_u32 s26, s26, 0x10000
	s_addc_u32 s27, s27, 0
	s_add_u32 s82, s82, 0x100
	s_addc_u32 s83, s83, 0
	s_cmpk_gt_u32 s84, 0x55
	s_cbranch_scc0 .LBB0_1446
	s_and_b64 vcc, exec, s[20:21]
	s_cbranch_vccz .LBB0_1449
	s_barrier

.LBB0_1465:
	s_or_b64 exec, exec, s[26:27]
	s_and_b64 vcc, exec, s[6:7]
	s_mov_b64 s[6:7], -1
	s_cbranch_vccnz .LBB0_1432
	s_andn2_b64 vcc, exec, s[10:11]
	s_cbranch_vccnz .LBB0_1431
	s_branch .LBB0_1431

.LBB0_1554:
	s_and_b64 vcc, exec, s[14:15]
	s_cbranch_vccz .LBB0_1581
	v_bfe_i32 v5, v2, 27, 1
	v_lshlrev_b32_e32 v3, 4, v2
	v_lshrrev_b32_e32 v5, 22, v5
	v_add_u32_e32 v5, v3, v5
	v_and_b32_e32 v5, 0xfffffc00, v5
	v_sub_u32_e32 v5, v3, v5
	v_lshrrev_b32_e32 v6, 4, v5
	v_ashrrev_i32_e32 v4, 31, v2
	v_bitop3_b32 v5, v6, v5, 32 bitop3:0x6c
	v_readlane_b32 s4, v254, 56
	v_lshrrev_b32_e32 v4, 26, v4
	v_ashrrev_i32_e32 v7, 31, v5
	v_readlane_b32 s5, v254, 57
	v_add_u32_e32 v4, v2, v4
	v_lshrrev_b32_e32 v7, 26, v7
	s_lshl_b64 s[4:5], s[4:5], 9
	v_ashrrev_i32_e32 v4, 6, v4
	v_add_u32_e32 v7, v5, v7
	s_add_u32 s4, s6, s4
	v_lshlrev_b32_e32 v6, 3, v4
	v_ashrrev_i32_e32 v8, 6, v7
	v_and_b32_e32 v7, 0xc0, v7
	s_addc_u32 s5, s7, s5
	v_and_b32_e32 v6, -16, v6
	v_lshlrev_b32_e32 v4, 5, v4
	v_sub_u32_e32 v5, v5, v7
	s_add_u32 s29, s4, 0x48000000
	v_add_u32_e32 v6, v8, v6
	v_and_b32_e32 v4, 32, v4
	v_ashrrev_i16_sdwa v5, v219, sext(v5) dst_sel:DWORD dst_unused:UNUSED_PAD src0_sel:DWORD src1_sel:BYTE_0
	s_addc_u32 s41, s5, 0
	v_add_u32_sdwa v4, v4, sext(v5) dst_sel:DWORD dst_unused:UNUSED_PAD src0_sel:DWORD src1_sel:WORD_0
	v_lshlrev_b32_e32 v5, 1, v6
	v_lshrrev_b32_e32 v7, 2, v6
	v_and_b32_e32 v8, 3, v8
	s_mov_b32 s5, 0xffffe0
	v_and_b32_e32 v5, 24, v5
	v_and_b32_e32 v7, 4, v7
	v_and_or_b32 v8, v6, s5, v8
	v_or3_b32 v5, v8, v7, v5
	v_lshlrev_b32_e32 v6, 12, v6
	v_mul_u32_u24_e32 v5, 0x900, v5
	v_add_u32_e32 v3, 0x2000, v3
	v_lshl_add_u32 v130, v4, 1, v6
	v_add_lshl_u32 v162, v5, v4, 1
	v_ashrrev_i32_e32 v4, 31, v3
	v_lshrrev_b32_e32 v4, 22, v4
	v_add_u32_e32 v4, v3, v4
	v_ashrrev_i32_e32 v4, 10, v4
	v_mul_i32_i24_e32 v5, 0x400, v4
	v_sub_u32_e32 v3, v3, v5
	v_lshrrev_b32_e32 v5, 4, v3
	v_bitop3_b32 v3, v5, v3, 32 bitop3:0x6c
	v_ashrrev_i32_e32 v6, 31, v3
	v_lshrrev_b32_e32 v6, 26, v6
	v_lshlrev_b32_e32 v5, 3, v4
	v_add_u32_e32 v6, v3, v6
	v_and_b32_e32 v5, -16, v5
	v_ashrrev_i32_e32 v7, 6, v6
	s_add_u32 s70, s68, 0xc401000
	v_add_u32_e32 v5, v7, v5
	v_and_b32_e32 v7, 3, v7
	s_addc_u32 s71, s69, 0
	v_and_or_b32 v7, v5, s5, v7
	s_ashr_i32 s5, s18, 6
	s_ashr_i32 s4, s18, 8
	s_lshl_b32 s72, s5, 10
	s_cmp_lt_i32 s8, 8
	s_cselect_b32 s9, 0, -8
	s_ashr_i32 s17, s16, 31
	v_and_b32_e32 v6, 0xc0, v6
	s_add_i32 s85, s9, s8
	s_lshl_b64 s[8:9], s[16:17], 20
	v_lshlrev_b32_e32 v4, 5, v4
	v_sub_u32_e32 v3, v3, v6
	s_add_u32 s20, s29, s8
	v_and_b32_e32 v4, 32, v4
	v_ashrrev_i16_sdwa v3, v219, sext(v3) dst_sel:DWORD dst_unused:UNUSED_PAD src0_sel:DWORD src1_sel:BYTE_0
	s_addc_u32 s21, s41, s9
	s_mul_i32 s9, s85, 0x120000
	v_add_u32_sdwa v3, v4, sext(v3) dst_sel:DWORD dst_unused:UNUSED_PAD src0_sel:DWORD src1_sel:WORD_0
	v_lshlrev_b32_e32 v4, 1, v5
	v_lshrrev_b32_e32 v6, 2, v5
	s_mul_hi_i32 s8, s85, 0x120000
	s_add_u32 s22, s70, s9
	v_and_b32_e32 v4, 24, v4
	v_and_b32_e32 v6, 4, v6
	s_addc_u32 s23, s71, s8
	s_add_i32 s17, s72, 0
	v_or3_b32 v4, v7, v6, v4
	s_add_i32 m0, s17, 0x10000
	v_mul_u32_u24_e32 v4, 0x900, v4
	global_load_lds_dwordx4 v162, s[22:23]
	s_add_i32 m0, s17, 0x12000
	v_add_lshl_u32 v134, v4, v3, 1
	s_add_u32 s8, s22, 0x90000
	global_load_lds_dwordx4 v134, s[22:23]
	s_addc_u32 s9, s23, 0
	s_add_i32 m0, s17, 0x14000
	s_add_i32 s73, s17, 0x2000
	global_load_lds_dwordx4 v162, s[8:9]
	s_add_i32 m0, s17, 0x16000
	v_lshlrev_b32_e32 v5, 12, v5
	global_load_lds_dwordx4 v134, s[8:9]
	s_mov_b32 m0, s17
	s_add_u32 s8, s20, 0x80000
	v_lshl_add_u32 v132, v3, 1, v5
	global_load_lds_dwordx4 v130, s[20:21]
	s_mov_b32 m0, s73
	s_addc_u32 s9, s21, 0
	s_add_i32 s74, s17, 0x4000
	global_load_lds_dwordx4 v132, s[20:21]
	s_mov_b32 m0, s74
	s_add_i32 s75, s17, 0x6000
	global_load_lds_dwordx4 v130, s[8:9]
	s_mov_b32 m0, s75
	s_cmp_eq_u32 s4, 1
	global_load_lds_dwordx4 v132, s[8:9]
	s_cselect_b64 s[14:15], -1, 0
	s_cmp_lg_u32 s4, 1
	s_cbranch_scc1 .LBB0_1557
.LBB0_1557:
	v_lshrrev_b32_e32 v12, 1, v2
	v_and_b32_e32 v12, 24, v12
	v_and_b32_e32 v3, 15, v2
	v_lshlrev_b32_e32 v13, 1, v12
	v_lshlrev_b32_e32 v2, 2, v2
	v_lshl_or_b32 v138, s4, 6, v3
	v_lshl_or_b32 v3, v3, 6, v13
	s_lshl_b32 s4, s4, 13
	v_and_b32_e32 v2, 32, v2
	v_bitop3_b32 v13, v3, s4, v2 bitop3:0xde
	s_lshl_b32 s4, s5, 5
	s_and_b32 s8, s4, 0x60
	v_lshl_add_u64 v[4:5], s[22:23], 0, v[162:163]
	v_mov_b32_e32 v135, v163
	s_lshl_b32 s4, s8, 7
	v_lshl_add_u64 v[6:7], s[22:23], 0, v[134:135]
	v_mov_b32_e32 v131, v163
	v_bitop3_b32 v139, v3, s4, v2 bitop3:0xde
	s_add_i32 m0, s17, 0x18000
	v_lshl_add_u64 v[2:3], v[4:5], 0, s[44:45]
	v_lshl_add_u64 v[8:9], s[20:21], 0, v[130:131]
	v_mov_b32_e32 v133, v163
	s_waitcnt vmcnt(2)
	s_barrier
	global_load_lds_dwordx4 v[2:3], off
	v_lshl_add_u64 v[2:3], v[6:7], 0, s[44:45]
	s_add_i32 m0, s17, 0x1a000
	s_add_i32 s76, s17, 0x8000
	s_add_i32 s77, s17, 0xa000
	v_lshl_add_u64 v[10:11], s[20:21], 0, v[132:133]
	global_load_lds_dwordx4 v[2:3], off
	v_lshl_add_u64 v[2:3], v[8:9], 0, s[44:45]
	s_mov_b32 m0, s76
	s_add_u32 s4, s22, 0x90080
	global_load_lds_dwordx4 v[2:3], off
	v_lshl_add_u64 v[2:3], v[10:11], 0, s[44:45]
	s_mov_b32 m0, s77
	s_addc_u32 s5, s23, 0
	global_load_lds_dwordx4 v[2:3], off
	s_add_i32 m0, s17, 0x1c000
	v_lshl_add_u64 v[2:3], s[4:5], 0, v[162:163]
	global_load_lds_dwordx4 v[2:3], off
	v_lshl_add_u64 v[2:3], s[4:5], 0, v[134:135]
	s_add_i32 m0, s17, 0x1e000
	s_and_b32 s79, s2, 7
	global_load_lds_dwordx4 v[2:3], off
	s_ashr_i32 s80, s2, 3
	s_lshl_b32 s4, s79, 3
	s_and_b32 s5, s80, 7
	s_waitcnt vmcnt(6)
	s_ashr_i32 s78, s2, 31
	s_or_b32 s81, s4, s5
	s_cmpk_lt_u32 s18, 0x100
	s_cselect_b64 s[18:19], -1, 0
	v_or_b32_e32 v140, s8, v12
	s_mov_b32 s82, 0
	v_add_u32_e32 v141, 0, v13
	s_barrier
	s_branch .LBB0_1560

.LBB0_1573:
	v_mov_b32_e32 v2, 0
	s_mov_b32 s60, 0
	s_mov_b64 s[56:57], -1
	s_mov_b64 s[58:59], 0
	v_mov_b32_e32 v3, v2
	v_mov_b32_e32 v4, v2
	v_mov_b32_e32 v5, v2
	v_mov_b32_e32 v6, v2
	v_mov_b32_e32 v7, v2
	v_mov_b32_e32 v8, v2
	v_mov_b32_e32 v9, v2
	v_mov_b32_e32 v10, v2
	v_mov_b32_e32 v11, v2
	v_mov_b32_e32 v12, v2
	v_mov_b32_e32 v13, v2
	v_mov_b32_e32 v18, v2
	v_mov_b32_e32 v19, v2
	v_mov_b32_e32 v20, v2
	v_mov_b32_e32 v21, v2
	v_mov_b32_e32 v26, v2
	v_mov_b32_e32 v27, v2
	v_mov_b32_e32 v28, v2
	v_mov_b32_e32 v29, v2
	v_mov_b32_e32 v34, v2
	v_mov_b32_e32 v35, v2
	v_mov_b32_e32 v36, v2
	v_mov_b32_e32 v37, v2
	v_mov_b32_e32 v42, v2
	v_mov_b32_e32 v43, v2
	v_mov_b32_e32 v44, v2
	v_mov_b32_e32 v45, v2
	v_mov_b32_e32 v50, v2
	v_mov_b32_e32 v51, v2
	v_mov_b32_e32 v52, v2
	v_mov_b32_e32 v53, v2
	v_mov_b32_e32 v14, v2
	v_mov_b32_e32 v15, v2
	v_mov_b32_e32 v16, v2
	v_mov_b32_e32 v17, v2
	v_mov_b32_e32 v22, v2
	v_mov_b32_e32 v23, v2
	v_mov_b32_e32 v24, v2
	v_mov_b32_e32 v25, v2
	v_mov_b32_e32 v30, v2
	v_mov_b32_e32 v31, v2
	v_mov_b32_e32 v32, v2
	v_mov_b32_e32 v33, v2
	v_mov_b32_e32 v38, v2
	v_mov_b32_e32 v39, v2
	v_mov_b32_e32 v40, v2
	v_mov_b32_e32 v41, v2
	v_mov_b32_e32 v46, v2
	v_mov_b32_e32 v47, v2
	v_mov_b32_e32 v48, v2
	v_mov_b32_e32 v49, v2
	v_mov_b32_e32 v54, v2
	v_mov_b32_e32 v55, v2
	v_mov_b32_e32 v56, v2
	v_mov_b32_e32 v57, v2
	v_mov_b32_e32 v58, v2
	v_mov_b32_e32 v59, v2
	v_mov_b32_e32 v60, v2
	v_mov_b32_e32 v61, v2
	v_mov_b32_e32 v62, v2
	v_mov_b32_e32 v63, v2
	v_mov_b32_e32 v64, v2
	v_mov_b32_e32 v65, v2
	v_mov_b32_e32 v66, v2
	v_mov_b32_e32 v67, v2
	v_mov_b32_e32 v68, v2
	v_mov_b32_e32 v69, v2
	v_mov_b32_e32 v70, v2
	v_mov_b32_e32 v71, v2
	v_mov_b32_e32 v72, v2
	v_mov_b32_e32 v73, v2
	v_mov_b32_e32 v74, v2
	v_mov_b32_e32 v75, v2
	v_mov_b32_e32 v76, v2
	v_mov_b32_e32 v77, v2
	v_mov_b32_e32 v82, v2
	v_mov_b32_e32 v83, v2
	v_mov_b32_e32 v84, v2
	v_mov_b32_e32 v85, v2
	v_mov_b32_e32 v90, v2
	v_mov_b32_e32 v91, v2
	v_mov_b32_e32 v92, v2
	v_mov_b32_e32 v93, v2
	v_mov_b32_e32 v98, v2
	v_mov_b32_e32 v99, v2
	v_mov_b32_e32 v100, v2
	v_mov_b32_e32 v101, v2
	v_mov_b32_e32 v106, v2
	v_mov_b32_e32 v107, v2
	v_mov_b32_e32 v108, v2
	v_mov_b32_e32 v109, v2
	v_mov_b32_e32 v114, v2
	v_mov_b32_e32 v115, v2
	v_mov_b32_e32 v116, v2
	v_mov_b32_e32 v117, v2
	v_mov_b32_e32 v78, v2
	v_mov_b32_e32 v79, v2
	v_mov_b32_e32 v80, v2
	v_mov_b32_e32 v81, v2
	v_mov_b32_e32 v86, v2
	v_mov_b32_e32 v87, v2
	v_mov_b32_e32 v88, v2
	v_mov_b32_e32 v89, v2
	v_mov_b32_e32 v94, v2
	v_mov_b32_e32 v95, v2
	v_mov_b32_e32 v96, v2
	v_mov_b32_e32 v97, v2
	v_mov_b32_e32 v102, v2
	v_mov_b32_e32 v103, v2
	v_mov_b32_e32 v104, v2
	v_mov_b32_e32 v105, v2
	v_mov_b32_e32 v110, v2
	v_mov_b32_e32 v111, v2
	v_mov_b32_e32 v112, v2
	v_mov_b32_e32 v113, v2
	v_mov_b32_e32 v118, v2
	v_mov_b32_e32 v119, v2
	v_mov_b32_e32 v120, v2
	v_mov_b32_e32 v121, v2
	v_mov_b32_e32 v122, v2
	v_mov_b32_e32 v123, v2
	v_mov_b32_e32 v124, v2
	v_mov_b32_e32 v125, v2
	v_mov_b32_e32 v126, v2
	v_mov_b32_e32 v127, v2
	v_mov_b32_e32 v128, v2
	v_mov_b32_e32 v129, v2
	v_readfirstlane_b32 s100, v0
	s_nop 3
	s_bitcmp1_b32 s100, 8
	s_cbranch_scc0 .Lrb_skip8
	s_barrier
.Lrb_skip8:
.LBB0_1574:
	s_add_u32 s36, s20, s60
	s_addc_u32 s37, s21, 0
	s_add_u32 s38, s36, 0x100
	s_addc_u32 s39, s37, 0
	s_and_b64 s[8:9], s[58:59], exec
	s_cselect_b32 s63, s25, s39
	s_cselect_b32 s62, s24, s38
	s_add_u32 s8, s22, s60
	s_addc_u32 s9, s23, 0
	s_add_u32 s38, s8, 0x100
	s_addc_u32 s39, s9, 0
	s_add_i32 s31, 0, 0x10000
	s_and_b64 s[8:9], s[58:59], exec
	s_cselect_b32 s65, s27, s39
	s_cselect_b32 s64, s26, s38
	s_add_i32 s38, 0, 0x14000
	s_add_u32 vcc_lo, s36, 0x80080
	s_addc_u32 vcc_hi, s37, 0
	s_add_i32 s8, s31, s72
	s_add_i32 m0, s17, 0xc000
	s_add_i32 s39, s17, 0xe000
	s_add_i32 s36, s8, 0x2000
	v_add_u32_e32 v136, s31, v139
	s_add_u32 s66, s64, 0x90000
	ds_read_b128 v[142:145], v136
	ds_read_b128 v[146:149], v136 offset:1024
	ds_read_b128 v[150:153], v136 offset:2048
	ds_read_b128 v[154:157], v136 offset:3072
	v_add_u32_e32 v136, s38, v139
	s_addc_u32 s67, s65, 0
	s_add_i32 s9, s38, s72
	ds_read_b128 v[158:161], v136
	ds_read_b128 v[172:175], v136 offset:1024
	ds_read_b128 v[176:179], v136 offset:2048
	ds_read_b128 v[180:183], v136 offset:3072
	s_add_i32 s43, s9, 0x2000
	s_add_i32 s89, 0, 0x18000
	s_add_i32 s88, 0, 0x1c000
	s_add_u32 s60, s62, 0x80000
	s_addc_u32 s61, s63, 0
	s_add_i32 s87, s89, s72
	s_add_i32 s86, s87, 0x2000
	s_add_u32 s58, s64, 0x90080
	s_addc_u32 s59, s65, 0
	s_add_i32 s38, s88, s72
	s_add_i32 s37, s38, 0x2000
	v_lshl_add_u64 v[136:137], vcc, 0, v[130:131]
	ds_read_b128 v[184:187], v141
	ds_read_b128 v[188:191], v141 offset:1024
	ds_read_b128 v[192:195], v141 offset:2048
	ds_read_b128 v[196:199], v141 offset:3072
	ds_read_b128 v[200:203], v141 offset:4096
	ds_read_b128 v[204:207], v141 offset:5120
	ds_read_b128 v[208:211], v141 offset:6144
	ds_read_b128 v[212:215], v141 offset:7168
	global_load_lds_dwordx4 v[136:137], off
	v_lshl_add_u64 v[136:137], vcc, 0, v[132:133]
	s_mov_b32 m0, s39
	s_nop 0
	global_load_lds_dwordx4 v[136:137], off
	s_waitcnt vmcnt(8)
	s_waitcnt lgkmcnt(0)
	s_barrier
	v_mfma_f32_16x16x32_bf16 v[126:129], v[142:145], v[184:187], v[126:129]
	v_mfma_f32_16x16x32_bf16 v[122:125], v[150:153], v[184:187], v[122:125]
	v_mfma_f32_16x16x32_bf16 v[118:121], v[142:145], v[192:195], v[118:121]
	v_mfma_f32_16x16x32_bf16 v[110:113], v[150:153], v[192:195], v[110:113]
	v_mfma_f32_16x16x32_bf16 v[102:105], v[142:145], v[200:203], v[102:105]
	v_mfma_f32_16x16x32_bf16 v[94:97], v[150:153], v[200:203], v[94:97]
	v_mfma_f32_16x16x32_bf16 v[86:89], v[142:145], v[208:211], v[86:89]
	v_mfma_f32_16x16x32_bf16 v[78:81], v[150:153], v[208:211], v[78:81]
	v_mfma_f32_16x16x32_bf16 v[126:129], v[146:149], v[188:191], v[126:129]
	v_mfma_f32_16x16x32_bf16 v[122:125], v[154:157], v[188:191], v[122:125]
	v_mfma_f32_16x16x32_bf16 v[118:121], v[146:149], v[196:199], v[118:121]
	v_mfma_f32_16x16x32_bf16 v[110:113], v[154:157], v[196:199], v[110:113]
	v_mfma_f32_16x16x32_bf16 v[102:105], v[146:149], v[204:207], v[102:105]
	v_mfma_f32_16x16x32_bf16 v[94:97], v[154:157], v[204:207], v[94:97]
	v_mfma_f32_16x16x32_bf16 v[86:89], v[146:149], v[212:215], v[86:89]
	v_mfma_f32_16x16x32_bf16 v[78:81], v[154:157], v[212:215], v[78:81]
	v_mfma_f32_16x16x32_bf16 v[114:117], v[158:161], v[184:187], v[114:117]
	v_mfma_f32_16x16x32_bf16 v[106:109], v[176:179], v[184:187], v[106:109]
	v_mfma_f32_16x16x32_bf16 v[98:101], v[158:161], v[192:195], v[98:101]
	v_mfma_f32_16x16x32_bf16 v[90:93], v[176:179], v[192:195], v[90:93]
	v_mfma_f32_16x16x32_bf16 v[82:85], v[158:161], v[200:203], v[82:85]
	v_mfma_f32_16x16x32_bf16 v[74:77], v[176:179], v[200:203], v[74:77]
	v_mfma_f32_16x16x32_bf16 v[70:73], v[158:161], v[208:211], v[70:73]
	v_mfma_f32_16x16x32_bf16 v[66:69], v[176:179], v[208:211], v[66:69]
	v_mfma_f32_16x16x32_bf16 v[114:117], v[172:175], v[188:191], v[114:117]
	v_mfma_f32_16x16x32_bf16 v[106:109], v[180:183], v[188:191], v[106:109]
	v_mfma_f32_16x16x32_bf16 v[98:101], v[172:175], v[196:199], v[98:101]
	v_mfma_f32_16x16x32_bf16 v[90:93], v[180:183], v[196:199], v[90:93]
	v_mfma_f32_16x16x32_bf16 v[82:85], v[172:175], v[204:207], v[82:85]
	v_mfma_f32_16x16x32_bf16 v[74:77], v[180:183], v[204:207], v[74:77]
	v_mfma_f32_16x16x32_bf16 v[70:73], v[172:175], v[212:215], v[70:73]
	v_mfma_f32_16x16x32_bf16 v[66:69], v[180:183], v[212:215], v[66:69]
	s_barrier
	s_mov_b32 m0, s8
	v_lshl_add_u64 v[136:137], s[64:65], 0, v[162:163]
	ds_read_b128 v[184:187], v141 offset:16384
	ds_read_b128 v[188:191], v141 offset:17408
	ds_read_b128 v[192:195], v141 offset:18432
	ds_read_b128 v[196:199], v141 offset:19456
	ds_read_b128 v[200:203], v141 offset:20480
	ds_read_b128 v[204:207], v141 offset:21504
	ds_read_b128 v[208:211], v141 offset:22528
	ds_read_b128 v[212:215], v141 offset:23552
	global_load_lds_dwordx4 v[136:137], off
	v_lshl_add_u64 v[168:169], s[64:65], 0, v[134:135]
	s_mov_b32 m0, s36
	v_lshl_add_u64 v[170:171], s[66:67], 0, v[162:163]
	global_load_lds_dwordx4 v[168:169], off
	s_mov_b32 m0, s9
	v_lshl_add_u64 v[216:217], s[62:63], 0, v[132:133]
	global_load_lds_dwordx4 v[170:171], off
	v_lshl_add_u64 v[170:171], s[66:67], 0, v[134:135]
	s_mov_b32 m0, s43
	s_nop 0
	global_load_lds_dwordx4 v[170:171], off
	v_lshl_add_u64 v[170:171], s[62:63], 0, v[130:131]
	s_mov_b32 m0, s17
	s_nop 0
	global_load_lds_dwordx4 v[170:171], off
	s_mov_b32 m0, s73
	s_nop 0
	global_load_lds_dwordx4 v[216:217], off
	s_waitcnt vmcnt(8)
	s_waitcnt lgkmcnt(0)
	s_barrier
	v_mfma_f32_16x16x32_bf16 v[62:65], v[142:145], v[184:187], v[62:65]
	v_mfma_f32_16x16x32_bf16 v[58:61], v[150:153], v[184:187], v[58:61]
	v_mfma_f32_16x16x32_bf16 v[54:57], v[142:145], v[192:195], v[54:57]
	v_mfma_f32_16x16x32_bf16 v[46:49], v[150:153], v[192:195], v[46:49]
	v_mfma_f32_16x16x32_bf16 v[38:41], v[142:145], v[200:203], v[38:41]
	v_mfma_f32_16x16x32_bf16 v[30:33], v[150:153], v[200:203], v[30:33]
	v_mfma_f32_16x16x32_bf16 v[22:25], v[142:145], v[208:211], v[22:25]
	v_mfma_f32_16x16x32_bf16 v[14:17], v[150:153], v[208:211], v[14:17]
	v_mfma_f32_16x16x32_bf16 v[62:65], v[146:149], v[188:191], v[62:65]
	v_mfma_f32_16x16x32_bf16 v[58:61], v[154:157], v[188:191], v[58:61]
	v_mfma_f32_16x16x32_bf16 v[54:57], v[146:149], v[196:199], v[54:57]
	v_mfma_f32_16x16x32_bf16 v[46:49], v[154:157], v[196:199], v[46:49]
	v_mfma_f32_16x16x32_bf16 v[38:41], v[146:149], v[204:207], v[38:41]
	v_mfma_f32_16x16x32_bf16 v[30:33], v[154:157], v[204:207], v[30:33]
	v_mfma_f32_16x16x32_bf16 v[22:25], v[146:149], v[212:215], v[22:25]
	v_mfma_f32_16x16x32_bf16 v[14:17], v[154:157], v[212:215], v[14:17]
	v_mfma_f32_16x16x32_bf16 v[50:53], v[158:161], v[184:187], v[50:53]
	v_mfma_f32_16x16x32_bf16 v[42:45], v[176:179], v[184:187], v[42:45]
	v_mfma_f32_16x16x32_bf16 v[34:37], v[158:161], v[192:195], v[34:37]
	v_mfma_f32_16x16x32_bf16 v[26:29], v[176:179], v[192:195], v[26:29]
	v_mfma_f32_16x16x32_bf16 v[18:21], v[158:161], v[200:203], v[18:21]
	v_mfma_f32_16x16x32_bf16 v[10:13], v[176:179], v[200:203], v[10:13]
	v_mfma_f32_16x16x32_bf16 v[6:9], v[158:161], v[208:211], v[6:9]
	v_mfma_f32_16x16x32_bf16 v[2:5], v[176:179], v[208:211], v[2:5]
	v_mfma_f32_16x16x32_bf16 v[50:53], v[172:175], v[188:191], v[50:53]
	v_mfma_f32_16x16x32_bf16 v[42:45], v[180:183], v[188:191], v[42:45]
	v_mfma_f32_16x16x32_bf16 v[34:37], v[172:175], v[196:199], v[34:37]
	v_mfma_f32_16x16x32_bf16 v[26:29], v[180:183], v[196:199], v[26:29]
	v_mfma_f32_16x16x32_bf16 v[18:21], v[172:175], v[204:207], v[18:21]
	v_mfma_f32_16x16x32_bf16 v[10:13], v[180:183], v[204:207], v[10:13]
	v_mfma_f32_16x16x32_bf16 v[6:9], v[172:175], v[212:215], v[6:9]
	v_mfma_f32_16x16x32_bf16 v[2:5], v[180:183], v[212:215], v[2:5]
	s_barrier
	v_add_u32_e32 v154, s89, v139
	v_add_u32_e32 v180, s88, v139
	ds_read_b128 v[142:145], v154
	ds_read_b128 v[146:149], v154 offset:1024
	ds_read_b128 v[150:153], v154 offset:2048
	ds_read_b128 v[154:157], v154 offset:3072
	ds_read_b128 v[158:161], v180
	ds_read_b128 v[172:175], v180 offset:1024
	ds_read_b128 v[176:179], v180 offset:2048
	ds_read_b128 v[180:183], v180 offset:3072
	s_mov_b32 m0, s74
	v_lshl_add_u64 v[222:223], s[60:61], 0, v[130:131]
	ds_read_b128 v[184:187], v141 offset:32768
	ds_read_b128 v[188:191], v141 offset:33792
	ds_read_b128 v[192:195], v141 offset:34816
	ds_read_b128 v[196:199], v141 offset:35840
	ds_read_b128 v[200:203], v141 offset:36864
	ds_read_b128 v[204:207], v141 offset:37888
	ds_read_b128 v[208:211], v141 offset:38912
	ds_read_b128 v[212:215], v141 offset:39936
	global_load_lds_dwordx4 v[222:223], off
	v_lshl_add_u64 v[222:223], s[60:61], 0, v[132:133]
	s_mov_b32 m0, s75
	s_nop 0
	global_load_lds_dwordx4 v[222:223], off
	s_waitcnt vmcnt(8)
	s_waitcnt lgkmcnt(0)
	s_barrier
	v_mfma_f32_16x16x32_bf16 v[126:129], v[142:145], v[184:187], v[126:129]
	v_mfma_f32_16x16x32_bf16 v[122:125], v[150:153], v[184:187], v[122:125]
	v_mfma_f32_16x16x32_bf16 v[118:121], v[142:145], v[192:195], v[118:121]
	v_mfma_f32_16x16x32_bf16 v[110:113], v[150:153], v[192:195], v[110:113]
	v_mfma_f32_16x16x32_bf16 v[102:105], v[142:145], v[200:203], v[102:105]
	v_mfma_f32_16x16x32_bf16 v[94:97], v[150:153], v[200:203], v[94:97]
	v_mfma_f32_16x16x32_bf16 v[86:89], v[142:145], v[208:211], v[86:89]
	v_mfma_f32_16x16x32_bf16 v[78:81], v[150:153], v[208:211], v[78:81]
	v_mfma_f32_16x16x32_bf16 v[126:129], v[146:149], v[188:191], v[126:129]
	v_mfma_f32_16x16x32_bf16 v[122:125], v[154:157], v[188:191], v[122:125]
	v_mfma_f32_16x16x32_bf16 v[118:121], v[146:149], v[196:199], v[118:121]
	v_mfma_f32_16x16x32_bf16 v[110:113], v[154:157], v[196:199], v[110:113]
	v_mfma_f32_16x16x32_bf16 v[102:105], v[146:149], v[204:207], v[102:105]
	v_mfma_f32_16x16x32_bf16 v[94:97], v[154:157], v[204:207], v[94:97]
	v_mfma_f32_16x16x32_bf16 v[86:89], v[146:149], v[212:215], v[86:89]
	v_mfma_f32_16x16x32_bf16 v[78:81], v[154:157], v[212:215], v[78:81]
	v_mfma_f32_16x16x32_bf16 v[114:117], v[158:161], v[184:187], v[114:117]
	v_mfma_f32_16x16x32_bf16 v[106:109], v[176:179], v[184:187], v[106:109]
	v_mfma_f32_16x16x32_bf16 v[98:101], v[158:161], v[192:195], v[98:101]
	v_mfma_f32_16x16x32_bf16 v[90:93], v[176:179], v[192:195], v[90:93]
	v_mfma_f32_16x16x32_bf16 v[82:85], v[158:161], v[200:203], v[82:85]
	v_mfma_f32_16x16x32_bf16 v[74:77], v[176:179], v[200:203], v[74:77]
	v_mfma_f32_16x16x32_bf16 v[70:73], v[158:161], v[208:211], v[70:73]
	v_mfma_f32_16x16x32_bf16 v[66:69], v[176:179], v[208:211], v[66:69]
	v_mfma_f32_16x16x32_bf16 v[114:117], v[172:175], v[188:191], v[114:117]
	v_mfma_f32_16x16x32_bf16 v[106:109], v[180:183], v[188:191], v[106:109]
	v_mfma_f32_16x16x32_bf16 v[98:101], v[172:175], v[196:199], v[98:101]
	v_mfma_f32_16x16x32_bf16 v[90:93], v[180:183], v[196:199], v[90:93]
	v_mfma_f32_16x16x32_bf16 v[82:85], v[172:175], v[204:207], v[82:85]
	v_mfma_f32_16x16x32_bf16 v[74:77], v[180:183], v[204:207], v[74:77]
	v_mfma_f32_16x16x32_bf16 v[70:73], v[172:175], v[212:215], v[70:73]
	v_mfma_f32_16x16x32_bf16 v[66:69], v[180:183], v[212:215], v[66:69]
	s_barrier
	s_mov_b32 m0, s87
	v_lshl_add_u64 v[136:137], v[136:137], 0, s[44:45]
	ds_read_b128 v[184:187], v141 offset:49152
	ds_read_b128 v[188:191], v141 offset:50176
	ds_read_b128 v[192:195], v141 offset:51200
	ds_read_b128 v[196:199], v141 offset:52224
	ds_read_b128 v[200:203], v141 offset:53248
	ds_read_b128 v[204:207], v141 offset:54272
	ds_read_b128 v[208:211], v141 offset:55296
	ds_read_b128 v[212:215], v141 offset:56320
	global_load_lds_dwordx4 v[136:137], off
	v_lshl_add_u64 v[136:137], v[168:169], 0, s[44:45]
	s_mov_b32 m0, s86
	s_nop 0
	global_load_lds_dwordx4 v[136:137], off
	v_lshl_add_u64 v[136:137], s[58:59], 0, v[162:163]
	s_mov_b32 m0, s38
	s_nop 0
	global_load_lds_dwordx4 v[136:137], off
	v_lshl_add_u64 v[136:137], s[58:59], 0, v[134:135]
	s_mov_b32 m0, s37
	s_nop 0
	global_load_lds_dwordx4 v[136:137], off
	v_lshl_add_u64 v[136:137], v[170:171], 0, s[44:45]
	s_mov_b32 m0, s76
	s_nop 0
	global_load_lds_dwordx4 v[136:137], off
	v_lshl_add_u64 v[136:137], v[216:217], 0, s[44:45]
	s_mov_b32 m0, s77
	s_nop 0
	global_load_lds_dwordx4 v[136:137], off
	s_waitcnt vmcnt(8)
	s_waitcnt lgkmcnt(0)
	s_barrier
	v_mfma_f32_16x16x32_bf16 v[62:65], v[142:145], v[184:187], v[62:65]
	v_mfma_f32_16x16x32_bf16 v[58:61], v[150:153], v[184:187], v[58:61]
	v_mfma_f32_16x16x32_bf16 v[54:57], v[142:145], v[192:195], v[54:57]
	v_mfma_f32_16x16x32_bf16 v[46:49], v[150:153], v[192:195], v[46:49]
	v_mfma_f32_16x16x32_bf16 v[38:41], v[142:145], v[200:203], v[38:41]
	v_mfma_f32_16x16x32_bf16 v[30:33], v[150:153], v[200:203], v[30:33]
	v_mfma_f32_16x16x32_bf16 v[22:25], v[142:145], v[208:211], v[22:25]
	v_mfma_f32_16x16x32_bf16 v[14:17], v[150:153], v[208:211], v[14:17]
	v_mfma_f32_16x16x32_bf16 v[62:65], v[146:149], v[188:191], v[62:65]
	v_mfma_f32_16x16x32_bf16 v[58:61], v[154:157], v[188:191], v[58:61]
	v_mfma_f32_16x16x32_bf16 v[54:57], v[146:149], v[196:199], v[54:57]
	v_mfma_f32_16x16x32_bf16 v[46:49], v[154:157], v[196:199], v[46:49]
	v_mfma_f32_16x16x32_bf16 v[38:41], v[146:149], v[204:207], v[38:41]
	v_mfma_f32_16x16x32_bf16 v[30:33], v[154:157], v[204:207], v[30:33]
	v_mfma_f32_16x16x32_bf16 v[22:25], v[146:149], v[212:215], v[22:25]
	v_mfma_f32_16x16x32_bf16 v[14:17], v[154:157], v[212:215], v[14:17]
	v_mfma_f32_16x16x32_bf16 v[50:53], v[158:161], v[184:187], v[50:53]
	v_mfma_f32_16x16x32_bf16 v[42:45], v[176:179], v[184:187], v[42:45]
	v_mfma_f32_16x16x32_bf16 v[34:37], v[158:161], v[192:195], v[34:37]
	v_mfma_f32_16x16x32_bf16 v[26:29], v[176:179], v[192:195], v[26:29]
	v_mfma_f32_16x16x32_bf16 v[18:21], v[158:161], v[200:203], v[18:21]
	v_mfma_f32_16x16x32_bf16 v[10:13], v[176:179], v[200:203], v[10:13]
	v_mfma_f32_16x16x32_bf16 v[6:9], v[158:161], v[208:211], v[6:9]
	v_mfma_f32_16x16x32_bf16 v[2:5], v[176:179], v[208:211], v[2:5]
	v_mfma_f32_16x16x32_bf16 v[50:53], v[172:175], v[188:191], v[50:53]
	v_mfma_f32_16x16x32_bf16 v[42:45], v[180:183], v[188:191], v[42:45]
	v_mfma_f32_16x16x32_bf16 v[34:37], v[172:175], v[196:199], v[34:37]
	v_mfma_f32_16x16x32_bf16 v[26:29], v[180:183], v[196:199], v[26:29]
	v_mfma_f32_16x16x32_bf16 v[18:21], v[172:175], v[204:207], v[18:21]
	v_mfma_f32_16x16x32_bf16 v[10:13], v[180:183], v[204:207], v[10:13]
	v_mfma_f32_16x16x32_bf16 v[6:9], v[172:175], v[212:215], v[6:9]
	v_mfma_f32_16x16x32_bf16 v[2:5], v[180:183], v[212:215], v[2:5]
	s_barrier
	s_movk_i32 s60, 0x100
	s_andn2_b64 vcc, exec, s[56:57]
	s_mov_b64 s[58:59], -1
	s_mov_b64 s[56:57], 0
	s_cbranch_vccz .LBB0_1574
	s_and_b64 vcc, exec, s[18:19]
	s_cbranch_vccz .LBB0_1577
	s_barrier
.LBB0_1577:
	v_lshl_add_u32 v142, s16, 8, v138
	v_lshl_or_b32 v136, s85, 8, v140
	v_ashrrev_i32_e32 v137, 31, v136
	v_ashrrev_i32_e32 v143, 31, v142
	v_lshl_add_u64 v[144:145], v[136:137], 1, s[10:11]
	v_lshlrev_b64 v[136:137], 12, v[142:143]
	v_lshl_add_u64 v[136:137], v[144:145], 0, v[136:137]
	v_cvt_pk_bf16_f32 v126, v126, v127
	v_cvt_pk_bf16_f32 v127, v128, v129
	v_cvt_pk_bf16_f32 v128, v122, v123
	v_cvt_pk_bf16_f32 v129, v124, v125
	global_store_dwordx4 v[136:137], v[126:129], off
	v_cvt_pk_bf16_f32 v114, v114, v115
	v_cvt_pk_bf16_f32 v115, v116, v117
	v_cvt_pk_bf16_f32 v116, v106, v107
	v_or_b32_e32 v106, 16, v142
	v_ashrrev_i32_e32 v107, 31, v106
	v_lshlrev_b64 v[106:107], 12, v[106:107]
	v_cvt_pk_bf16_f32 v117, v108, v109
	global_store_dwordx4 v[136:137], v[114:117], off offset:256
	s_mov_b64 s[8:9], 0x80000
	v_readlane_b32 s86, v255, 14
	v_lshl_add_u64 v[114:115], v[144:145], 0, v[106:107]
	v_cvt_pk_bf16_f32 v106, v118, v119
	v_cvt_pk_bf16_f32 v107, v120, v121
	v_cvt_pk_bf16_f32 v108, v110, v111
	v_cvt_pk_bf16_f32 v109, v112, v113
	global_store_dwordx4 v[114:115], v[106:109], off
	v_cvt_pk_bf16_f32 v98, v98, v99
	v_cvt_pk_bf16_f32 v99, v100, v101
	v_cvt_pk_bf16_f32 v100, v90, v91
	v_or_b32_e32 v90, 32, v142
	v_ashrrev_i32_e32 v91, 31, v90
	v_lshlrev_b64 v[90:91], 12, v[90:91]
	v_cvt_pk_bf16_f32 v101, v92, v93
	global_store_dwordx4 v[114:115], v[98:101], off offset:256
	v_readlane_b32 s88, v255, 16
	v_readlane_b32 s87, v255, 15
	v_lshl_add_u64 v[98:99], v[144:145], 0, v[90:91]
	v_cvt_pk_bf16_f32 v90, v102, v103
	v_cvt_pk_bf16_f32 v91, v104, v105
	v_cvt_pk_bf16_f32 v92, v94, v95
	v_cvt_pk_bf16_f32 v93, v96, v97
	global_store_dwordx4 v[98:99], v[90:93], off
	v_cvt_pk_bf16_f32 v82, v82, v83
	v_cvt_pk_bf16_f32 v83, v84, v85
	v_cvt_pk_bf16_f32 v84, v74, v75
	v_or_b32_e32 v74, 48, v142
	v_ashrrev_i32_e32 v75, 31, v74
	v_lshlrev_b64 v[74:75], 12, v[74:75]
	v_cvt_pk_bf16_f32 v85, v76, v77
	global_store_dwordx4 v[98:99], v[82:85], off offset:256
	v_readlane_b32 s89, v255, 17
	s_nop 0
	v_lshl_add_u64 v[82:83], v[144:145], 0, v[74:75]
	v_cvt_pk_bf16_f32 v74, v86, v87
	v_cvt_pk_bf16_f32 v75, v88, v89
	v_cvt_pk_bf16_f32 v76, v78, v79
	v_cvt_pk_bf16_f32 v77, v80, v81
	global_store_dwordx4 v[82:83], v[74:77], off
	v_cvt_pk_bf16_f32 v70, v70, v71
	v_cvt_pk_bf16_f32 v71, v72, v73
	v_cvt_pk_bf16_f32 v72, v66, v67
	v_lshl_add_u64 v[66:67], v[136:137], 0, s[8:9]
	s_mov_b32 s8, 0x80000
	v_cvt_pk_bf16_f32 v73, v68, v69
	global_store_dwordx4 v[82:83], v[70:73], off offset:256
	v_cvt_pk_bf16_f32 v62, v62, v63
	v_cvt_pk_bf16_f32 v63, v64, v65
	v_cvt_pk_bf16_f32 v64, v58, v59
	v_add_co_u32_e32 v58, vcc, s8, v136
	v_cvt_pk_bf16_f32 v65, v60, v61
	s_mov_b64 s[8:9], 0x90000
	s_nop 0
	v_addc_co_u32_e32 v59, vcc, 0, v137, vcc
	global_store_dwordx4 v[58:59], v[62:65], off
	v_cvt_pk_bf16_f32 v50, v50, v51
	v_cvt_pk_bf16_f32 v51, v52, v53
	v_cvt_pk_bf16_f32 v52, v42, v43
	v_cvt_pk_bf16_f32 v53, v44, v45
	global_store_dwordx4 v[66:67], v[50:53], off offset:256
	v_cvt_pk_bf16_f32 v42, v54, v55
	v_cvt_pk_bf16_f32 v43, v56, v57
	v_cvt_pk_bf16_f32 v44, v46, v47
	v_cvt_pk_bf16_f32 v45, v48, v49
	s_nop 1
	v_lshl_add_u64 v[50:51], v[136:137], 0, s[8:9]
	s_mov_b32 s8, 0x90000
	v_add_co_u32_e32 v46, vcc, s8, v136
	s_mov_b64 s[8:9], 0xa0000
	s_nop 0
	v_addc_co_u32_e32 v47, vcc, 0, v137, vcc
	global_store_dwordx4 v[46:47], v[42:45], off
	v_cvt_pk_bf16_f32 v34, v34, v35
	v_cvt_pk_bf16_f32 v35, v36, v37
	v_cvt_pk_bf16_f32 v36, v26, v27
	v_cvt_pk_bf16_f32 v37, v28, v29
	global_store_dwordx4 v[50:51], v[34:37], off offset:256
	v_cvt_pk_bf16_f32 v26, v38, v39
	v_cvt_pk_bf16_f32 v27, v40, v41
	v_cvt_pk_bf16_f32 v28, v30, v31
	v_cvt_pk_bf16_f32 v29, v32, v33
	s_nop 1
	v_lshl_add_u64 v[34:35], v[136:137], 0, s[8:9]
	s_mov_b32 s8, 0xa0000
	v_add_co_u32_e32 v30, vcc, s8, v136
	s_mov_b64 s[8:9], 0xb0000
	s_nop 0
	v_addc_co_u32_e32 v31, vcc, 0, v137, vcc
	global_store_dwordx4 v[30:31], v[26:29], off
	v_cvt_pk_bf16_f32 v18, v18, v19
	v_cvt_pk_bf16_f32 v19, v20, v21
	v_cvt_pk_bf16_f32 v20, v10, v11
	v_cvt_pk_bf16_f32 v21, v12, v13
	global_store_dwordx4 v[34:35], v[18:21], off offset:256
	v_cvt_pk_bf16_f32 v10, v22, v23
	v_cvt_pk_bf16_f32 v11, v24, v25
	v_cvt_pk_bf16_f32 v12, v14, v15
	v_cvt_pk_bf16_f32 v13, v16, v17
	s_nop 1
	v_lshl_add_u64 v[18:19], v[136:137], 0, s[8:9]
	s_mov_b32 s8, 0xb0000
	v_add_co_u32_e32 v14, vcc, s8, v136
	s_nop 1
	v_addc_co_u32_e32 v15, vcc, 0, v137, vcc
	s_and_b64 vcc, exec, s[4:5]
	s_mov_b64 s[4:5], -1
	global_store_dwordx4 v[14:15], v[10:13], off
	v_cvt_pk_bf16_f32 v6, v6, v7
	v_cvt_pk_bf16_f32 v7, v8, v9
	v_cvt_pk_bf16_f32 v8, v2, v3
	v_cvt_pk_bf16_f32 v9, v4, v5
	global_store_dwordx4 v[18:19], v[6:9], off offset:256
	s_cbranch_vccnz .LBB0_1559
	s_andn2_b64 vcc, exec, s[14:15]
	s_cbranch_vccnz .LBB0_1558
	s_branch .LBB0_1558

.LBB0_1596:
	v_ashrrev_i32_e32 v3, 31, v195
	v_lshrrev_b32_e32 v3, 26, v3
	v_add_u32_e32 v3, v195, v3
	v_ashrrev_i32_e32 v10, 6, v3
	v_bfe_i32 v3, v195, 27, 1
	v_lshlrev_b32_e32 v2, 4, v195
	v_lshrrev_b32_e32 v3, 22, v3
	v_add_u32_e32 v3, v2, v3
	v_and_b32_e32 v3, 0xfffffc00, v3
	v_sub_u32_e32 v3, v2, v3
	v_lshrrev_b32_e32 v4, 4, v3
	v_bitop3_b32 v3, v4, v3, 32 bitop3:0x6c
	v_ashrrev_i32_e32 v5, 31, v3
	v_lshrrev_b32_e32 v5, 26, v5
	v_add_u32_e32 v5, v3, v5
	v_ashrrev_i32_e32 v11, 6, v5
	v_and_b32_e32 v5, 0xc0, v5
	v_lshlrev_b32_e32 v4, 3, v10
	v_sub_u32_e32 v3, v3, v5
	v_and_b32_e32 v4, -16, v4
	v_lshlrev_b32_e32 v6, 5, v10
	v_ashrrev_i16_sdwa v3, v219, sext(v3) dst_sel:DWORD dst_unused:UNUSED_PAD src0_sel:DWORD src1_sel:BYTE_0
	v_add_u32_e32 v4, v11, v4
	v_and_b32_e32 v6, 32, v6
	v_bfe_i32 v12, v3, 0, 16
	v_add_u32_e32 v3, v6, v12
	v_lshlrev_b32_e32 v5, 1, v4
	v_lshrrev_b32_e32 v6, 2, v4
	v_and_b32_e32 v7, 3, v11
	s_mov_b32 s12, 0xffffe0
	v_and_b32_e32 v5, 24, v5
	v_and_b32_e32 v6, 4, v6
	v_and_or_b32 v7, v4, s12, v7
	v_or3_b32 v5, v7, v6, v5
	v_lshlrev_b32_e32 v4, 11, v4
	v_lshl_add_u32 v172, v3, 1, v4
	v_mul_u32_u24_e32 v4, 0x900, v5
	v_add_u32_e32 v2, 0x2000, v2
	v_add_lshl_u32 v162, v4, v3, 1
	v_ashrrev_i32_e32 v3, 31, v2
	v_lshrrev_b32_e32 v3, 22, v3
	v_add_u32_e32 v3, v2, v3
	v_ashrrev_i32_e32 v13, 10, v3
	v_mul_i32_i24_e32 v3, 0x400, v13
	v_sub_u32_e32 v2, v2, v3
	v_lshrrev_b32_e32 v3, 4, v2
	v_bitop3_b32 v2, v3, v2, 32 bitop3:0x6c
	v_ashrrev_i32_e32 v4, 31, v2
	v_lshrrev_b32_e32 v4, 26, v4
	v_add_u32_e32 v4, v2, v4
	v_ashrrev_i32_e32 v14, 6, v4
	v_and_b32_e32 v4, 0xc0, v4
	v_lshlrev_b32_e32 v3, 3, v13
	v_sub_u32_e32 v2, v2, v4
	v_and_b32_e32 v3, -16, v3
	v_lshlrev_b32_e32 v5, 5, v13
	v_ashrrev_i16_sdwa v2, v219, sext(v2) dst_sel:DWORD dst_unused:UNUSED_PAD src0_sel:DWORD src1_sel:BYTE_0
	v_add_u32_e32 v3, v14, v3
	v_and_b32_e32 v5, 32, v5
	v_bfe_i32 v15, v2, 0, 16
	v_add_u32_e32 v2, v5, v15
	v_lshlrev_b32_e32 v4, 1, v3
	v_lshrrev_b32_e32 v5, 2, v3
	v_and_b32_e32 v6, 3, v14
	s_lshl_b32 s61, s4, 10
	v_and_b32_e32 v4, 24, v4
	v_and_b32_e32 v5, 4, v5
	v_and_or_b32 v6, v3, s12, v6
	s_add_i32 s63, s61, 0
	v_or3_b32 v4, v6, v5, v4
	v_lshlrev_b32_e32 v3, 11, v3
	s_add_i32 m0, s63, 0x10000
	s_ashr_i32 s23, s22, 8
	v_lshl_add_u32 v174, v2, 1, v3
	v_mul_u32_u24_e32 v3, 0x900, v4
	global_load_lds_dwordx4 v162, s[66:67]
	s_add_i32 m0, s63, 0x12000
	v_add_lshl_u32 v176, v3, v2, 1
	s_add_u32 s12, s66, 0x90000
	global_load_lds_dwordx4 v176, s[66:67]
	s_addc_u32 s13, s67, 0
	s_add_i32 m0, s63, 0x14000
	s_add_i32 s78, s63, 0x2000
	global_load_lds_dwordx4 v162, s[12:13]
	s_add_i32 m0, s63, 0x16000
	v_mov_b32_e32 v177, v163
	global_load_lds_dwordx4 v176, s[12:13]
	s_mov_b32 m0, s63
	s_add_u32 s12, s64, 0x40000
	global_load_lds_dwordx4 v172, s[64:65]
	s_mov_b32 m0, s78
	s_addc_u32 s13, s65, 0
	s_add_i32 s79, s63, 0x4000
	global_load_lds_dwordx4 v174, s[64:65]
	s_mov_b32 m0, s79
	s_add_i32 s80, s63, 0x6000
	global_load_lds_dwordx4 v172, s[12:13]
	s_mov_b32 m0, s80
	v_mov_b32_e32 v173, v163
	global_load_lds_dwordx4 v174, s[12:13]
	v_mov_b32_e32 v175, v163
	s_cmp_eq_u32 s23, 1
	v_lshl_add_u64 v[8:9], s[66:67], 0, v[162:163]
	v_lshl_add_u64 v[6:7], s[66:67], 0, v[176:177]
	v_lshl_add_u64 v[2:3], s[64:65], 0, v[172:173]
	s_cselect_b64 s[12:13], -1, 0
	s_cmp_lg_u32 s23, 1
	v_lshl_add_u64 v[4:5], s[64:65], 0, v[174:175]
	s_cbranch_scc1 .LBB0_1598
.LBB0_1598:
	s_add_u32 s14, s6, 0x44000000
	s_addc_u32 s15, s7, 0
	v_readlane_b32 s20, v255, 23
	s_add_u32 s16, s6, 0x63000000
	v_readlane_b32 s21, v255, 24
	s_addc_u32 s17, s7, 0
	s_lshl_b64 s[20:21], s[20:21], 3
	s_add_u32 s5, s5, s20
	s_addc_u32 s19, s18, s21
	s_add_u32 s18, s5, 0x80000
	s_addc_u32 s19, s19, 0
	s_add_u32 s20, s6, 0x69000000
	v_bfe_u32 v17, v195, 4, 2
	s_addc_u32 s21, s7, 0
	v_and_b32_e32 v16, 15, v195
	v_lshlrev_b32_e32 v18, 4, v17
	s_lshl_b32 s4, s4, 5
	v_lshl_or_b32 v197, s23, 6, v16
	v_lshl_or_b32 v16, v16, 6, v18
	v_lshlrev_b32_e32 v18, 2, v195
	s_and_b32 s81, s4, 0x60
	s_add_i32 m0, s63, 0x18000
	v_lshl_add_u64 v[8:9], v[8:9], 0, s[44:45]
	s_lshl_b32 s5, s23, 13
	v_and_b32_e32 v18, 32, v18
	s_lshl_b32 s4, s81, 7
	s_waitcnt vmcnt(2)
	s_barrier
	global_load_lds_dwordx4 v[8:9], off
	v_lshl_add_u64 v[6:7], v[6:7], 0, s[44:45]
	s_add_i32 m0, s63, 0x1a000
	s_add_i32 s82, s63, 0x8000
	s_add_i32 s83, s63, 0xa000
	v_bitop3_b32 v201, v16, s4, v18 bitop3:0xde
	global_load_lds_dwordx4 v[6:7], off
	v_lshl_add_u64 v[2:3], v[2:3], 0, s[44:45]
	s_mov_b32 m0, s82
	s_add_u32 s4, s66, 0x90080
	v_bitop3_b32 v19, v16, s5, v18 bitop3:0xde
	global_load_lds_dwordx4 v[2:3], off
	v_lshl_add_u64 v[2:3], v[4:5], 0, s[44:45]
	s_mov_b32 m0, s83
	s_addc_u32 s5, s67, 0
	global_load_lds_dwordx4 v[2:3], off
	s_add_i32 m0, s63, 0x1c000
	v_lshl_add_u64 v[2:3], s[4:5], 0, v[162:163]
	global_load_lds_dwordx4 v[2:3], off
	v_lshl_add_u64 v[2:3], s[4:5], 0, v[176:177]
	s_add_i32 m0, s63, 0x1e000
	s_and_b32 s85, s2, 7
	global_load_lds_dwordx4 v[2:3], off
	v_lshlrev_b32_e32 v2, 14, v13
	v_and_b32_e32 v2, 0xffff8000, v2
	v_lshl_add_u32 v2, v14, 11, v2
	v_and_b32_e32 v3, 1, v13
	v_lshl_or_b32 v2, v3, 6, v2
	s_ashr_i32 s86, s2, 3
	v_lshl_add_u32 v178, v15, 1, v2
	v_lshlrev_b32_e32 v2, 14, v10
	s_lshl_b32 s4, s85, 3
	s_and_b32 s5, s86, 7
	v_and_b32_e32 v2, 0xffff8000, v2
	s_waitcnt vmcnt(6)
	s_ashr_i32 s84, s2, 31
	s_or_b32 s87, s4, s5
	v_lshl_add_u32 v2, v11, 11, v2
	v_and_b32_e32 v3, 1, v10
	v_lshlrev_b32_e32 v199, 3, v17
	s_cmpk_lt_u32 s22, 0x100
	v_lshl_or_b32 v2, v3, 6, v2
	s_cselect_b64 s[22:23], -1, 0
	v_lshlrev_b32_e32 v216, 3, v197
	s_mov_b32 s89, 0
	v_cmp_eq_u32_e64 s[4:5], 0, v17
	v_or_b32_e32 v217, s81, v199
	v_mov_b32_e32 v179, v163
	v_lshl_add_u32 v180, v12, 1, v2
	v_mov_b32_e32 v181, v163
	v_add_u32_e32 v222, 0, v19
	s_mov_b32 s88, 0
	s_barrier
	s_branch .LBB0_1601

.LBB0_1614:
	s_add_u32 s25, s66, 0x100
	s_addc_u32 s26, s67, 0
	s_add_u32 s64, s64, 0x40080
	v_mov_b32_e32 v2, 0
	s_addc_u32 s65, s65, 0
	s_mov_b32 s27, -2
	s_waitcnt lgkmcnt(0)
	v_mov_b32_e32 v3, v2
	v_mov_b32_e32 v4, v2
	v_mov_b32_e32 v5, v2
	v_mov_b32_e32 v6, v2
	v_mov_b32_e32 v7, v2
	v_mov_b32_e32 v8, v2
	v_mov_b32_e32 v9, v2
	v_mov_b32_e32 v10, v2
	v_mov_b32_e32 v11, v2
	v_mov_b32_e32 v12, v2
	v_mov_b32_e32 v13, v2
	v_mov_b32_e32 v14, v2
	v_mov_b32_e32 v15, v2
	v_mov_b32_e32 v16, v2
	v_mov_b32_e32 v17, v2
	v_mov_b32_e32 v18, v2
	v_mov_b32_e32 v19, v2
	v_mov_b32_e32 v20, v2
	v_mov_b32_e32 v21, v2
	v_mov_b32_e32 v22, v2
	v_mov_b32_e32 v23, v2
	v_mov_b32_e32 v24, v2
	v_mov_b32_e32 v25, v2
	v_mov_b32_e32 v26, v2
	v_mov_b32_e32 v27, v2
	v_mov_b32_e32 v28, v2
	v_mov_b32_e32 v29, v2
	v_mov_b32_e32 v30, v2
	v_mov_b32_e32 v31, v2
	v_mov_b32_e32 v32, v2
	v_mov_b32_e32 v33, v2
	v_mov_b32_e32 v34, v2
	v_mov_b32_e32 v35, v2
	v_mov_b32_e32 v36, v2
	v_mov_b32_e32 v37, v2
	v_mov_b32_e32 v38, v2
	v_mov_b32_e32 v39, v2
	v_mov_b32_e32 v40, v2
	v_mov_b32_e32 v41, v2
	v_mov_b32_e32 v42, v2
	v_mov_b32_e32 v43, v2
	v_mov_b32_e32 v44, v2
	v_mov_b32_e32 v45, v2
	v_mov_b32_e32 v46, v2
	v_mov_b32_e32 v47, v2
	v_mov_b32_e32 v48, v2
	v_mov_b32_e32 v49, v2
	v_mov_b32_e32 v50, v2
	v_mov_b32_e32 v51, v2
	v_mov_b32_e32 v52, v2
	v_mov_b32_e32 v53, v2
	v_mov_b32_e32 v54, v2
	v_mov_b32_e32 v55, v2
	v_mov_b32_e32 v56, v2
	v_mov_b32_e32 v57, v2
	v_mov_b32_e32 v58, v2
	v_mov_b32_e32 v59, v2
	v_mov_b32_e32 v60, v2
	v_mov_b32_e32 v61, v2
	v_mov_b32_e32 v62, v2
	v_mov_b32_e32 v63, v2
	v_mov_b32_e32 v64, v2
	v_mov_b32_e32 v65, v2
	v_mov_b32_e32 v82, v2
	v_mov_b32_e32 v83, v2
	v_mov_b32_e32 v84, v2
	v_mov_b32_e32 v85, v2
	v_mov_b32_e32 v86, v2
	v_mov_b32_e32 v87, v2
	v_mov_b32_e32 v88, v2
	v_mov_b32_e32 v89, v2
	v_mov_b32_e32 v90, v2
	v_mov_b32_e32 v91, v2
	v_mov_b32_e32 v92, v2
	v_mov_b32_e32 v93, v2
	v_mov_b32_e32 v94, v2
	v_mov_b32_e32 v95, v2
	v_mov_b32_e32 v96, v2
	v_mov_b32_e32 v97, v2
	v_mov_b32_e32 v98, v2
	v_mov_b32_e32 v99, v2
	v_mov_b32_e32 v100, v2
	v_mov_b32_e32 v101, v2
	v_mov_b32_e32 v102, v2
	v_mov_b32_e32 v103, v2
	v_mov_b32_e32 v104, v2
	v_mov_b32_e32 v105, v2
	v_mov_b32_e32 v106, v2
	v_mov_b32_e32 v107, v2
	v_mov_b32_e32 v108, v2
	v_mov_b32_e32 v109, v2
	v_mov_b32_e32 v110, v2
	v_mov_b32_e32 v111, v2
	v_mov_b32_e32 v112, v2
	v_mov_b32_e32 v113, v2
	v_mov_b32_e32 v74, v2
	v_mov_b32_e32 v75, v2
	v_mov_b32_e32 v76, v2
	v_mov_b32_e32 v77, v2
	v_mov_b32_e32 v78, v2
	v_mov_b32_e32 v79, v2
	v_mov_b32_e32 v80, v2
	v_mov_b32_e32 v81, v2
	v_mov_b32_e32 v114, v2
	v_mov_b32_e32 v115, v2
	v_mov_b32_e32 v116, v2
	v_mov_b32_e32 v117, v2
	v_mov_b32_e32 v118, v2
	v_mov_b32_e32 v119, v2
	v_mov_b32_e32 v120, v2
	v_mov_b32_e32 v121, v2
	v_mov_b32_e32 v122, v2
	v_mov_b32_e32 v123, v2
	v_mov_b32_e32 v124, v2
	v_mov_b32_e32 v125, v2
	v_mov_b32_e32 v126, v2
	v_mov_b32_e32 v127, v2
	v_mov_b32_e32 v128, v2
	v_mov_b32_e32 v129, v2
	v_mov_b32_e32 v130, v2
	v_mov_b32_e32 v131, v2
	v_mov_b32_e32 v132, v2
	v_mov_b32_e32 v133, v2
	v_mov_b32_e32 v134, v2
	v_mov_b32_e32 v135, v2
	v_mov_b32_e32 v136, v2
	v_mov_b32_e32 v137, v2
	v_readfirstlane_b32 s100, v0
	s_nop 3
	s_bitcmp1_b32 s100, 8
	s_cbranch_scc0 .Lrb_skip9
	s_barrier
.Lrb_skip9:
.LBB0_1615:
	s_add_u32 s31, s64, 0xfffc0080
	s_addc_u32 s36, s65, -1
	s_add_i32 s37, 0, 0x10000
	s_cmp_eq_u32 s27, 12
	s_cselect_b32 vcc_hi, s57, s36
	s_cselect_b32 vcc_lo, s56, s31
	s_cselect_b32 s67, s59, s26
	s_cselect_b32 s66, s58, s25
	s_add_i32 s31, 0, 0x14000
	v_add_u32_e32 v142, s37, v201
	v_add_u32_e32 v158, s31, v201
	ds_read_b128 v[66:69], v142
	ds_read_b128 v[70:73], v142 offset:1024
	ds_read_b128 v[138:141], v142 offset:2048
	ds_read_b128 v[142:145], v142 offset:3072
	ds_read_b128 v[146:149], v158
	ds_read_b128 v[150:153], v158 offset:1024
	ds_read_b128 v[154:157], v158 offset:2048
	ds_read_b128 v[158:161], v158 offset:3072
	v_lshl_add_u64 v[168:169], s[64:65], 0, v[180:181]
	s_add_i32 m0, s63, 0xc000
	ds_read_b128 v[182:185], v222
	ds_read_b128 v[186:189], v222 offset:1024
	ds_read_b128 v[190:193], v222 offset:2048
	ds_read_b128 v[202:205], v222 offset:3072
	ds_read_b128 v[206:209], v222 offset:4096
	ds_read_b128 v[210:213], v222 offset:5120
	ds_read_b128 v[224:227], v222 offset:6144
	ds_read_b128 v[228:231], v222 offset:7168
	global_load_lds_dwordx4 v[168:169], off
	v_lshl_add_u64 v[168:169], s[64:65], 0, v[178:179]
	s_add_i32 m0, s63, 0xe000
	s_nop 0
	global_load_lds_dwordx4 v[168:169], off
	s_waitcnt vmcnt(8)
	s_waitcnt lgkmcnt(0)
	s_barrier
	v_mfma_i32_16x16x64_i8 v[134:137], v[66:69], v[182:185], v[134:137]
	v_mfma_i32_16x16x64_i8 v[130:133], v[138:141], v[182:185], v[130:133]
	v_mfma_i32_16x16x64_i8 v[126:129], v[66:69], v[190:193], v[126:129]
	v_mfma_i32_16x16x64_i8 v[122:125], v[138:141], v[190:193], v[122:125]
	v_mfma_i32_16x16x64_i8 v[118:121], v[66:69], v[206:209], v[118:121]
	v_mfma_i32_16x16x64_i8 v[114:117], v[138:141], v[206:209], v[114:117]
	v_mfma_i32_16x16x64_i8 v[78:81], v[66:69], v[224:227], v[78:81]
	v_mfma_i32_16x16x64_i8 v[74:77], v[138:141], v[224:227], v[74:77]
	v_mfma_i32_16x16x64_i8 v[134:137], v[70:73], v[186:189], v[134:137]
	v_mfma_i32_16x16x64_i8 v[130:133], v[142:145], v[186:189], v[130:133]
	v_mfma_i32_16x16x64_i8 v[126:129], v[70:73], v[202:205], v[126:129]
	v_mfma_i32_16x16x64_i8 v[122:125], v[142:145], v[202:205], v[122:125]
	v_mfma_i32_16x16x64_i8 v[118:121], v[70:73], v[210:213], v[118:121]
	v_mfma_i32_16x16x64_i8 v[114:117], v[142:145], v[210:213], v[114:117]
	v_mfma_i32_16x16x64_i8 v[78:81], v[70:73], v[228:231], v[78:81]
	v_mfma_i32_16x16x64_i8 v[74:77], v[142:145], v[228:231], v[74:77]
	v_mfma_i32_16x16x64_i8 v[110:113], v[146:149], v[182:185], v[110:113]
	v_mfma_i32_16x16x64_i8 v[106:109], v[154:157], v[182:185], v[106:109]
	v_mfma_i32_16x16x64_i8 v[102:105], v[146:149], v[190:193], v[102:105]
	v_mfma_i32_16x16x64_i8 v[98:101], v[154:157], v[190:193], v[98:101]
	v_mfma_i32_16x16x64_i8 v[94:97], v[146:149], v[206:209], v[94:97]
	v_mfma_i32_16x16x64_i8 v[90:93], v[154:157], v[206:209], v[90:93]
	v_mfma_i32_16x16x64_i8 v[86:89], v[146:149], v[224:227], v[86:89]
	v_mfma_i32_16x16x64_i8 v[82:85], v[154:157], v[224:227], v[82:85]
	v_mfma_i32_16x16x64_i8 v[110:113], v[150:153], v[186:189], v[110:113]
	v_mfma_i32_16x16x64_i8 v[106:109], v[158:161], v[186:189], v[106:109]
	v_mfma_i32_16x16x64_i8 v[102:105], v[150:153], v[202:205], v[102:105]
	v_mfma_i32_16x16x64_i8 v[98:101], v[158:161], v[202:205], v[98:101]
	v_mfma_i32_16x16x64_i8 v[94:97], v[150:153], v[210:213], v[94:97]
	v_mfma_i32_16x16x64_i8 v[90:93], v[158:161], v[210:213], v[90:93]
	v_mfma_i32_16x16x64_i8 v[86:89], v[150:153], v[228:231], v[86:89]
	v_mfma_i32_16x16x64_i8 v[82:85], v[158:161], v[228:231], v[82:85]
	s_barrier
	s_add_i32 s36, s37, s61
	v_lshl_add_u64 v[168:169], s[66:67], 0, v[162:163]
	s_mov_b32 m0, s36
	ds_read_b128 v[182:185], v222 offset:16384
	ds_read_b128 v[186:189], v222 offset:17408
	ds_read_b128 v[190:193], v222 offset:18432
	ds_read_b128 v[202:205], v222 offset:19456
	ds_read_b128 v[206:209], v222 offset:20480
	ds_read_b128 v[210:213], v222 offset:21504
	ds_read_b128 v[224:227], v222 offset:22528
	ds_read_b128 v[228:231], v222 offset:23552
	global_load_lds_dwordx4 v[168:169], off
	s_add_i32 m0, s36, 0x2000
	s_add_u32 s36, s66, 0x90000
	v_lshl_add_u64 v[170:171], s[66:67], 0, v[176:177]
	s_addc_u32 s37, s67, 0
	s_add_i32 s31, s31, s61
	global_load_lds_dwordx4 v[170:171], off
	v_lshl_add_u64 v[214:215], s[36:37], 0, v[162:163]
	s_mov_b32 m0, s31
	v_lshl_add_u64 v[232:233], vcc, 0, v[174:175]
	global_load_lds_dwordx4 v[214:215], off
	v_lshl_add_u64 v[214:215], s[36:37], 0, v[176:177]
	s_add_i32 m0, s31, 0x2000
	s_nop 0
	global_load_lds_dwordx4 v[214:215], off
	v_lshl_add_u64 v[214:215], vcc, 0, v[172:173]
	s_mov_b32 m0, s63
	s_nop 0
	global_load_lds_dwordx4 v[214:215], off
	s_mov_b32 m0, s78
	s_nop 0
	global_load_lds_dwordx4 v[232:233], off
	s_waitcnt vmcnt(8)
	s_waitcnt lgkmcnt(0)
	s_barrier
	v_mfma_i32_16x16x64_i8 v[62:65], v[66:69], v[182:185], v[62:65]
	v_mfma_i32_16x16x64_i8 v[58:61], v[138:141], v[182:185], v[58:61]
	v_mfma_i32_16x16x64_i8 v[54:57], v[66:69], v[190:193], v[54:57]
	v_mfma_i32_16x16x64_i8 v[50:53], v[138:141], v[190:193], v[50:53]
	v_mfma_i32_16x16x64_i8 v[46:49], v[66:69], v[206:209], v[46:49]
	v_mfma_i32_16x16x64_i8 v[42:45], v[138:141], v[206:209], v[42:45]
	v_mfma_i32_16x16x64_i8 v[38:41], v[66:69], v[224:227], v[38:41]
	v_mfma_i32_16x16x64_i8 v[34:37], v[138:141], v[224:227], v[34:37]
	v_mfma_i32_16x16x64_i8 v[62:65], v[70:73], v[186:189], v[62:65]
	v_mfma_i32_16x16x64_i8 v[58:61], v[142:145], v[186:189], v[58:61]
	v_mfma_i32_16x16x64_i8 v[54:57], v[70:73], v[202:205], v[54:57]
	v_mfma_i32_16x16x64_i8 v[50:53], v[142:145], v[202:205], v[50:53]
	v_mfma_i32_16x16x64_i8 v[46:49], v[70:73], v[210:213], v[46:49]
	v_mfma_i32_16x16x64_i8 v[42:45], v[142:145], v[210:213], v[42:45]
	v_mfma_i32_16x16x64_i8 v[38:41], v[70:73], v[228:231], v[38:41]
	v_mfma_i32_16x16x64_i8 v[34:37], v[142:145], v[228:231], v[34:37]
	v_mfma_i32_16x16x64_i8 v[30:33], v[146:149], v[182:185], v[30:33]
	v_mfma_i32_16x16x64_i8 v[26:29], v[154:157], v[182:185], v[26:29]
	v_mfma_i32_16x16x64_i8 v[22:25], v[146:149], v[190:193], v[22:25]
	v_mfma_i32_16x16x64_i8 v[18:21], v[154:157], v[190:193], v[18:21]
	v_mfma_i32_16x16x64_i8 v[14:17], v[146:149], v[206:209], v[14:17]
	v_mfma_i32_16x16x64_i8 v[10:13], v[154:157], v[206:209], v[10:13]
	v_mfma_i32_16x16x64_i8 v[6:9], v[146:149], v[224:227], v[6:9]
	v_mfma_i32_16x16x64_i8 v[2:5], v[154:157], v[224:227], v[2:5]
	v_mfma_i32_16x16x64_i8 v[30:33], v[150:153], v[186:189], v[30:33]
	v_mfma_i32_16x16x64_i8 v[26:29], v[158:161], v[186:189], v[26:29]
	v_mfma_i32_16x16x64_i8 v[22:25], v[150:153], v[202:205], v[22:25]
	v_mfma_i32_16x16x64_i8 v[18:21], v[158:161], v[202:205], v[18:21]
	v_mfma_i32_16x16x64_i8 v[14:17], v[150:153], v[210:213], v[14:17]
	v_mfma_i32_16x16x64_i8 v[10:13], v[158:161], v[210:213], v[10:13]
	v_mfma_i32_16x16x64_i8 v[6:9], v[150:153], v[228:231], v[6:9]
	v_mfma_i32_16x16x64_i8 v[2:5], v[158:161], v[228:231], v[2:5]
	s_barrier
	s_add_i32 s31, 0, 0x18000
	s_add_i32 s38, 0, 0x1c000
	v_add_u32_e32 v142, s31, v201
	v_add_u32_e32 v158, s38, v201
	ds_read_b128 v[66:69], v142
	ds_read_b128 v[70:73], v142 offset:1024
	ds_read_b128 v[138:141], v142 offset:2048
	ds_read_b128 v[142:145], v142 offset:3072
	ds_read_b128 v[146:149], v158
	ds_read_b128 v[150:153], v158 offset:1024
	ds_read_b128 v[154:157], v158 offset:2048
	ds_read_b128 v[158:161], v158 offset:3072
	s_add_u32 s36, vcc_lo, 0x40000
	s_addc_u32 s37, vcc_hi, 0
	s_mov_b32 m0, s79
	v_lshl_add_u64 v[234:235], s[36:37], 0, v[172:173]
	ds_read_b128 v[182:185], v222 offset:32768
	ds_read_b128 v[186:189], v222 offset:33792
	ds_read_b128 v[190:193], v222 offset:34816
	ds_read_b128 v[202:205], v222 offset:35840
	ds_read_b128 v[206:209], v222 offset:36864
	ds_read_b128 v[210:213], v222 offset:37888
	ds_read_b128 v[224:227], v222 offset:38912
	ds_read_b128 v[228:231], v222 offset:39936
	global_load_lds_dwordx4 v[234:235], off
	v_lshl_add_u64 v[234:235], s[36:37], 0, v[174:175]
	s_mov_b32 m0, s80
	s_nop 0
	global_load_lds_dwordx4 v[234:235], off
	s_waitcnt vmcnt(8)
	s_waitcnt lgkmcnt(0)
	s_barrier
	v_mfma_i32_16x16x64_i8 v[134:137], v[66:69], v[182:185], v[134:137]
	v_mfma_i32_16x16x64_i8 v[130:133], v[138:141], v[182:185], v[130:133]
	v_mfma_i32_16x16x64_i8 v[126:129], v[66:69], v[190:193], v[126:129]
	v_mfma_i32_16x16x64_i8 v[122:125], v[138:141], v[190:193], v[122:125]
	v_mfma_i32_16x16x64_i8 v[118:121], v[66:69], v[206:209], v[118:121]
	v_mfma_i32_16x16x64_i8 v[114:117], v[138:141], v[206:209], v[114:117]
	v_mfma_i32_16x16x64_i8 v[78:81], v[66:69], v[224:227], v[78:81]
	v_mfma_i32_16x16x64_i8 v[74:77], v[138:141], v[224:227], v[74:77]
	v_mfma_i32_16x16x64_i8 v[134:137], v[70:73], v[186:189], v[134:137]
	v_mfma_i32_16x16x64_i8 v[130:133], v[142:145], v[186:189], v[130:133]
	v_mfma_i32_16x16x64_i8 v[126:129], v[70:73], v[202:205], v[126:129]
	v_mfma_i32_16x16x64_i8 v[122:125], v[142:145], v[202:205], v[122:125]
	v_mfma_i32_16x16x64_i8 v[118:121], v[70:73], v[210:213], v[118:121]
	v_mfma_i32_16x16x64_i8 v[114:117], v[142:145], v[210:213], v[114:117]
	v_mfma_i32_16x16x64_i8 v[78:81], v[70:73], v[228:231], v[78:81]
	v_mfma_i32_16x16x64_i8 v[74:77], v[142:145], v[228:231], v[74:77]
	v_mfma_i32_16x16x64_i8 v[110:113], v[146:149], v[182:185], v[110:113]
	v_mfma_i32_16x16x64_i8 v[106:109], v[154:157], v[182:185], v[106:109]
	v_mfma_i32_16x16x64_i8 v[102:105], v[146:149], v[190:193], v[102:105]
	v_mfma_i32_16x16x64_i8 v[98:101], v[154:157], v[190:193], v[98:101]
	v_mfma_i32_16x16x64_i8 v[94:97], v[146:149], v[206:209], v[94:97]
	v_mfma_i32_16x16x64_i8 v[90:93], v[154:157], v[206:209], v[90:93]
	v_mfma_i32_16x16x64_i8 v[86:89], v[146:149], v[224:227], v[86:89]
	v_mfma_i32_16x16x64_i8 v[82:85], v[154:157], v[224:227], v[82:85]
	v_mfma_i32_16x16x64_i8 v[110:113], v[150:153], v[186:189], v[110:113]
	v_mfma_i32_16x16x64_i8 v[106:109], v[158:161], v[186:189], v[106:109]
	v_mfma_i32_16x16x64_i8 v[102:105], v[150:153], v[202:205], v[102:105]
	v_mfma_i32_16x16x64_i8 v[98:101], v[158:161], v[202:205], v[98:101]
	v_mfma_i32_16x16x64_i8 v[94:97], v[150:153], v[210:213], v[94:97]
	v_mfma_i32_16x16x64_i8 v[90:93], v[158:161], v[210:213], v[90:93]
	v_mfma_i32_16x16x64_i8 v[86:89], v[150:153], v[228:231], v[86:89]
	v_mfma_i32_16x16x64_i8 v[82:85], v[158:161], v[228:231], v[82:85]
	s_barrier
	s_add_i32 s31, s31, s61
	v_lshl_add_u64 v[168:169], v[168:169], 0, s[44:45]
	s_mov_b32 m0, s31
	ds_read_b128 v[182:185], v222 offset:49152
	ds_read_b128 v[186:189], v222 offset:50176
	ds_read_b128 v[190:193], v222 offset:51200
	ds_read_b128 v[202:205], v222 offset:52224
	ds_read_b128 v[206:209], v222 offset:53248
	ds_read_b128 v[210:213], v222 offset:54272
	ds_read_b128 v[224:227], v222 offset:55296
	ds_read_b128 v[228:231], v222 offset:56320
	global_load_lds_dwordx4 v[168:169], off
	s_add_i32 m0, s31, 0x2000
	s_add_u32 s36, s66, 0x90080
	v_lshl_add_u64 v[168:169], v[170:171], 0, s[44:45]
	s_addc_u32 s37, s67, 0
	s_add_i32 s31, s38, s61
	global_load_lds_dwordx4 v[168:169], off
	v_lshl_add_u64 v[168:169], s[36:37], 0, v[162:163]
	s_mov_b32 m0, s31
	s_nop 0
	global_load_lds_dwordx4 v[168:169], off
	v_lshl_add_u64 v[168:169], s[36:37], 0, v[176:177]
	s_add_i32 m0, s31, 0x2000
	s_nop 0
	global_load_lds_dwordx4 v[168:169], off
	v_lshl_add_u64 v[168:169], v[214:215], 0, s[44:45]
	s_mov_b32 m0, s82
	s_nop 0
	global_load_lds_dwordx4 v[168:169], off
	v_lshl_add_u64 v[168:169], v[232:233], 0, s[44:45]
	s_mov_b32 m0, s83
	s_nop 0
	global_load_lds_dwordx4 v[168:169], off
	s_waitcnt vmcnt(8)
	s_waitcnt lgkmcnt(0)
	s_barrier
	v_mfma_i32_16x16x64_i8 v[62:65], v[66:69], v[182:185], v[62:65]
	v_mfma_i32_16x16x64_i8 v[58:61], v[138:141], v[182:185], v[58:61]
	v_mfma_i32_16x16x64_i8 v[54:57], v[66:69], v[190:193], v[54:57]
	v_mfma_i32_16x16x64_i8 v[50:53], v[138:141], v[190:193], v[50:53]
	v_mfma_i32_16x16x64_i8 v[46:49], v[66:69], v[206:209], v[46:49]
	v_mfma_i32_16x16x64_i8 v[42:45], v[138:141], v[206:209], v[42:45]
	v_mfma_i32_16x16x64_i8 v[38:41], v[66:69], v[224:227], v[38:41]
	v_mfma_i32_16x16x64_i8 v[34:37], v[138:141], v[224:227], v[34:37]
	v_mfma_i32_16x16x64_i8 v[62:65], v[70:73], v[186:189], v[62:65]
	v_mfma_i32_16x16x64_i8 v[58:61], v[142:145], v[186:189], v[58:61]
	v_mfma_i32_16x16x64_i8 v[54:57], v[70:73], v[202:205], v[54:57]
	v_mfma_i32_16x16x64_i8 v[50:53], v[142:145], v[202:205], v[50:53]
	v_mfma_i32_16x16x64_i8 v[46:49], v[70:73], v[210:213], v[46:49]
	v_mfma_i32_16x16x64_i8 v[42:45], v[142:145], v[210:213], v[42:45]
	v_mfma_i32_16x16x64_i8 v[38:41], v[70:73], v[228:231], v[38:41]
	v_mfma_i32_16x16x64_i8 v[34:37], v[142:145], v[228:231], v[34:37]
	v_mfma_i32_16x16x64_i8 v[30:33], v[146:149], v[182:185], v[30:33]
	v_mfma_i32_16x16x64_i8 v[26:29], v[154:157], v[182:185], v[26:29]
	v_mfma_i32_16x16x64_i8 v[22:25], v[146:149], v[190:193], v[22:25]
	v_mfma_i32_16x16x64_i8 v[18:21], v[154:157], v[190:193], v[18:21]
	v_mfma_i32_16x16x64_i8 v[14:17], v[146:149], v[206:209], v[14:17]
	v_mfma_i32_16x16x64_i8 v[10:13], v[154:157], v[206:209], v[10:13]
	v_mfma_i32_16x16x64_i8 v[6:9], v[146:149], v[224:227], v[6:9]
	v_mfma_i32_16x16x64_i8 v[2:5], v[154:157], v[224:227], v[2:5]
	v_mfma_i32_16x16x64_i8 v[30:33], v[150:153], v[186:189], v[30:33]
	v_mfma_i32_16x16x64_i8 v[26:29], v[158:161], v[186:189], v[26:29]
	v_mfma_i32_16x16x64_i8 v[22:25], v[150:153], v[202:205], v[22:25]
	v_mfma_i32_16x16x64_i8 v[18:21], v[158:161], v[202:205], v[18:21]
	v_mfma_i32_16x16x64_i8 v[14:17], v[150:153], v[210:213], v[14:17]
	v_mfma_i32_16x16x64_i8 v[10:13], v[158:161], v[210:213], v[10:13]
	v_mfma_i32_16x16x64_i8 v[6:9], v[150:153], v[228:231], v[6:9]
	v_mfma_i32_16x16x64_i8 v[2:5], v[158:161], v[228:231], v[2:5]
	s_barrier
	s_add_i32 s27, s27, 2
	s_add_u32 s25, s25, 0x100
	s_addc_u32 s26, s26, 0
	s_add_u32 s64, s64, 0x100
	s_addc_u32 s65, s65, 0
	s_cmp_gt_u32 s27, 13
	s_cbranch_scc0 .LBB0_1615
	s_and_b64 vcc, exec, s[22:23]
	s_cbranch_vccz .LBB0_1618
	s_barrier

.LBB0_1637:
	s_andn2_b64 vcc, exec, s[12:13]
	s_cbranch_vccnz .LBB0_1599
	s_branch .LBB0_1599
